# v11 + code placement: s_nop pads before the closing wait of load segments so every 16-MFMA block in the 13 GEMM main loops starts 8-byte aligned
# baseline (speedup 1.0000x reference)
.LBB0_472:
	ds_read_b128 v[152:155], v148
	ds_read_b128 v[156:159], v148 offset:1024
	ds_read_b128 v[166:169], v148 offset:2048
	ds_read_b128 v[170:173], v148 offset:3072
	ds_read_b128 v[174:177], v149
	ds_read_b128 v[178:181], v149 offset:1024
	ds_read_b128 v[182:185], v149 offset:2048
	ds_read_b128 v[186:189], v149 offset:3072
	s_add_u32 s44, s54, 0xfff00080
	s_addc_u32 s56, s55, -1
	s_cmp_eq_u32 s72, 60
	s_cselect_b32 s59, s17, s56
	s_cselect_b32 s58, s68, s44
	s_cselect_b32 s57, s15, s71
	s_cselect_b32 s56, s69, s70
	v_lshl_add_u64 v[160:161], s[54:55], 0, v[138:139]
	s_add_i32 m0, s41, 0xc000
	ds_read_b128 v[190:193], v150
	ds_read_b128 v[194:197], v150 offset:1024
	ds_read_b128 v[198:201], v150 offset:2048
	ds_read_b128 v[202:205], v150 offset:3072
	ds_read_b128 v[206:209], v150 offset:4096
	ds_read_b128 v[210:213], v150 offset:5120
	ds_read_b128 v[214:217], v150 offset:6144
	ds_read_b128 v[218:221], v150 offset:7168
	global_load_lds_dwordx4 v[160:161], off
	v_lshl_add_u64 v[160:161], s[54:55], 0, v[140:141]
	s_add_i32 m0, s41, 0xe000
	s_nop 0
	global_load_lds_dwordx4 v[160:161], off
	s_nop 0
	s_waitcnt vmcnt(8)
	s_waitcnt lgkmcnt(0)
	s_barrier
	s_setprio 1
	s_waitcnt lgkmcnt(0)
	v_mfma_f32_16x16x32_bf16 v[126:129], v[152:155], v[190:193], v[126:129]
	v_mfma_f32_16x16x32_bf16 v[126:129], v[156:159], v[194:197], v[126:129]
	v_mfma_f32_16x16x32_bf16 v[122:125], v[170:173], v[194:197], v[122:125]
	v_mfma_f32_16x16x32_bf16 v[122:125], v[166:169], v[190:193], v[122:125]
	v_mfma_f32_16x16x32_bf16 v[110:113], v[166:169], v[198:201], v[110:113]
	v_mfma_f32_16x16x32_bf16 v[110:113], v[170:173], v[202:205], v[110:113]
	v_mfma_f32_16x16x32_bf16 v[118:121], v[156:159], v[202:205], v[118:121]
	v_mfma_f32_16x16x32_bf16 v[118:121], v[152:155], v[198:201], v[118:121]
	v_mfma_f32_16x16x32_bf16 v[102:105], v[152:155], v[206:209], v[102:105]
	v_mfma_f32_16x16x32_bf16 v[102:105], v[156:159], v[210:213], v[102:105]
	v_mfma_f32_16x16x32_bf16 v[94:97], v[170:173], v[210:213], v[94:97]
	v_mfma_f32_16x16x32_bf16 v[94:97], v[166:169], v[206:209], v[94:97]
	v_mfma_f32_16x16x32_bf16 v[78:81], v[166:169], v[214:217], v[78:81]
	v_mfma_f32_16x16x32_bf16 v[78:81], v[170:173], v[218:221], v[78:81]
	v_mfma_f32_16x16x32_bf16 v[86:89], v[156:159], v[218:221], v[86:89]
	v_mfma_f32_16x16x32_bf16 v[86:89], v[152:155], v[214:217], v[86:89]
	s_setprio 0
	s_setprio 1
	v_mfma_f32_16x16x32_bf16 v[114:117], v[174:177], v[190:193], v[114:117]
	v_mfma_f32_16x16x32_bf16 v[114:117], v[178:181], v[194:197], v[114:117]
	v_mfma_f32_16x16x32_bf16 v[106:109], v[186:189], v[194:197], v[106:109]
	v_mfma_f32_16x16x32_bf16 v[106:109], v[182:185], v[190:193], v[106:109]
	v_mfma_f32_16x16x32_bf16 v[90:93], v[182:185], v[198:201], v[90:93]
	v_mfma_f32_16x16x32_bf16 v[90:93], v[186:189], v[202:205], v[90:93]
	v_mfma_f32_16x16x32_bf16 v[98:101], v[178:181], v[202:205], v[98:101]
	v_mfma_f32_16x16x32_bf16 v[98:101], v[174:177], v[198:201], v[98:101]
	v_mfma_f32_16x16x32_bf16 v[82:85], v[174:177], v[206:209], v[82:85]
	v_mfma_f32_16x16x32_bf16 v[82:85], v[178:181], v[210:213], v[82:85]
	v_mfma_f32_16x16x32_bf16 v[74:77], v[186:189], v[210:213], v[74:77]
	v_mfma_f32_16x16x32_bf16 v[74:77], v[182:185], v[206:209], v[74:77]
	v_mfma_f32_16x16x32_bf16 v[66:69], v[182:185], v[214:217], v[66:69]
	v_mfma_f32_16x16x32_bf16 v[66:69], v[186:189], v[218:221], v[66:69]
	v_mfma_f32_16x16x32_bf16 v[70:73], v[178:181], v[218:221], v[70:73]
	v_mfma_f32_16x16x32_bf16 v[70:73], v[174:177], v[214:217], v[70:73]
	s_setprio 0
	s_barrier
	s_add_i32 s44, s64, s27
	v_lshl_add_u64 v[160:161], s[56:57], 0, v[134:135]
	s_mov_b32 m0, s44
	ds_read_b128 v[190:193], v150 offset:16384
	ds_read_b128 v[194:197], v150 offset:17408
	ds_read_b128 v[198:201], v150 offset:18432
	ds_read_b128 v[202:205], v150 offset:19456
	ds_read_b128 v[206:209], v150 offset:20480
	ds_read_b128 v[210:213], v150 offset:21504
	ds_read_b128 v[214:217], v150 offset:22528
	ds_read_b128 v[218:221], v150 offset:23552
	global_load_lds_dwordx4 v[160:161], off
	s_add_i32 m0, s44, 0x2000
	s_add_u32 s74, s56, 0x100000
	v_lshl_add_u64 v[222:223], s[56:57], 0, v[130:131]
	s_addc_u32 s75, s57, 0
	s_add_i32 s44, s65, s27
	global_load_lds_dwordx4 v[222:223], off
	v_lshl_add_u64 v[224:225], s[74:75], 0, v[134:135]
	s_mov_b32 m0, s44
	v_lshl_add_u64 v[226:227], s[58:59], 0, v[132:133]
	global_load_lds_dwordx4 v[224:225], off
	v_lshl_add_u64 v[224:225], s[74:75], 0, v[130:131]
	s_add_i32 m0, s44, 0x2000
	s_nop 0
	global_load_lds_dwordx4 v[224:225], off
	v_lshl_add_u64 v[224:225], s[58:59], 0, v[136:137]
	s_mov_b32 m0, s41
	s_nop 0
	global_load_lds_dwordx4 v[224:225], off
	s_mov_b32 m0, s43
	s_nop 0
	global_load_lds_dwordx4 v[226:227], off
	s_nop 0
	s_waitcnt vmcnt(8)
	s_waitcnt lgkmcnt(0)
	s_barrier
	s_setprio 1
	s_waitcnt lgkmcnt(0)
	v_mfma_f32_16x16x32_bf16 v[62:65], v[152:155], v[190:193], v[62:65]
	v_mfma_f32_16x16x32_bf16 v[62:65], v[156:159], v[194:197], v[62:65]
	v_mfma_f32_16x16x32_bf16 v[58:61], v[170:173], v[194:197], v[58:61]
	v_mfma_f32_16x16x32_bf16 v[58:61], v[166:169], v[190:193], v[58:61]
	v_mfma_f32_16x16x32_bf16 v[46:49], v[166:169], v[198:201], v[46:49]
	v_mfma_f32_16x16x32_bf16 v[46:49], v[170:173], v[202:205], v[46:49]
	v_mfma_f32_16x16x32_bf16 v[54:57], v[156:159], v[202:205], v[54:57]
	v_mfma_f32_16x16x32_bf16 v[54:57], v[152:155], v[198:201], v[54:57]
	v_mfma_f32_16x16x32_bf16 v[38:41], v[152:155], v[206:209], v[38:41]
	v_mfma_f32_16x16x32_bf16 v[38:41], v[156:159], v[210:213], v[38:41]
	v_mfma_f32_16x16x32_bf16 v[30:33], v[170:173], v[210:213], v[30:33]
	v_mfma_f32_16x16x32_bf16 v[30:33], v[166:169], v[206:209], v[30:33]
	v_mfma_f32_16x16x32_bf16 v[14:17], v[166:169], v[214:217], v[14:17]
	v_mfma_f32_16x16x32_bf16 v[14:17], v[170:173], v[218:221], v[14:17]
	v_mfma_f32_16x16x32_bf16 v[22:25], v[156:159], v[218:221], v[22:25]
	v_mfma_f32_16x16x32_bf16 v[22:25], v[152:155], v[214:217], v[22:25]
	s_setprio 0
	s_setprio 1
	v_mfma_f32_16x16x32_bf16 v[50:53], v[174:177], v[190:193], v[50:53]
	v_mfma_f32_16x16x32_bf16 v[50:53], v[178:181], v[194:197], v[50:53]
	v_mfma_f32_16x16x32_bf16 v[42:45], v[186:189], v[194:197], v[42:45]
	v_mfma_f32_16x16x32_bf16 v[42:45], v[182:185], v[190:193], v[42:45]
	v_mfma_f32_16x16x32_bf16 v[26:29], v[182:185], v[198:201], v[26:29]
	v_mfma_f32_16x16x32_bf16 v[26:29], v[186:189], v[202:205], v[26:29]
	v_mfma_f32_16x16x32_bf16 v[34:37], v[178:181], v[202:205], v[34:37]
	v_mfma_f32_16x16x32_bf16 v[34:37], v[174:177], v[198:201], v[34:37]
	v_mfma_f32_16x16x32_bf16 v[18:21], v[174:177], v[206:209], v[18:21]
	v_mfma_f32_16x16x32_bf16 v[18:21], v[178:181], v[210:213], v[18:21]
	v_mfma_f32_16x16x32_bf16 v[10:13], v[186:189], v[210:213], v[10:13]
	v_mfma_f32_16x16x32_bf16 v[10:13], v[182:185], v[206:209], v[10:13]
	v_mfma_f32_16x16x32_bf16 v[2:5], v[182:185], v[214:217], v[2:5]
	v_mfma_f32_16x16x32_bf16 v[2:5], v[186:189], v[218:221], v[2:5]
	v_mfma_f32_16x16x32_bf16 v[6:9], v[178:181], v[218:221], v[6:9]
	v_mfma_f32_16x16x32_bf16 v[6:9], v[174:177], v[214:217], v[6:9]
	s_setprio 0
	s_barrier
	s_add_i32 s44, 0, 0x18000
	v_add_u32_e32 v151, s44, v146
	s_add_i32 s73, 0, 0x1c000
	ds_read_b128 v[152:155], v151
	ds_read_b128 v[156:159], v151 offset:1024
	ds_read_b128 v[166:169], v151 offset:2048
	ds_read_b128 v[170:173], v151 offset:3072
	v_add_u32_e32 v151, s73, v146
	ds_read_b128 v[174:177], v151
	ds_read_b128 v[178:181], v151 offset:1024
	ds_read_b128 v[182:185], v151 offset:2048
	ds_read_b128 v[186:189], v151 offset:3072
	s_add_u32 s58, s58, 0x100000
	s_addc_u32 s59, s59, 0
	s_mov_b32 m0, s45
	v_lshl_add_u64 v[228:229], s[58:59], 0, v[136:137]
	ds_read_b128 v[190:193], v150 offset:32768
	ds_read_b128 v[194:197], v150 offset:33792
	ds_read_b128 v[198:201], v150 offset:34816
	ds_read_b128 v[202:205], v150 offset:35840
	ds_read_b128 v[206:209], v150 offset:36864
	ds_read_b128 v[210:213], v150 offset:37888
	ds_read_b128 v[214:217], v150 offset:38912
	ds_read_b128 v[218:221], v150 offset:39936
	global_load_lds_dwordx4 v[228:229], off
	v_lshl_add_u64 v[228:229], s[58:59], 0, v[132:133]
	s_mov_b32 m0, s53
	s_nop 0
	global_load_lds_dwordx4 v[228:229], off
	s_nop 0
	s_waitcnt vmcnt(8)
	s_waitcnt lgkmcnt(0)
	s_barrier
	s_setprio 1
	s_waitcnt lgkmcnt(0)
	v_mfma_f32_16x16x32_bf16 v[126:129], v[152:155], v[190:193], v[126:129]
	v_mfma_f32_16x16x32_bf16 v[126:129], v[156:159], v[194:197], v[126:129]
	v_mfma_f32_16x16x32_bf16 v[122:125], v[170:173], v[194:197], v[122:125]
	v_mfma_f32_16x16x32_bf16 v[122:125], v[166:169], v[190:193], v[122:125]
	v_mfma_f32_16x16x32_bf16 v[110:113], v[166:169], v[198:201], v[110:113]
	v_mfma_f32_16x16x32_bf16 v[110:113], v[170:173], v[202:205], v[110:113]
	v_mfma_f32_16x16x32_bf16 v[118:121], v[156:159], v[202:205], v[118:121]
	v_mfma_f32_16x16x32_bf16 v[118:121], v[152:155], v[198:201], v[118:121]
	v_mfma_f32_16x16x32_bf16 v[102:105], v[152:155], v[206:209], v[102:105]
	v_mfma_f32_16x16x32_bf16 v[102:105], v[156:159], v[210:213], v[102:105]
	v_mfma_f32_16x16x32_bf16 v[94:97], v[170:173], v[210:213], v[94:97]
	v_mfma_f32_16x16x32_bf16 v[94:97], v[166:169], v[206:209], v[94:97]
	v_mfma_f32_16x16x32_bf16 v[78:81], v[166:169], v[214:217], v[78:81]
	v_mfma_f32_16x16x32_bf16 v[78:81], v[170:173], v[218:221], v[78:81]
	v_mfma_f32_16x16x32_bf16 v[86:89], v[156:159], v[218:221], v[86:89]
	v_mfma_f32_16x16x32_bf16 v[86:89], v[152:155], v[214:217], v[86:89]
	s_setprio 0
	s_setprio 1
	v_mfma_f32_16x16x32_bf16 v[114:117], v[174:177], v[190:193], v[114:117]
	v_mfma_f32_16x16x32_bf16 v[114:117], v[178:181], v[194:197], v[114:117]
	v_mfma_f32_16x16x32_bf16 v[106:109], v[186:189], v[194:197], v[106:109]
	v_mfma_f32_16x16x32_bf16 v[106:109], v[182:185], v[190:193], v[106:109]
	v_mfma_f32_16x16x32_bf16 v[90:93], v[182:185], v[198:201], v[90:93]
	v_mfma_f32_16x16x32_bf16 v[90:93], v[186:189], v[202:205], v[90:93]
	v_mfma_f32_16x16x32_bf16 v[98:101], v[178:181], v[202:205], v[98:101]
	v_mfma_f32_16x16x32_bf16 v[98:101], v[174:177], v[198:201], v[98:101]
	v_mfma_f32_16x16x32_bf16 v[82:85], v[174:177], v[206:209], v[82:85]
	v_mfma_f32_16x16x32_bf16 v[82:85], v[178:181], v[210:213], v[82:85]
	v_mfma_f32_16x16x32_bf16 v[74:77], v[186:189], v[210:213], v[74:77]
	v_mfma_f32_16x16x32_bf16 v[74:77], v[182:185], v[206:209], v[74:77]
	v_mfma_f32_16x16x32_bf16 v[66:69], v[182:185], v[214:217], v[66:69]
	v_mfma_f32_16x16x32_bf16 v[66:69], v[186:189], v[218:221], v[66:69]
	v_mfma_f32_16x16x32_bf16 v[70:73], v[178:181], v[218:221], v[70:73]
	v_mfma_f32_16x16x32_bf16 v[70:73], v[174:177], v[214:217], v[70:73]
	s_setprio 0
	s_barrier
	s_add_i32 s44, s44, s27
	v_lshl_add_u64 v[160:161], v[160:161], 0, s[10:11]
	s_mov_b32 m0, s44
	ds_read_b128 v[190:193], v150 offset:49152
	ds_read_b128 v[194:197], v150 offset:50176
	ds_read_b128 v[198:201], v150 offset:51200
	ds_read_b128 v[202:205], v150 offset:52224
	ds_read_b128 v[206:209], v150 offset:53248
	ds_read_b128 v[210:213], v150 offset:54272
	ds_read_b128 v[214:217], v150 offset:55296
	ds_read_b128 v[218:221], v150 offset:56320
	global_load_lds_dwordx4 v[160:161], off
	s_add_i32 m0, s44, 0x2000
	s_add_u32 s56, s56, 0x100080
	v_lshl_add_u64 v[160:161], v[222:223], 0, s[10:11]
	s_addc_u32 s57, s57, 0
	s_add_i32 s44, s73, s27
	global_load_lds_dwordx4 v[160:161], off
	v_lshl_add_u64 v[160:161], s[56:57], 0, v[134:135]
	s_mov_b32 m0, s44
	s_nop 0
	global_load_lds_dwordx4 v[160:161], off
	v_lshl_add_u64 v[160:161], s[56:57], 0, v[130:131]
	s_add_i32 m0, s44, 0x2000
	s_nop 0
	global_load_lds_dwordx4 v[160:161], off
	v_lshl_add_u64 v[160:161], v[224:225], 0, s[10:11]
	s_mov_b32 m0, s61
	s_nop 0
	global_load_lds_dwordx4 v[160:161], off
	v_lshl_add_u64 v[160:161], v[226:227], 0, s[10:11]
	s_mov_b32 m0, s62
	s_nop 0
	global_load_lds_dwordx4 v[160:161], off
	s_waitcnt vmcnt(8)
	s_waitcnt lgkmcnt(0)
	s_barrier
	s_setprio 1
	s_waitcnt lgkmcnt(0)
	v_mfma_f32_16x16x32_bf16 v[62:65], v[152:155], v[190:193], v[62:65]
	v_mfma_f32_16x16x32_bf16 v[62:65], v[156:159], v[194:197], v[62:65]
	v_mfma_f32_16x16x32_bf16 v[58:61], v[170:173], v[194:197], v[58:61]
	v_mfma_f32_16x16x32_bf16 v[58:61], v[166:169], v[190:193], v[58:61]
	v_mfma_f32_16x16x32_bf16 v[46:49], v[166:169], v[198:201], v[46:49]
	v_mfma_f32_16x16x32_bf16 v[46:49], v[170:173], v[202:205], v[46:49]
	v_mfma_f32_16x16x32_bf16 v[54:57], v[156:159], v[202:205], v[54:57]
	v_mfma_f32_16x16x32_bf16 v[54:57], v[152:155], v[198:201], v[54:57]
	v_mfma_f32_16x16x32_bf16 v[38:41], v[152:155], v[206:209], v[38:41]
	v_mfma_f32_16x16x32_bf16 v[38:41], v[156:159], v[210:213], v[38:41]
	v_mfma_f32_16x16x32_bf16 v[30:33], v[170:173], v[210:213], v[30:33]
	v_mfma_f32_16x16x32_bf16 v[30:33], v[166:169], v[206:209], v[30:33]
	v_mfma_f32_16x16x32_bf16 v[14:17], v[166:169], v[214:217], v[14:17]
	v_mfma_f32_16x16x32_bf16 v[14:17], v[170:173], v[218:221], v[14:17]
	v_mfma_f32_16x16x32_bf16 v[22:25], v[156:159], v[218:221], v[22:25]
	v_mfma_f32_16x16x32_bf16 v[22:25], v[152:155], v[214:217], v[22:25]
	s_setprio 0
	s_setprio 1
	v_mfma_f32_16x16x32_bf16 v[50:53], v[174:177], v[190:193], v[50:53]
	v_mfma_f32_16x16x32_bf16 v[50:53], v[178:181], v[194:197], v[50:53]
	v_mfma_f32_16x16x32_bf16 v[42:45], v[186:189], v[194:197], v[42:45]
	v_mfma_f32_16x16x32_bf16 v[42:45], v[182:185], v[190:193], v[42:45]
	v_mfma_f32_16x16x32_bf16 v[26:29], v[182:185], v[198:201], v[26:29]
	v_mfma_f32_16x16x32_bf16 v[26:29], v[186:189], v[202:205], v[26:29]
	v_mfma_f32_16x16x32_bf16 v[34:37], v[178:181], v[202:205], v[34:37]
	v_mfma_f32_16x16x32_bf16 v[34:37], v[174:177], v[198:201], v[34:37]
	v_mfma_f32_16x16x32_bf16 v[18:21], v[174:177], v[206:209], v[18:21]
	v_mfma_f32_16x16x32_bf16 v[18:21], v[178:181], v[210:213], v[18:21]
	v_mfma_f32_16x16x32_bf16 v[10:13], v[186:189], v[210:213], v[10:13]
	v_mfma_f32_16x16x32_bf16 v[10:13], v[182:185], v[206:209], v[10:13]
	v_mfma_f32_16x16x32_bf16 v[2:5], v[182:185], v[214:217], v[2:5]
	v_mfma_f32_16x16x32_bf16 v[2:5], v[186:189], v[218:221], v[2:5]
	v_mfma_f32_16x16x32_bf16 v[6:9], v[178:181], v[218:221], v[6:9]
	v_mfma_f32_16x16x32_bf16 v[6:9], v[174:177], v[214:217], v[6:9]
	s_setprio 0
	s_barrier
	s_add_i32 s72, s72, 2
	s_add_u32 s54, s54, 0x100
	s_addc_u32 s55, s55, 0
	s_add_u32 s70, s70, 0x100
	s_addc_u32 s71, s71, 0
	s_cmp_gt_u32 s72, 61
	s_cbranch_scc0 .LBB0_472
	s_and_b64 vcc, exec, s[12:13]
	s_cbranch_vccz .LBB0_475
	s_barrier

.LBB0_1226:
	v_add_u32_e32 v3, s71, v165
	ds_read_b128 v[150:153], v3
	ds_read_b128 v[154:157], v3 offset:1024
	ds_read_b128 v[158:161], v3 offset:2048
	ds_read_b128 v[170:173], v3 offset:3072
	v_add_u32_e32 v3, s72, v165
	ds_read_b128 v[174:177], v3
	ds_read_b128 v[178:181], v3 offset:1024
	ds_read_b128 v[182:185], v3 offset:2048
	ds_read_b128 v[186:189], v3 offset:3072
	s_add_u32 s36, s52, 0xfff80080
	s_addc_u32 s37, s53, -1
	s_cmp_eq_u32 s78, 28
	s_cselect_b32 s59, s21, s37
	s_cselect_b32 s58, s44, s36
	s_cselect_b32 s57, s19, s77
	s_cselect_b32 s56, s55, s76
	v_lshl_add_u64 v[4:5], s[52:53], 0, v[142:143]
	s_add_i32 m0, s63, 0xc000
	ds_read_b128 v[190:193], v169
	ds_read_b128 v[194:197], v169 offset:1024
	ds_read_b128 v[202:205], v169 offset:2048
	ds_read_b128 v[206:209], v169 offset:3072
	ds_read_b128 v[210:213], v169 offset:4096
	ds_read_b128 v[214:217], v169 offset:5120
	ds_read_b128 v[218:221], v169 offset:6144
	ds_read_b128 v[222:225], v169 offset:7168
	global_load_lds_dwordx4 v[4:5], off
	v_lshl_add_u64 v[4:5], s[52:53], 0, v[144:145]
	s_add_i32 m0, s63, 0xe000
	s_nop 0
	global_load_lds_dwordx4 v[4:5], off
	s_nop 0
	s_waitcnt vmcnt(8)
	s_waitcnt lgkmcnt(0)
	s_barrier
	s_setprio 1
	s_waitcnt lgkmcnt(0)
	v_mfma_f32_16x16x32_bf16 v[130:133], v[150:153], v[190:193], v[130:133]
	v_mfma_f32_16x16x32_bf16 v[130:133], v[154:157], v[194:197], v[130:133]
	v_mfma_f32_16x16x32_bf16 v[126:129], v[170:173], v[194:197], v[126:129]
	v_mfma_f32_16x16x32_bf16 v[126:129], v[158:161], v[190:193], v[126:129]
	v_mfma_f32_16x16x32_bf16 v[118:121], v[158:161], v[202:205], v[118:121]
	v_mfma_f32_16x16x32_bf16 v[118:121], v[170:173], v[206:209], v[118:121]
	v_mfma_f32_16x16x32_bf16 v[122:125], v[154:157], v[206:209], v[122:125]
	v_mfma_f32_16x16x32_bf16 v[122:125], v[150:153], v[202:205], v[122:125]
	v_mfma_f32_16x16x32_bf16 v[114:117], v[150:153], v[210:213], v[114:117]
	v_mfma_f32_16x16x32_bf16 v[114:117], v[154:157], v[214:217], v[114:117]
	v_mfma_f32_16x16x32_bf16 v[110:113], v[170:173], v[214:217], v[110:113]
	v_mfma_f32_16x16x32_bf16 v[110:113], v[158:161], v[210:213], v[110:113]
	v_mfma_f32_16x16x32_bf16 v[102:105], v[158:161], v[218:221], v[102:105]
	v_mfma_f32_16x16x32_bf16 v[102:105], v[170:173], v[222:225], v[102:105]
	v_mfma_f32_16x16x32_bf16 v[106:109], v[154:157], v[222:225], v[106:109]
	v_mfma_f32_16x16x32_bf16 v[106:109], v[150:153], v[218:221], v[106:109]
	s_setprio 0
	s_setprio 1
	v_mfma_f32_16x16x32_bf16 v[98:101], v[174:177], v[190:193], v[98:101]
	v_mfma_f32_16x16x32_bf16 v[98:101], v[178:181], v[194:197], v[98:101]
	v_mfma_f32_16x16x32_bf16 v[94:97], v[186:189], v[194:197], v[94:97]
	v_mfma_f32_16x16x32_bf16 v[94:97], v[182:185], v[190:193], v[94:97]
	v_mfma_f32_16x16x32_bf16 v[86:89], v[182:185], v[202:205], v[86:89]
	v_mfma_f32_16x16x32_bf16 v[86:89], v[186:189], v[206:209], v[86:89]
	v_mfma_f32_16x16x32_bf16 v[90:93], v[178:181], v[206:209], v[90:93]
	v_mfma_f32_16x16x32_bf16 v[90:93], v[174:177], v[202:205], v[90:93]
	v_mfma_f32_16x16x32_bf16 v[82:85], v[174:177], v[210:213], v[82:85]
	v_mfma_f32_16x16x32_bf16 v[82:85], v[178:181], v[214:217], v[82:85]
	v_mfma_f32_16x16x32_bf16 v[78:81], v[186:189], v[214:217], v[78:81]
	v_mfma_f32_16x16x32_bf16 v[78:81], v[182:185], v[210:213], v[78:81]
	v_mfma_f32_16x16x32_bf16 v[70:73], v[182:185], v[218:221], v[70:73]
	v_mfma_f32_16x16x32_bf16 v[70:73], v[186:189], v[222:225], v[70:73]
	v_mfma_f32_16x16x32_bf16 v[74:77], v[178:181], v[222:225], v[74:77]
	v_mfma_f32_16x16x32_bf16 v[74:77], v[174:177], v[218:221], v[74:77]
	s_setprio 0
	s_barrier
	s_add_i32 s36, s71, s43
	v_lshl_add_u64 v[166:167], s[56:57], 0, v[138:139]
	s_mov_b32 m0, s36
	ds_read_b128 v[190:193], v169 offset:16384
	ds_read_b128 v[194:197], v169 offset:17408
	ds_read_b128 v[202:205], v169 offset:18432
	ds_read_b128 v[206:209], v169 offset:19456
	ds_read_b128 v[210:213], v169 offset:20480
	ds_read_b128 v[214:217], v169 offset:21504
	ds_read_b128 v[218:221], v169 offset:22528
	ds_read_b128 v[222:225], v169 offset:23552
	global_load_lds_dwordx4 v[166:167], off
	s_add_i32 m0, s36, 0x2000
	s_add_u32 s80, s56, 0x80000
	v_lshl_add_u64 v[198:199], s[56:57], 0, v[134:135]
	s_addc_u32 s81, s57, 0
	s_add_i32 s36, s72, s43
	global_load_lds_dwordx4 v[198:199], off
	v_lshl_add_u64 v[4:5], s[80:81], 0, v[138:139]
	s_mov_b32 m0, s36
	v_lshl_add_u64 v[226:227], s[58:59], 0, v[140:141]
	global_load_lds_dwordx4 v[4:5], off
	v_lshl_add_u64 v[4:5], s[80:81], 0, v[134:135]
	s_add_i32 m0, s36, 0x2000
	v_lshl_add_u64 v[228:229], s[58:59], 0, v[136:137]
	global_load_lds_dwordx4 v[4:5], off
	s_mov_b32 m0, s63
	s_nop 0
	global_load_lds_dwordx4 v[226:227], off
	s_mov_b32 m0, s64
	s_nop 0
	global_load_lds_dwordx4 v[228:229], off
	s_waitcnt vmcnt(8)
	s_waitcnt lgkmcnt(0)
	s_barrier
	s_setprio 1
	s_waitcnt lgkmcnt(0)
	v_mfma_f32_16x16x32_bf16 v[66:69], v[150:153], v[190:193], v[66:69]
	v_mfma_f32_16x16x32_bf16 v[66:69], v[154:157], v[194:197], v[66:69]
	v_mfma_f32_16x16x32_bf16 v[62:65], v[170:173], v[194:197], v[62:65]
	v_mfma_f32_16x16x32_bf16 v[62:65], v[158:161], v[190:193], v[62:65]
	v_mfma_f32_16x16x32_bf16 v[54:57], v[158:161], v[202:205], v[54:57]
	v_mfma_f32_16x16x32_bf16 v[54:57], v[170:173], v[206:209], v[54:57]
	v_mfma_f32_16x16x32_bf16 v[58:61], v[154:157], v[206:209], v[58:61]
	v_mfma_f32_16x16x32_bf16 v[58:61], v[150:153], v[202:205], v[58:61]
	v_mfma_f32_16x16x32_bf16 v[50:53], v[150:153], v[210:213], v[50:53]
	v_mfma_f32_16x16x32_bf16 v[50:53], v[154:157], v[214:217], v[50:53]
	v_mfma_f32_16x16x32_bf16 v[46:49], v[170:173], v[214:217], v[46:49]
	v_mfma_f32_16x16x32_bf16 v[46:49], v[158:161], v[210:213], v[46:49]
	v_mfma_f32_16x16x32_bf16 v[38:41], v[158:161], v[218:221], v[38:41]
	v_mfma_f32_16x16x32_bf16 v[38:41], v[170:173], v[222:225], v[38:41]
	v_mfma_f32_16x16x32_bf16 v[42:45], v[154:157], v[222:225], v[42:45]
	v_mfma_f32_16x16x32_bf16 v[42:45], v[150:153], v[218:221], v[42:45]
	s_setprio 0
	s_setprio 1
	v_mfma_f32_16x16x32_bf16 v[34:37], v[174:177], v[190:193], v[34:37]
	v_mfma_f32_16x16x32_bf16 v[30:33], v[182:185], v[190:193], v[30:33]
	v_mfma_f32_16x16x32_bf16 v[26:29], v[174:177], v[202:205], v[26:29]
	v_mfma_f32_16x16x32_bf16 v[22:25], v[182:185], v[202:205], v[22:25]
	v_mfma_f32_16x16x32_bf16 v[18:21], v[174:177], v[210:213], v[18:21]
	v_mfma_f32_16x16x32_bf16 v[14:17], v[182:185], v[210:213], v[14:17]
	v_mfma_f32_16x16x32_bf16 v[10:13], v[174:177], v[218:221], v[10:13]
	v_mfma_f32_16x16x32_bf16 v[4:7], v[182:185], v[218:221], v[6:9]
	v_mfma_f32_16x16x32_bf16 v[34:37], v[178:181], v[194:197], v[34:37]
	v_mfma_f32_16x16x32_bf16 v[30:33], v[186:189], v[194:197], v[30:33]
	v_mfma_f32_16x16x32_bf16 v[26:29], v[178:181], v[206:209], v[26:29]
	v_mfma_f32_16x16x32_bf16 v[22:25], v[186:189], v[206:209], v[22:25]
	v_mfma_f32_16x16x32_bf16 v[18:21], v[178:181], v[214:217], v[18:21]
	v_mfma_f32_16x16x32_bf16 v[14:17], v[186:189], v[214:217], v[14:17]
	v_mfma_f32_16x16x32_bf16 v[10:13], v[178:181], v[222:225], v[10:13]
	v_mfma_f32_16x16x32_bf16 v[4:7], v[186:189], v[222:225], v[4:7]
	s_setprio 0
	s_barrier
	s_add_i32 s36, 0, 0x18000
	v_add_u32_e32 v3, s36, v165
	s_add_i32 s37, 0, 0x1c000
	ds_read_b128 v[150:153], v3
	ds_read_b128 v[154:157], v3 offset:1024
	ds_read_b128 v[158:161], v3 offset:2048
	ds_read_b128 v[170:173], v3 offset:3072
	v_add_u32_e32 v3, s37, v165
	ds_read_b128 v[174:177], v3
	ds_read_b128 v[178:181], v3 offset:1024
	ds_read_b128 v[182:185], v3 offset:2048
	ds_read_b128 v[186:189], v3 offset:3072
	s_add_u32 s58, s58, 0x80000
	s_addc_u32 s59, s59, 0
	s_mov_b32 m0, s65
	v_lshl_add_u64 v[8:9], s[58:59], 0, v[140:141]
	ds_read_b128 v[190:193], v169 offset:32768
	ds_read_b128 v[194:197], v169 offset:33792
	ds_read_b128 v[202:205], v169 offset:34816
	ds_read_b128 v[206:209], v169 offset:35840
	ds_read_b128 v[210:213], v169 offset:36864
	ds_read_b128 v[214:217], v169 offset:37888
	ds_read_b128 v[218:221], v169 offset:38912
	ds_read_b128 v[222:225], v169 offset:39936
	global_load_lds_dwordx4 v[8:9], off
	v_lshl_add_u64 v[8:9], s[58:59], 0, v[136:137]
	s_mov_b32 m0, s66
	s_nop 0
	global_load_lds_dwordx4 v[8:9], off
	s_nop 0
	s_waitcnt vmcnt(8)
	s_waitcnt lgkmcnt(0)
	s_barrier
	s_setprio 1
	s_waitcnt lgkmcnt(0)
	v_mfma_f32_16x16x32_bf16 v[130:133], v[150:153], v[190:193], v[130:133]
	v_mfma_f32_16x16x32_bf16 v[130:133], v[154:157], v[194:197], v[130:133]
	v_mfma_f32_16x16x32_bf16 v[126:129], v[170:173], v[194:197], v[126:129]
	v_mfma_f32_16x16x32_bf16 v[126:129], v[158:161], v[190:193], v[126:129]
	v_mfma_f32_16x16x32_bf16 v[118:121], v[158:161], v[202:205], v[118:121]
	v_mfma_f32_16x16x32_bf16 v[118:121], v[170:173], v[206:209], v[118:121]
	v_mfma_f32_16x16x32_bf16 v[122:125], v[154:157], v[206:209], v[122:125]
	v_mfma_f32_16x16x32_bf16 v[122:125], v[150:153], v[202:205], v[122:125]
	v_mfma_f32_16x16x32_bf16 v[114:117], v[150:153], v[210:213], v[114:117]
	v_mfma_f32_16x16x32_bf16 v[114:117], v[154:157], v[214:217], v[114:117]
	v_mfma_f32_16x16x32_bf16 v[110:113], v[170:173], v[214:217], v[110:113]
	v_mfma_f32_16x16x32_bf16 v[110:113], v[158:161], v[210:213], v[110:113]
	v_mfma_f32_16x16x32_bf16 v[102:105], v[158:161], v[218:221], v[102:105]
	v_mfma_f32_16x16x32_bf16 v[102:105], v[170:173], v[222:225], v[102:105]
	v_mfma_f32_16x16x32_bf16 v[106:109], v[154:157], v[222:225], v[106:109]
	v_mfma_f32_16x16x32_bf16 v[106:109], v[150:153], v[218:221], v[106:109]
	s_setprio 0
	s_setprio 1
	v_mfma_f32_16x16x32_bf16 v[98:101], v[174:177], v[190:193], v[98:101]
	v_mfma_f32_16x16x32_bf16 v[98:101], v[178:181], v[194:197], v[98:101]
	v_mfma_f32_16x16x32_bf16 v[94:97], v[186:189], v[194:197], v[94:97]
	v_mfma_f32_16x16x32_bf16 v[94:97], v[182:185], v[190:193], v[94:97]
	v_mfma_f32_16x16x32_bf16 v[86:89], v[182:185], v[202:205], v[86:89]
	v_mfma_f32_16x16x32_bf16 v[86:89], v[186:189], v[206:209], v[86:89]
	v_mfma_f32_16x16x32_bf16 v[90:93], v[178:181], v[206:209], v[90:93]
	v_mfma_f32_16x16x32_bf16 v[90:93], v[174:177], v[202:205], v[90:93]
	v_mfma_f32_16x16x32_bf16 v[82:85], v[174:177], v[210:213], v[82:85]
	v_mfma_f32_16x16x32_bf16 v[82:85], v[178:181], v[214:217], v[82:85]
	v_mfma_f32_16x16x32_bf16 v[78:81], v[186:189], v[214:217], v[78:81]
	v_mfma_f32_16x16x32_bf16 v[78:81], v[182:185], v[210:213], v[78:81]
	v_mfma_f32_16x16x32_bf16 v[70:73], v[182:185], v[218:221], v[70:73]
	v_mfma_f32_16x16x32_bf16 v[70:73], v[186:189], v[222:225], v[70:73]
	v_mfma_f32_16x16x32_bf16 v[74:77], v[178:181], v[222:225], v[74:77]
	v_mfma_f32_16x16x32_bf16 v[74:77], v[174:177], v[218:221], v[74:77]
	s_setprio 0
	s_barrier
	s_add_i32 s36, s36, s43
	v_lshl_add_u64 v[8:9], v[166:167], 0, s[10:11]
	s_mov_b32 m0, s36
	ds_read_b128 v[190:193], v169 offset:49152
	ds_read_b128 v[194:197], v169 offset:50176
	ds_read_b128 v[202:205], v169 offset:51200
	ds_read_b128 v[206:209], v169 offset:52224
	ds_read_b128 v[210:213], v169 offset:53248
	ds_read_b128 v[214:217], v169 offset:54272
	ds_read_b128 v[218:221], v169 offset:55296
	ds_read_b128 v[222:225], v169 offset:56320
	global_load_lds_dwordx4 v[8:9], off
	s_add_i32 m0, s36, 0x2000
	s_add_u32 s56, s56, 0x80080
	v_lshl_add_u64 v[8:9], v[198:199], 0, s[10:11]
	s_addc_u32 s57, s57, 0
	s_add_i32 s36, s37, s43
	global_load_lds_dwordx4 v[8:9], off
	v_lshl_add_u64 v[8:9], s[56:57], 0, v[138:139]
	s_mov_b32 m0, s36
	s_nop 0
	global_load_lds_dwordx4 v[8:9], off
	v_lshl_add_u64 v[8:9], s[56:57], 0, v[134:135]
	s_add_i32 m0, s36, 0x2000
	s_nop 0
	global_load_lds_dwordx4 v[8:9], off
	v_lshl_add_u64 v[8:9], v[226:227], 0, s[10:11]
	s_mov_b32 m0, s69
	s_nop 0
	global_load_lds_dwordx4 v[8:9], off
	v_lshl_add_u64 v[8:9], v[228:229], 0, s[10:11]
	s_mov_b32 m0, s70
	s_nop 0
	global_load_lds_dwordx4 v[8:9], off
	s_waitcnt vmcnt(8)
	s_waitcnt lgkmcnt(0)
	s_barrier
	s_setprio 1
	s_waitcnt lgkmcnt(0)
	v_mfma_f32_16x16x32_bf16 v[66:69], v[150:153], v[190:193], v[66:69]
	v_mfma_f32_16x16x32_bf16 v[66:69], v[154:157], v[194:197], v[66:69]
	v_mfma_f32_16x16x32_bf16 v[62:65], v[170:173], v[194:197], v[62:65]
	v_mfma_f32_16x16x32_bf16 v[62:65], v[158:161], v[190:193], v[62:65]
	v_mfma_f32_16x16x32_bf16 v[54:57], v[158:161], v[202:205], v[54:57]
	v_mfma_f32_16x16x32_bf16 v[54:57], v[170:173], v[206:209], v[54:57]
	v_mfma_f32_16x16x32_bf16 v[58:61], v[154:157], v[206:209], v[58:61]
	v_mfma_f32_16x16x32_bf16 v[58:61], v[150:153], v[202:205], v[58:61]
	v_mfma_f32_16x16x32_bf16 v[50:53], v[150:153], v[210:213], v[50:53]
	v_mfma_f32_16x16x32_bf16 v[50:53], v[154:157], v[214:217], v[50:53]
	v_mfma_f32_16x16x32_bf16 v[46:49], v[170:173], v[214:217], v[46:49]
	v_mfma_f32_16x16x32_bf16 v[46:49], v[158:161], v[210:213], v[46:49]
	v_mfma_f32_16x16x32_bf16 v[38:41], v[158:161], v[218:221], v[38:41]
	v_mfma_f32_16x16x32_bf16 v[38:41], v[170:173], v[222:225], v[38:41]
	v_mfma_f32_16x16x32_bf16 v[42:45], v[154:157], v[222:225], v[42:45]
	v_mfma_f32_16x16x32_bf16 v[42:45], v[150:153], v[218:221], v[42:45]
	s_setprio 0
	s_setprio 1
	v_mfma_f32_16x16x32_bf16 v[34:37], v[174:177], v[190:193], v[34:37]
	v_mfma_f32_16x16x32_bf16 v[30:33], v[182:185], v[190:193], v[30:33]
	v_mfma_f32_16x16x32_bf16 v[26:29], v[174:177], v[202:205], v[26:29]
	v_mfma_f32_16x16x32_bf16 v[22:25], v[182:185], v[202:205], v[22:25]
	v_mfma_f32_16x16x32_bf16 v[18:21], v[174:177], v[210:213], v[18:21]
	v_mfma_f32_16x16x32_bf16 v[14:17], v[182:185], v[210:213], v[14:17]
	v_mfma_f32_16x16x32_bf16 v[8:11], v[174:177], v[218:221], v[10:13]
	v_mfma_f32_16x16x32_bf16 v[4:7], v[182:185], v[218:221], v[4:7]
	v_mfma_f32_16x16x32_bf16 v[34:37], v[178:181], v[194:197], v[34:37]
	v_mfma_f32_16x16x32_bf16 v[30:33], v[186:189], v[194:197], v[30:33]
	v_mfma_f32_16x16x32_bf16 v[26:29], v[178:181], v[206:209], v[26:29]
	v_mfma_f32_16x16x32_bf16 v[22:25], v[186:189], v[206:209], v[22:25]
	v_mfma_f32_16x16x32_bf16 v[18:21], v[178:181], v[214:217], v[18:21]
	v_mfma_f32_16x16x32_bf16 v[14:17], v[186:189], v[214:217], v[14:17]
	v_mfma_f32_16x16x32_bf16 v[10:13], v[178:181], v[222:225], v[8:11]
	v_mfma_f32_16x16x32_bf16 v[6:9], v[186:189], v[222:225], v[4:7]
	s_setprio 0
	s_barrier
	s_add_i32 s78, s78, 2
	s_add_u32 s52, s52, 0x100
	s_addc_u32 s53, s53, 0
	s_add_u32 s76, s76, 0x100
	s_addc_u32 s77, s77, 0
	s_cmp_gt_u32 s78, 29
	s_cbranch_scc0 .LBB0_1226
	s_and_b64 vcc, exec, s[12:13]
	s_cbranch_vccz .LBB0_1229
	s_barrier

.LBB0_1397:
	ds_read_b128 v[146:149], v154
	ds_read_b128 v[158:161], v154 offset:1024
	ds_read_b128 v[166:169], v154 offset:2048
	ds_read_b128 v[170:173], v154 offset:3072
	ds_read_b128 v[174:177], v155
	ds_read_b128 v[178:181], v155 offset:1024
	ds_read_b128 v[182:185], v155 offset:2048
	ds_read_b128 v[186:189], v155 offset:3072
	s_add_i32 s93, s44, 2
	s_add_u32 s36, s62, 0xfff00080
	s_addc_u32 s37, s63, -1
	s_cmp_eq_u32 s59, s44
	s_cselect_b32 s67, s38, s37
	s_cselect_b32 s66, s39, s36
	s_cselect_b32 s65, s51, s92
	s_cselect_b32 s64, s53, s61
	v_lshl_add_u64 v[150:151], s[62:63], 0, v[140:141]
	s_add_i32 m0, s72, 0xc000
	ds_read_b128 v[190:193], v156
	ds_read_b128 v[194:197], v156 offset:1024
	ds_read_b128 v[202:205], v156 offset:2048
	ds_read_b128 v[206:209], v156 offset:3072
	ds_read_b128 v[210:213], v156 offset:4096
	ds_read_b128 v[214:217], v156 offset:5120
	ds_read_b128 v[218:221], v156 offset:6144
	ds_read_b128 v[222:225], v156 offset:7168
	global_load_lds_dwordx4 v[150:151], off
	v_lshl_add_u64 v[150:151], s[62:63], 0, v[142:143]
	s_add_i32 m0, s72, 0xe000
	s_nop 0
	global_load_lds_dwordx4 v[150:151], off
	s_waitcnt vmcnt(8)
	s_waitcnt lgkmcnt(0)
	s_barrier
	s_setprio 1
	s_waitcnt lgkmcnt(0)
	v_mfma_f32_16x16x32_bf16 v[126:129], v[146:149], v[190:193], v[126:129]
	v_mfma_f32_16x16x32_bf16 v[126:129], v[158:161], v[194:197], v[126:129]
	v_mfma_f32_16x16x32_bf16 v[122:125], v[170:173], v[194:197], v[122:125]
	v_mfma_f32_16x16x32_bf16 v[122:125], v[166:169], v[190:193], v[122:125]
	v_mfma_f32_16x16x32_bf16 v[106:109], v[166:169], v[202:205], v[106:109]
	v_mfma_f32_16x16x32_bf16 v[106:109], v[170:173], v[206:209], v[106:109]
	v_mfma_f32_16x16x32_bf16 v[110:113], v[158:161], v[206:209], v[110:113]
	v_mfma_f32_16x16x32_bf16 v[110:113], v[146:149], v[202:205], v[110:113]
	v_mfma_f32_16x16x32_bf16 v[94:97], v[146:149], v[210:213], v[94:97]
	v_mfma_f32_16x16x32_bf16 v[94:97], v[158:161], v[214:217], v[94:97]
	v_mfma_f32_16x16x32_bf16 v[90:93], v[170:173], v[214:217], v[90:93]
	v_mfma_f32_16x16x32_bf16 v[90:93], v[166:169], v[210:213], v[90:93]
	v_mfma_f32_16x16x32_bf16 v[74:77], v[166:169], v[218:221], v[74:77]
	v_mfma_f32_16x16x32_bf16 v[74:77], v[170:173], v[222:225], v[74:77]
	v_mfma_f32_16x16x32_bf16 v[78:81], v[158:161], v[222:225], v[78:81]
	v_mfma_f32_16x16x32_bf16 v[78:81], v[146:149], v[218:221], v[78:81]
	s_setprio 0
	s_setprio 1
	v_mfma_f32_16x16x32_bf16 v[118:121], v[174:177], v[190:193], v[118:121]
	v_mfma_f32_16x16x32_bf16 v[118:121], v[178:181], v[194:197], v[118:121]
	v_mfma_f32_16x16x32_bf16 v[114:117], v[186:189], v[194:197], v[114:117]
	v_mfma_f32_16x16x32_bf16 v[114:117], v[182:185], v[190:193], v[114:117]
	v_mfma_f32_16x16x32_bf16 v[98:101], v[182:185], v[202:205], v[98:101]
	v_mfma_f32_16x16x32_bf16 v[98:101], v[186:189], v[206:209], v[98:101]
	v_mfma_f32_16x16x32_bf16 v[102:105], v[178:181], v[206:209], v[102:105]
	v_mfma_f32_16x16x32_bf16 v[102:105], v[174:177], v[202:205], v[102:105]
	v_mfma_f32_16x16x32_bf16 v[86:89], v[174:177], v[210:213], v[86:89]
	v_mfma_f32_16x16x32_bf16 v[86:89], v[178:181], v[214:217], v[86:89]
	v_mfma_f32_16x16x32_bf16 v[82:85], v[186:189], v[214:217], v[82:85]
	v_mfma_f32_16x16x32_bf16 v[82:85], v[182:185], v[210:213], v[82:85]
	v_mfma_f32_16x16x32_bf16 v[66:69], v[182:185], v[218:221], v[66:69]
	v_mfma_f32_16x16x32_bf16 v[66:69], v[186:189], v[222:225], v[66:69]
	v_mfma_f32_16x16x32_bf16 v[70:73], v[178:181], v[222:225], v[70:73]
	v_mfma_f32_16x16x32_bf16 v[70:73], v[174:177], v[218:221], v[70:73]
	s_setprio 0
	s_barrier
	s_add_i32 s36, s82, s69
	v_lshl_add_u64 v[150:151], s[64:65], 0, v[132:133]
	s_mov_b32 m0, s36
	ds_read_b128 v[190:193], v156 offset:16384
	ds_read_b128 v[194:197], v156 offset:17408
	ds_read_b128 v[202:205], v156 offset:18432
	ds_read_b128 v[206:209], v156 offset:19456
	ds_read_b128 v[210:213], v156 offset:20480
	ds_read_b128 v[214:217], v156 offset:21504
	ds_read_b128 v[218:221], v156 offset:22528
	ds_read_b128 v[222:225], v156 offset:23552
	global_load_lds_dwordx4 v[150:151], off
	s_add_i32 m0, s36, 0x2000
	s_add_u32 s94, s64, 0x100000
	v_lshl_add_u64 v[198:199], s[64:65], 0, v[136:137]
	s_addc_u32 s95, s65, 0
	s_add_i32 s36, s83, s69
	global_load_lds_dwordx4 v[198:199], off
	v_lshl_add_u64 v[226:227], s[94:95], 0, v[132:133]
	s_mov_b32 m0, s36
	v_lshl_add_u64 v[228:229], s[66:67], 0, v[134:135]
	global_load_lds_dwordx4 v[226:227], off
	v_lshl_add_u64 v[226:227], s[94:95], 0, v[136:137]
	s_add_i32 m0, s36, 0x2000
	s_nop 0
	global_load_lds_dwordx4 v[226:227], off
	v_lshl_add_u64 v[226:227], s[66:67], 0, v[130:131]
	s_mov_b32 m0, s72
	s_nop 0
	global_load_lds_dwordx4 v[226:227], off
	s_mov_b32 m0, s73
	s_nop 0
	global_load_lds_dwordx4 v[228:229], off
	s_nop 0
	s_waitcnt vmcnt(8)
	s_waitcnt lgkmcnt(0)
	s_barrier
	s_setprio 1
	s_waitcnt lgkmcnt(0)
	v_mfma_f32_16x16x32_bf16 v[62:65], v[146:149], v[190:193], v[62:65]
	v_mfma_f32_16x16x32_bf16 v[62:65], v[158:161], v[194:197], v[62:65]
	v_mfma_f32_16x16x32_bf16 v[58:61], v[170:173], v[194:197], v[58:61]
	v_mfma_f32_16x16x32_bf16 v[58:61], v[166:169], v[190:193], v[58:61]
	v_mfma_f32_16x16x32_bf16 v[42:45], v[166:169], v[202:205], v[42:45]
	v_mfma_f32_16x16x32_bf16 v[42:45], v[170:173], v[206:209], v[42:45]
	v_mfma_f32_16x16x32_bf16 v[46:49], v[158:161], v[206:209], v[46:49]
	v_mfma_f32_16x16x32_bf16 v[46:49], v[146:149], v[202:205], v[46:49]
	v_mfma_f32_16x16x32_bf16 v[30:33], v[146:149], v[210:213], v[30:33]
	v_mfma_f32_16x16x32_bf16 v[30:33], v[158:161], v[214:217], v[30:33]
	v_mfma_f32_16x16x32_bf16 v[26:29], v[170:173], v[214:217], v[26:29]
	v_mfma_f32_16x16x32_bf16 v[26:29], v[166:169], v[210:213], v[26:29]
	v_mfma_f32_16x16x32_bf16 v[10:13], v[166:169], v[218:221], v[10:13]
	v_mfma_f32_16x16x32_bf16 v[10:13], v[170:173], v[222:225], v[10:13]
	v_mfma_f32_16x16x32_bf16 v[14:17], v[158:161], v[222:225], v[14:17]
	v_mfma_f32_16x16x32_bf16 v[14:17], v[146:149], v[218:221], v[14:17]
	s_setprio 0
	s_setprio 1
	v_mfma_f32_16x16x32_bf16 v[54:57], v[174:177], v[190:193], v[54:57]
	v_mfma_f32_16x16x32_bf16 v[54:57], v[178:181], v[194:197], v[54:57]
	v_mfma_f32_16x16x32_bf16 v[50:53], v[186:189], v[194:197], v[50:53]
	v_mfma_f32_16x16x32_bf16 v[50:53], v[182:185], v[190:193], v[50:53]
	v_mfma_f32_16x16x32_bf16 v[34:37], v[182:185], v[202:205], v[34:37]
	v_mfma_f32_16x16x32_bf16 v[34:37], v[186:189], v[206:209], v[34:37]
	v_mfma_f32_16x16x32_bf16 v[38:41], v[178:181], v[206:209], v[38:41]
	v_mfma_f32_16x16x32_bf16 v[38:41], v[174:177], v[202:205], v[38:41]
	v_mfma_f32_16x16x32_bf16 v[22:25], v[174:177], v[210:213], v[22:25]
	v_mfma_f32_16x16x32_bf16 v[22:25], v[178:181], v[214:217], v[22:25]
	v_mfma_f32_16x16x32_bf16 v[18:21], v[186:189], v[214:217], v[18:21]
	v_mfma_f32_16x16x32_bf16 v[18:21], v[182:185], v[210:213], v[18:21]
	v_mfma_f32_16x16x32_bf16 v[2:5], v[182:185], v[218:221], v[2:5]
	v_mfma_f32_16x16x32_bf16 v[2:5], v[186:189], v[222:225], v[2:5]
	v_mfma_f32_16x16x32_bf16 v[6:9], v[178:181], v[222:225], v[6:9]
	v_mfma_f32_16x16x32_bf16 v[6:9], v[174:177], v[218:221], v[6:9]
	s_setprio 0
	s_barrier
	s_add_i32 s36, 0, 0x18000
	v_add_u32_e32 v138, s36, v152
	s_add_i32 s37, 0, 0x1c000
	ds_read_b128 v[146:149], v138
	ds_read_b128 v[158:161], v138 offset:1024
	ds_read_b128 v[166:169], v138 offset:2048
	ds_read_b128 v[170:173], v138 offset:3072
	v_add_u32_e32 v138, s37, v152
	ds_read_b128 v[174:177], v138
	ds_read_b128 v[178:181], v138 offset:1024
	ds_read_b128 v[182:185], v138 offset:2048
	ds_read_b128 v[186:189], v138 offset:3072
	s_add_u32 s66, s66, 0x100000
	s_addc_u32 s67, s67, 0
	s_mov_b32 m0, s74
	v_lshl_add_u64 v[230:231], s[66:67], 0, v[130:131]
	ds_read_b128 v[190:193], v156 offset:32768
	ds_read_b128 v[194:197], v156 offset:33792
	ds_read_b128 v[202:205], v156 offset:34816
	ds_read_b128 v[206:209], v156 offset:35840
	ds_read_b128 v[210:213], v156 offset:36864
	ds_read_b128 v[214:217], v156 offset:37888
	ds_read_b128 v[218:221], v156 offset:38912
	ds_read_b128 v[222:225], v156 offset:39936
	global_load_lds_dwordx4 v[230:231], off
	v_lshl_add_u64 v[230:231], s[66:67], 0, v[134:135]
	s_mov_b32 m0, s75
	s_nop 0
	global_load_lds_dwordx4 v[230:231], off
	s_nop 0
	s_waitcnt vmcnt(8)
	s_waitcnt lgkmcnt(0)
	s_barrier
	s_setprio 1
	s_waitcnt lgkmcnt(0)
	v_mfma_f32_16x16x32_bf16 v[126:129], v[146:149], v[190:193], v[126:129]
	v_mfma_f32_16x16x32_bf16 v[126:129], v[158:161], v[194:197], v[126:129]
	v_mfma_f32_16x16x32_bf16 v[122:125], v[170:173], v[194:197], v[122:125]
	v_mfma_f32_16x16x32_bf16 v[122:125], v[166:169], v[190:193], v[122:125]
	v_mfma_f32_16x16x32_bf16 v[106:109], v[166:169], v[202:205], v[106:109]
	v_mfma_f32_16x16x32_bf16 v[106:109], v[170:173], v[206:209], v[106:109]
	v_mfma_f32_16x16x32_bf16 v[110:113], v[158:161], v[206:209], v[110:113]
	v_mfma_f32_16x16x32_bf16 v[110:113], v[146:149], v[202:205], v[110:113]
	v_mfma_f32_16x16x32_bf16 v[94:97], v[146:149], v[210:213], v[94:97]
	v_mfma_f32_16x16x32_bf16 v[94:97], v[158:161], v[214:217], v[94:97]
	v_mfma_f32_16x16x32_bf16 v[90:93], v[170:173], v[214:217], v[90:93]
	v_mfma_f32_16x16x32_bf16 v[90:93], v[166:169], v[210:213], v[90:93]
	v_mfma_f32_16x16x32_bf16 v[74:77], v[166:169], v[218:221], v[74:77]
	v_mfma_f32_16x16x32_bf16 v[74:77], v[170:173], v[222:225], v[74:77]
	v_mfma_f32_16x16x32_bf16 v[78:81], v[158:161], v[222:225], v[78:81]
	v_mfma_f32_16x16x32_bf16 v[78:81], v[146:149], v[218:221], v[78:81]
	s_setprio 0
	s_setprio 1
	v_mfma_f32_16x16x32_bf16 v[118:121], v[174:177], v[190:193], v[118:121]
	v_mfma_f32_16x16x32_bf16 v[118:121], v[178:181], v[194:197], v[118:121]
	v_mfma_f32_16x16x32_bf16 v[114:117], v[186:189], v[194:197], v[114:117]
	v_mfma_f32_16x16x32_bf16 v[114:117], v[182:185], v[190:193], v[114:117]
	v_mfma_f32_16x16x32_bf16 v[98:101], v[182:185], v[202:205], v[98:101]
	v_mfma_f32_16x16x32_bf16 v[98:101], v[186:189], v[206:209], v[98:101]
	v_mfma_f32_16x16x32_bf16 v[102:105], v[178:181], v[206:209], v[102:105]
	v_mfma_f32_16x16x32_bf16 v[102:105], v[174:177], v[202:205], v[102:105]
	v_mfma_f32_16x16x32_bf16 v[86:89], v[174:177], v[210:213], v[86:89]
	v_mfma_f32_16x16x32_bf16 v[86:89], v[178:181], v[214:217], v[86:89]
	v_mfma_f32_16x16x32_bf16 v[82:85], v[186:189], v[214:217], v[82:85]
	v_mfma_f32_16x16x32_bf16 v[82:85], v[182:185], v[210:213], v[82:85]
	v_mfma_f32_16x16x32_bf16 v[66:69], v[182:185], v[218:221], v[66:69]
	v_mfma_f32_16x16x32_bf16 v[66:69], v[186:189], v[222:225], v[66:69]
	v_mfma_f32_16x16x32_bf16 v[70:73], v[178:181], v[222:225], v[70:73]
	v_mfma_f32_16x16x32_bf16 v[70:73], v[174:177], v[218:221], v[70:73]
	s_setprio 0
	s_barrier
	s_add_i32 s36, s36, s69
	v_lshl_add_u64 v[150:151], v[150:151], 0, s[16:17]
	s_mov_b32 m0, s36
	ds_read_b128 v[190:193], v156 offset:49152
	ds_read_b128 v[194:197], v156 offset:50176
	ds_read_b128 v[202:205], v156 offset:51200
	ds_read_b128 v[206:209], v156 offset:52224
	ds_read_b128 v[210:213], v156 offset:53248
	ds_read_b128 v[214:217], v156 offset:54272
	ds_read_b128 v[218:221], v156 offset:55296
	ds_read_b128 v[222:225], v156 offset:56320
	global_load_lds_dwordx4 v[150:151], off
	s_add_i32 m0, s36, 0x2000
	s_add_u32 s64, s64, 0x100080
	v_lshl_add_u64 v[150:151], v[198:199], 0, s[16:17]
	s_addc_u32 s65, s65, 0
	s_add_i32 s36, s37, s69
	global_load_lds_dwordx4 v[150:151], off
	v_lshl_add_u64 v[150:151], s[64:65], 0, v[132:133]
	s_mov_b32 m0, s36
	s_nop 0
	global_load_lds_dwordx4 v[150:151], off
	v_lshl_add_u64 v[150:151], s[64:65], 0, v[136:137]
	s_add_i32 m0, s36, 0x2000
	s_nop 0
	global_load_lds_dwordx4 v[150:151], off
	v_lshl_add_u64 v[150:151], v[226:227], 0, s[16:17]
	s_mov_b32 m0, s78
	s_nop 0
	global_load_lds_dwordx4 v[150:151], off
	v_lshl_add_u64 v[150:151], v[228:229], 0, s[16:17]
	s_mov_b32 m0, s79
	s_nop 0
	global_load_lds_dwordx4 v[150:151], off
	s_waitcnt vmcnt(8)
	s_waitcnt lgkmcnt(0)
	s_barrier
	s_setprio 1
	s_waitcnt lgkmcnt(0)
	v_mfma_f32_16x16x32_bf16 v[62:65], v[146:149], v[190:193], v[62:65]
	v_mfma_f32_16x16x32_bf16 v[62:65], v[158:161], v[194:197], v[62:65]
	v_mfma_f32_16x16x32_bf16 v[58:61], v[170:173], v[194:197], v[58:61]
	v_mfma_f32_16x16x32_bf16 v[58:61], v[166:169], v[190:193], v[58:61]
	v_mfma_f32_16x16x32_bf16 v[42:45], v[166:169], v[202:205], v[42:45]
	v_mfma_f32_16x16x32_bf16 v[42:45], v[170:173], v[206:209], v[42:45]
	v_mfma_f32_16x16x32_bf16 v[46:49], v[158:161], v[206:209], v[46:49]
	v_mfma_f32_16x16x32_bf16 v[46:49], v[146:149], v[202:205], v[46:49]
	v_mfma_f32_16x16x32_bf16 v[30:33], v[146:149], v[210:213], v[30:33]
	v_mfma_f32_16x16x32_bf16 v[30:33], v[158:161], v[214:217], v[30:33]
	v_mfma_f32_16x16x32_bf16 v[26:29], v[170:173], v[214:217], v[26:29]
	v_mfma_f32_16x16x32_bf16 v[26:29], v[166:169], v[210:213], v[26:29]
	v_mfma_f32_16x16x32_bf16 v[10:13], v[166:169], v[218:221], v[10:13]
	v_mfma_f32_16x16x32_bf16 v[10:13], v[170:173], v[222:225], v[10:13]
	v_mfma_f32_16x16x32_bf16 v[14:17], v[158:161], v[222:225], v[14:17]
	v_mfma_f32_16x16x32_bf16 v[14:17], v[146:149], v[218:221], v[14:17]
	s_setprio 0
	s_setprio 1
	v_mfma_f32_16x16x32_bf16 v[54:57], v[174:177], v[190:193], v[54:57]
	v_mfma_f32_16x16x32_bf16 v[54:57], v[178:181], v[194:197], v[54:57]
	v_mfma_f32_16x16x32_bf16 v[50:53], v[186:189], v[194:197], v[50:53]
	v_mfma_f32_16x16x32_bf16 v[50:53], v[182:185], v[190:193], v[50:53]
	v_mfma_f32_16x16x32_bf16 v[34:37], v[182:185], v[202:205], v[34:37]
	v_mfma_f32_16x16x32_bf16 v[34:37], v[186:189], v[206:209], v[34:37]
	v_mfma_f32_16x16x32_bf16 v[38:41], v[178:181], v[206:209], v[38:41]
	v_mfma_f32_16x16x32_bf16 v[38:41], v[174:177], v[202:205], v[38:41]
	v_mfma_f32_16x16x32_bf16 v[22:25], v[174:177], v[210:213], v[22:25]
	v_mfma_f32_16x16x32_bf16 v[22:25], v[178:181], v[214:217], v[22:25]
	v_mfma_f32_16x16x32_bf16 v[18:21], v[186:189], v[214:217], v[18:21]
	v_mfma_f32_16x16x32_bf16 v[18:21], v[182:185], v[210:213], v[18:21]
	v_mfma_f32_16x16x32_bf16 v[2:5], v[182:185], v[218:221], v[2:5]
	v_mfma_f32_16x16x32_bf16 v[2:5], v[186:189], v[222:225], v[2:5]
	v_mfma_f32_16x16x32_bf16 v[6:9], v[178:181], v[222:225], v[6:9]
	v_mfma_f32_16x16x32_bf16 v[6:9], v[174:177], v[218:221], v[6:9]
	s_setprio 0
	s_barrier
	s_add_u32 s62, s62, 0x100
	s_addc_u32 s63, s63, 0
	s_add_u32 s61, s61, 0x100
	s_addc_u32 s92, s92, 0
	s_cmp_ge_i32 s93, s11
	s_mov_b32 s44, s93
	s_cbranch_scc0 .LBB0_1397
	s_and_b64 vcc, exec, s[18:19]
	s_cbranch_vccz .LBB0_1400

.LBB0_1631:
	ds_read_b128 v[166:169], v158
	ds_read_b128 v[170:173], v158 offset:1024
	ds_read_b128 v[174:177], v158 offset:2048
	ds_read_b128 v[178:181], v158 offset:3072
	ds_read_b128 v[182:185], v159
	ds_read_b128 v[186:189], v159 offset:1024
	ds_read_b128 v[190:193], v159 offset:2048
	ds_read_b128 v[194:197], v159 offset:3072
	s_add_u32 s36, s54, 0xfff00080
	s_addc_u32 s37, s55, -1
	s_cmp_eq_u32 s78, 60
	s_cselect_b32 s59, s21, s37
	s_cselect_b32 s58, s74, s36
	s_cselect_b32 s57, s19, s77
	s_cselect_b32 s56, s75, s76
	v_lshl_add_u64 v[198:199], s[54:55], 0, v[140:141]
	s_add_i32 m0, s53, 0xc000
	ds_read_b128 v[202:205], v160
	ds_read_b128 v[206:209], v160 offset:1024
	ds_read_b128 v[210:213], v160 offset:2048
	ds_read_b128 v[214:217], v160 offset:3072
	ds_read_b128 v[218:221], v160 offset:4096
	ds_read_b128 v[222:225], v160 offset:5120
	ds_read_b128 v[226:229], v160 offset:6144
	ds_read_b128 v[230:233], v160 offset:7168
	global_load_lds_dwordx4 v[198:199], off
	v_lshl_add_u64 v[198:199], s[54:55], 0, v[142:143]
	s_add_i32 m0, s53, 0xe000
	s_nop 0
	global_load_lds_dwordx4 v[198:199], off
	s_nop 0
	s_waitcnt vmcnt(8)
	s_waitcnt lgkmcnt(0)
	s_barrier
	s_setprio 1
	s_waitcnt lgkmcnt(0)
	v_mfma_f32_16x16x32_bf16 v[126:129], v[166:169], v[202:205], v[126:129]
	v_mfma_f32_16x16x32_bf16 v[126:129], v[170:173], v[206:209], v[126:129]
	v_mfma_f32_16x16x32_bf16 v[122:125], v[178:181], v[206:209], v[122:125]
	v_mfma_f32_16x16x32_bf16 v[122:125], v[174:177], v[202:205], v[122:125]
	v_mfma_f32_16x16x32_bf16 v[110:113], v[174:177], v[210:213], v[110:113]
	v_mfma_f32_16x16x32_bf16 v[110:113], v[178:181], v[214:217], v[110:113]
	v_mfma_f32_16x16x32_bf16 v[118:121], v[170:173], v[214:217], v[118:121]
	v_mfma_f32_16x16x32_bf16 v[118:121], v[166:169], v[210:213], v[118:121]
	v_mfma_f32_16x16x32_bf16 v[102:105], v[166:169], v[218:221], v[102:105]
	v_mfma_f32_16x16x32_bf16 v[102:105], v[170:173], v[222:225], v[102:105]
	v_mfma_f32_16x16x32_bf16 v[94:97], v[178:181], v[222:225], v[94:97]
	v_mfma_f32_16x16x32_bf16 v[94:97], v[174:177], v[218:221], v[94:97]
	v_mfma_f32_16x16x32_bf16 v[78:81], v[174:177], v[226:229], v[78:81]
	v_mfma_f32_16x16x32_bf16 v[78:81], v[178:181], v[230:233], v[78:81]
	v_mfma_f32_16x16x32_bf16 v[86:89], v[170:173], v[230:233], v[86:89]
	v_mfma_f32_16x16x32_bf16 v[86:89], v[166:169], v[226:229], v[86:89]
	s_setprio 0
	s_setprio 1
	v_mfma_f32_16x16x32_bf16 v[114:117], v[182:185], v[202:205], v[114:117]
	v_mfma_f32_16x16x32_bf16 v[114:117], v[186:189], v[206:209], v[114:117]
	v_mfma_f32_16x16x32_bf16 v[106:109], v[194:197], v[206:209], v[106:109]
	v_mfma_f32_16x16x32_bf16 v[106:109], v[190:193], v[202:205], v[106:109]
	v_mfma_f32_16x16x32_bf16 v[90:93], v[190:193], v[210:213], v[90:93]
	v_mfma_f32_16x16x32_bf16 v[90:93], v[194:197], v[214:217], v[90:93]
	v_mfma_f32_16x16x32_bf16 v[98:101], v[186:189], v[214:217], v[98:101]
	v_mfma_f32_16x16x32_bf16 v[98:101], v[182:185], v[210:213], v[98:101]
	v_mfma_f32_16x16x32_bf16 v[82:85], v[182:185], v[218:221], v[82:85]
	v_mfma_f32_16x16x32_bf16 v[82:85], v[186:189], v[222:225], v[82:85]
	v_mfma_f32_16x16x32_bf16 v[74:77], v[194:197], v[222:225], v[74:77]
	v_mfma_f32_16x16x32_bf16 v[74:77], v[190:193], v[218:221], v[74:77]
	v_mfma_f32_16x16x32_bf16 v[66:69], v[190:193], v[226:229], v[66:69]
	v_mfma_f32_16x16x32_bf16 v[66:69], v[194:197], v[230:233], v[66:69]
	v_mfma_f32_16x16x32_bf16 v[70:73], v[186:189], v[230:233], v[70:73]
	v_mfma_f32_16x16x32_bf16 v[70:73], v[182:185], v[226:229], v[70:73]
	s_setprio 0
	s_barrier
	s_add_i32 s36, s68, s38
	v_lshl_add_u64 v[198:199], s[56:57], 0, v[136:137]
	s_mov_b32 m0, s36
	ds_read_b128 v[202:205], v160 offset:16384
	ds_read_b128 v[206:209], v160 offset:17408
	ds_read_b128 v[210:213], v160 offset:18432
	ds_read_b128 v[214:217], v160 offset:19456
	ds_read_b128 v[218:221], v160 offset:20480
	ds_read_b128 v[222:225], v160 offset:21504
	ds_read_b128 v[226:229], v160 offset:22528
	ds_read_b128 v[230:233], v160 offset:23552
	global_load_lds_dwordx4 v[198:199], off
	s_add_i32 m0, s36, 0x2000
	s_add_u32 s80, s56, 0x100000
	v_lshl_add_u64 v[234:235], s[56:57], 0, v[132:133]
	s_addc_u32 s81, s57, 0
	s_add_i32 s36, s69, s38
	global_load_lds_dwordx4 v[234:235], off
	v_lshl_add_u64 v[236:237], s[80:81], 0, v[136:137]
	s_mov_b32 m0, s36
	v_lshl_add_u64 v[238:239], s[58:59], 0, v[134:135]
	global_load_lds_dwordx4 v[236:237], off
	v_lshl_add_u64 v[236:237], s[80:81], 0, v[132:133]
	s_add_i32 m0, s36, 0x2000
	s_nop 0
	global_load_lds_dwordx4 v[236:237], off
	v_lshl_add_u64 v[236:237], s[58:59], 0, v[138:139]
	s_mov_b32 m0, s53
	s_nop 0
	global_load_lds_dwordx4 v[236:237], off
	s_mov_b32 m0, s61
	s_nop 0
	global_load_lds_dwordx4 v[238:239], off
	s_nop 0
	s_waitcnt vmcnt(8)
	s_waitcnt lgkmcnt(0)
	s_barrier
	s_setprio 1
	s_waitcnt lgkmcnt(0)
	v_mfma_f32_16x16x32_bf16 v[62:65], v[166:169], v[202:205], v[62:65]
	v_mfma_f32_16x16x32_bf16 v[62:65], v[170:173], v[206:209], v[62:65]
	v_mfma_f32_16x16x32_bf16 v[58:61], v[178:181], v[206:209], v[58:61]
	v_mfma_f32_16x16x32_bf16 v[58:61], v[174:177], v[202:205], v[58:61]
	v_mfma_f32_16x16x32_bf16 v[46:49], v[174:177], v[210:213], v[46:49]
	v_mfma_f32_16x16x32_bf16 v[46:49], v[178:181], v[214:217], v[46:49]
	v_mfma_f32_16x16x32_bf16 v[54:57], v[170:173], v[214:217], v[54:57]
	v_mfma_f32_16x16x32_bf16 v[54:57], v[166:169], v[210:213], v[54:57]
	v_mfma_f32_16x16x32_bf16 v[38:41], v[166:169], v[218:221], v[38:41]
	v_mfma_f32_16x16x32_bf16 v[38:41], v[170:173], v[222:225], v[38:41]
	v_mfma_f32_16x16x32_bf16 v[30:33], v[178:181], v[222:225], v[30:33]
	v_mfma_f32_16x16x32_bf16 v[30:33], v[174:177], v[218:221], v[30:33]
	v_mfma_f32_16x16x32_bf16 v[14:17], v[174:177], v[226:229], v[14:17]
	v_mfma_f32_16x16x32_bf16 v[14:17], v[178:181], v[230:233], v[14:17]
	v_mfma_f32_16x16x32_bf16 v[22:25], v[170:173], v[230:233], v[22:25]
	v_mfma_f32_16x16x32_bf16 v[22:25], v[166:169], v[226:229], v[22:25]
	s_setprio 0
	s_setprio 1
	v_mfma_f32_16x16x32_bf16 v[50:53], v[182:185], v[202:205], v[50:53]
	v_mfma_f32_16x16x32_bf16 v[50:53], v[186:189], v[206:209], v[50:53]
	v_mfma_f32_16x16x32_bf16 v[42:45], v[194:197], v[206:209], v[42:45]
	v_mfma_f32_16x16x32_bf16 v[42:45], v[190:193], v[202:205], v[42:45]
	v_mfma_f32_16x16x32_bf16 v[26:29], v[190:193], v[210:213], v[26:29]
	v_mfma_f32_16x16x32_bf16 v[26:29], v[194:197], v[214:217], v[26:29]
	v_mfma_f32_16x16x32_bf16 v[34:37], v[186:189], v[214:217], v[34:37]
	v_mfma_f32_16x16x32_bf16 v[34:37], v[182:185], v[210:213], v[34:37]
	v_mfma_f32_16x16x32_bf16 v[18:21], v[182:185], v[218:221], v[18:21]
	v_mfma_f32_16x16x32_bf16 v[18:21], v[186:189], v[222:225], v[18:21]
	v_mfma_f32_16x16x32_bf16 v[10:13], v[194:197], v[222:225], v[10:13]
	v_mfma_f32_16x16x32_bf16 v[10:13], v[190:193], v[218:221], v[10:13]
	v_mfma_f32_16x16x32_bf16 v[2:5], v[190:193], v[226:229], v[2:5]
	v_mfma_f32_16x16x32_bf16 v[2:5], v[194:197], v[230:233], v[2:5]
	v_mfma_f32_16x16x32_bf16 v[6:9], v[186:189], v[230:233], v[6:9]
	v_mfma_f32_16x16x32_bf16 v[6:9], v[182:185], v[226:229], v[6:9]
	s_setprio 0
	s_barrier
	s_add_i32 s36, 0, 0x18000
	v_add_u32_e32 v161, s36, v156
	s_add_i32 s37, 0, 0x1c000
	ds_read_b128 v[166:169], v161
	ds_read_b128 v[170:173], v161 offset:1024
	ds_read_b128 v[174:177], v161 offset:2048
	ds_read_b128 v[178:181], v161 offset:3072
	v_add_u32_e32 v161, s37, v156
	ds_read_b128 v[182:185], v161
	ds_read_b128 v[186:189], v161 offset:1024
	ds_read_b128 v[190:193], v161 offset:2048
	ds_read_b128 v[194:197], v161 offset:3072
	s_add_u32 s58, s58, 0x100000
	s_addc_u32 s59, s59, 0
	s_mov_b32 m0, s62
	v_lshl_add_u64 v[240:241], s[58:59], 0, v[138:139]
	ds_read_b128 v[202:205], v160 offset:32768
	ds_read_b128 v[206:209], v160 offset:33792
	ds_read_b128 v[210:213], v160 offset:34816
	ds_read_b128 v[214:217], v160 offset:35840
	ds_read_b128 v[218:221], v160 offset:36864
	ds_read_b128 v[222:225], v160 offset:37888
	ds_read_b128 v[226:229], v160 offset:38912
	ds_read_b128 v[230:233], v160 offset:39936
	global_load_lds_dwordx4 v[240:241], off
	v_lshl_add_u64 v[240:241], s[58:59], 0, v[134:135]
	s_mov_b32 m0, s63
	s_nop 0
	global_load_lds_dwordx4 v[240:241], off
	s_nop 0
	s_waitcnt vmcnt(8)
	s_waitcnt lgkmcnt(0)
	s_barrier
	s_setprio 1
	s_waitcnt lgkmcnt(0)
	v_mfma_f32_16x16x32_bf16 v[126:129], v[166:169], v[202:205], v[126:129]
	v_mfma_f32_16x16x32_bf16 v[126:129], v[170:173], v[206:209], v[126:129]
	v_mfma_f32_16x16x32_bf16 v[122:125], v[178:181], v[206:209], v[122:125]
	v_mfma_f32_16x16x32_bf16 v[122:125], v[174:177], v[202:205], v[122:125]
	v_mfma_f32_16x16x32_bf16 v[110:113], v[174:177], v[210:213], v[110:113]
	v_mfma_f32_16x16x32_bf16 v[110:113], v[178:181], v[214:217], v[110:113]
	v_mfma_f32_16x16x32_bf16 v[118:121], v[170:173], v[214:217], v[118:121]
	v_mfma_f32_16x16x32_bf16 v[118:121], v[166:169], v[210:213], v[118:121]
	v_mfma_f32_16x16x32_bf16 v[102:105], v[166:169], v[218:221], v[102:105]
	v_mfma_f32_16x16x32_bf16 v[102:105], v[170:173], v[222:225], v[102:105]
	v_mfma_f32_16x16x32_bf16 v[94:97], v[178:181], v[222:225], v[94:97]
	v_mfma_f32_16x16x32_bf16 v[94:97], v[174:177], v[218:221], v[94:97]
	v_mfma_f32_16x16x32_bf16 v[78:81], v[174:177], v[226:229], v[78:81]
	v_mfma_f32_16x16x32_bf16 v[78:81], v[178:181], v[230:233], v[78:81]
	v_mfma_f32_16x16x32_bf16 v[86:89], v[170:173], v[230:233], v[86:89]
	v_mfma_f32_16x16x32_bf16 v[86:89], v[166:169], v[226:229], v[86:89]
	s_setprio 0
	s_setprio 1
	v_mfma_f32_16x16x32_bf16 v[114:117], v[182:185], v[202:205], v[114:117]
	v_mfma_f32_16x16x32_bf16 v[114:117], v[186:189], v[206:209], v[114:117]
	v_mfma_f32_16x16x32_bf16 v[106:109], v[194:197], v[206:209], v[106:109]
	v_mfma_f32_16x16x32_bf16 v[106:109], v[190:193], v[202:205], v[106:109]
	v_mfma_f32_16x16x32_bf16 v[90:93], v[190:193], v[210:213], v[90:93]
	v_mfma_f32_16x16x32_bf16 v[90:93], v[194:197], v[214:217], v[90:93]
	v_mfma_f32_16x16x32_bf16 v[98:101], v[186:189], v[214:217], v[98:101]
	v_mfma_f32_16x16x32_bf16 v[98:101], v[182:185], v[210:213], v[98:101]
	v_mfma_f32_16x16x32_bf16 v[82:85], v[182:185], v[218:221], v[82:85]
	v_mfma_f32_16x16x32_bf16 v[82:85], v[186:189], v[222:225], v[82:85]
	v_mfma_f32_16x16x32_bf16 v[74:77], v[194:197], v[222:225], v[74:77]
	v_mfma_f32_16x16x32_bf16 v[74:77], v[190:193], v[218:221], v[74:77]
	v_mfma_f32_16x16x32_bf16 v[66:69], v[190:193], v[226:229], v[66:69]
	v_mfma_f32_16x16x32_bf16 v[66:69], v[194:197], v[230:233], v[66:69]
	v_mfma_f32_16x16x32_bf16 v[70:73], v[186:189], v[230:233], v[70:73]
	v_mfma_f32_16x16x32_bf16 v[70:73], v[182:185], v[226:229], v[70:73]
	s_setprio 0
	s_barrier
	s_add_i32 s36, s36, s38
	v_lshl_add_u64 v[198:199], v[198:199], 0, s[14:15]
	s_mov_b32 m0, s36
	ds_read_b128 v[202:205], v160 offset:49152
	ds_read_b128 v[206:209], v160 offset:50176
	ds_read_b128 v[210:213], v160 offset:51200
	ds_read_b128 v[214:217], v160 offset:52224
	ds_read_b128 v[218:221], v160 offset:53248
	ds_read_b128 v[222:225], v160 offset:54272
	ds_read_b128 v[226:229], v160 offset:55296
	ds_read_b128 v[230:233], v160 offset:56320
	global_load_lds_dwordx4 v[198:199], off
	s_add_i32 m0, s36, 0x2000
	s_add_u32 s56, s56, 0x100080
	v_lshl_add_u64 v[198:199], v[234:235], 0, s[14:15]
	s_addc_u32 s57, s57, 0
	s_add_i32 s36, s37, s38
	global_load_lds_dwordx4 v[198:199], off
	v_lshl_add_u64 v[198:199], s[56:57], 0, v[136:137]
	s_mov_b32 m0, s36
	s_nop 0
	global_load_lds_dwordx4 v[198:199], off
	v_lshl_add_u64 v[198:199], s[56:57], 0, v[132:133]
	s_add_i32 m0, s36, 0x2000
	s_nop 0
	global_load_lds_dwordx4 v[198:199], off
	v_lshl_add_u64 v[198:199], v[236:237], 0, s[14:15]
	s_mov_b32 m0, s65
	s_nop 0
	global_load_lds_dwordx4 v[198:199], off
	v_lshl_add_u64 v[198:199], v[238:239], 0, s[14:15]
	s_mov_b32 m0, s66
	s_nop 0
	global_load_lds_dwordx4 v[198:199], off
	s_waitcnt vmcnt(8)
	s_waitcnt lgkmcnt(0)
	s_barrier
	s_setprio 1
	s_waitcnt lgkmcnt(0)
	v_mfma_f32_16x16x32_bf16 v[62:65], v[166:169], v[202:205], v[62:65]
	v_mfma_f32_16x16x32_bf16 v[62:65], v[170:173], v[206:209], v[62:65]
	v_mfma_f32_16x16x32_bf16 v[58:61], v[178:181], v[206:209], v[58:61]
	v_mfma_f32_16x16x32_bf16 v[58:61], v[174:177], v[202:205], v[58:61]
	v_mfma_f32_16x16x32_bf16 v[46:49], v[174:177], v[210:213], v[46:49]
	v_mfma_f32_16x16x32_bf16 v[46:49], v[178:181], v[214:217], v[46:49]
	v_mfma_f32_16x16x32_bf16 v[54:57], v[170:173], v[214:217], v[54:57]
	v_mfma_f32_16x16x32_bf16 v[54:57], v[166:169], v[210:213], v[54:57]
	v_mfma_f32_16x16x32_bf16 v[38:41], v[166:169], v[218:221], v[38:41]
	v_mfma_f32_16x16x32_bf16 v[38:41], v[170:173], v[222:225], v[38:41]
	v_mfma_f32_16x16x32_bf16 v[30:33], v[178:181], v[222:225], v[30:33]
	v_mfma_f32_16x16x32_bf16 v[30:33], v[174:177], v[218:221], v[30:33]
	v_mfma_f32_16x16x32_bf16 v[14:17], v[174:177], v[226:229], v[14:17]
	v_mfma_f32_16x16x32_bf16 v[14:17], v[178:181], v[230:233], v[14:17]
	v_mfma_f32_16x16x32_bf16 v[22:25], v[170:173], v[230:233], v[22:25]
	v_mfma_f32_16x16x32_bf16 v[22:25], v[166:169], v[226:229], v[22:25]
	s_setprio 0
	s_setprio 1
	v_mfma_f32_16x16x32_bf16 v[50:53], v[182:185], v[202:205], v[50:53]
	v_mfma_f32_16x16x32_bf16 v[50:53], v[186:189], v[206:209], v[50:53]
	v_mfma_f32_16x16x32_bf16 v[42:45], v[194:197], v[206:209], v[42:45]
	v_mfma_f32_16x16x32_bf16 v[42:45], v[190:193], v[202:205], v[42:45]
	v_mfma_f32_16x16x32_bf16 v[26:29], v[190:193], v[210:213], v[26:29]
	v_mfma_f32_16x16x32_bf16 v[26:29], v[194:197], v[214:217], v[26:29]
	v_mfma_f32_16x16x32_bf16 v[34:37], v[186:189], v[214:217], v[34:37]
	v_mfma_f32_16x16x32_bf16 v[34:37], v[182:185], v[210:213], v[34:37]
	v_mfma_f32_16x16x32_bf16 v[18:21], v[182:185], v[218:221], v[18:21]
	v_mfma_f32_16x16x32_bf16 v[18:21], v[186:189], v[222:225], v[18:21]
	v_mfma_f32_16x16x32_bf16 v[10:13], v[194:197], v[222:225], v[10:13]
	v_mfma_f32_16x16x32_bf16 v[10:13], v[190:193], v[218:221], v[10:13]
	v_mfma_f32_16x16x32_bf16 v[2:5], v[190:193], v[226:229], v[2:5]
	v_mfma_f32_16x16x32_bf16 v[2:5], v[194:197], v[230:233], v[2:5]
	v_mfma_f32_16x16x32_bf16 v[6:9], v[186:189], v[230:233], v[6:9]
	v_mfma_f32_16x16x32_bf16 v[6:9], v[182:185], v[226:229], v[6:9]
	s_setprio 0
	s_barrier
	s_add_i32 s78, s78, 2
	s_add_u32 s54, s54, 0x100
	s_addc_u32 s55, s55, 0
	s_add_u32 s76, s76, 0x100
	s_addc_u32 s77, s77, 0
	s_cmp_gt_u32 s78, 61
	s_cbranch_scc0 .LBB0_1631
	s_and_b64 vcc, exec, s[16:17]
	s_cbranch_vccz .LBB0_1634
	s_barrier

.LBB0_1649:
	s_add_u32 s36, s56, s44
	s_addc_u32 s37, s57, 0
	s_add_u32 s64, s36, 0x100
	s_addc_u32 s65, s37, 0
	s_and_b64 s[62:63], s[60:61], exec
	s_cselect_b32 s65, s21, s65
	s_cselect_b32 s64, s87, s64
	s_add_u32 s44, s54, s44
	s_addc_u32 s62, s55, 0
	s_add_u32 s44, s44, 0x100
	s_addc_u32 s62, s62, 0
	s_and_b64 s[60:61], s[60:61], exec
	s_cselect_b32 s67, s19, s62
	s_cselect_b32 s66, s89, s44
	s_add_u32 s70, s36, 0x10080
	s_addc_u32 s71, s37, 0
	s_add_i32 vcc_lo, s84, s39
	ds_read_b128 v[158:161], v147
	ds_read_b128 v[166:169], v147 offset:1024
	ds_read_b128 v[170:173], v147 offset:2048
	ds_read_b128 v[174:177], v147 offset:3072
	ds_read_b128 v[178:181], v155
	ds_read_b128 v[182:185], v155 offset:1024
	ds_read_b128 v[186:189], v155 offset:2048
	ds_read_b128 v[190:193], v155 offset:3072
	s_add_i32 m0, s53, 0xc000
	s_add_i32 vcc_hi, s53, 0xe000
	s_add_i32 s95, vcc_lo, 0x2000
	s_add_u32 s68, s66, 0x10000
	s_addc_u32 s69, s67, 0
	s_add_i32 s97, s85, s39
	s_add_i32 s96, s97, 0x2000
	s_add_i32 s94, 0, 0x18000
	s_add_i32 s93, 0, 0x1c000
	s_add_u32 s62, s64, 0x10000
	s_addc_u32 s63, s65, 0
	s_add_i32 s92, s94, s39
	s_add_i32 s90, s92, 0x2000
	s_add_u32 s60, s66, 0x10080
	s_addc_u32 s61, s67, 0
	s_add_i32 s91, s93, s39
	s_add_i32 s44, s91, 0x2000
	v_lshl_add_u64 v[198:199], s[70:71], 0, v[138:139]
	ds_read_b128 v[194:197], v156
	ds_read_b128 v[202:205], v156 offset:1024
	ds_read_b128 v[206:209], v156 offset:2048
	ds_read_b128 v[210:213], v156 offset:3072
	ds_read_b128 v[214:217], v156 offset:4096
	ds_read_b128 v[218:221], v156 offset:5120
	ds_read_b128 v[222:225], v156 offset:6144
	ds_read_b128 v[226:229], v156 offset:7168
	global_load_lds_dwordx4 v[198:199], off
	v_lshl_add_u64 v[198:199], s[70:71], 0, v[134:135]
	s_mov_b32 m0, vcc_hi
	s_nop 0
	global_load_lds_dwordx4 v[198:199], off
	s_nop 0
	s_waitcnt vmcnt(8)
	s_waitcnt lgkmcnt(0)
	s_barrier
	s_setprio 1
	s_waitcnt lgkmcnt(0)
	v_mfma_f32_16x16x32_bf16 v[126:129], v[158:161], v[194:197], v[126:129]
	v_mfma_f32_16x16x32_bf16 v[126:129], v[166:169], v[202:205], v[126:129]
	v_mfma_f32_16x16x32_bf16 v[122:125], v[174:177], v[202:205], v[122:125]
	v_mfma_f32_16x16x32_bf16 v[122:125], v[170:173], v[194:197], v[122:125]
	v_mfma_f32_16x16x32_bf16 v[110:113], v[170:173], v[206:209], v[110:113]
	v_mfma_f32_16x16x32_bf16 v[110:113], v[174:177], v[210:213], v[110:113]
	v_mfma_f32_16x16x32_bf16 v[118:121], v[166:169], v[210:213], v[118:121]
	v_mfma_f32_16x16x32_bf16 v[118:121], v[158:161], v[206:209], v[118:121]
	v_mfma_f32_16x16x32_bf16 v[102:105], v[158:161], v[214:217], v[102:105]
	v_mfma_f32_16x16x32_bf16 v[102:105], v[166:169], v[218:221], v[102:105]
	v_mfma_f32_16x16x32_bf16 v[94:97], v[174:177], v[218:221], v[94:97]
	v_mfma_f32_16x16x32_bf16 v[94:97], v[170:173], v[214:217], v[94:97]
	v_mfma_f32_16x16x32_bf16 v[78:81], v[170:173], v[222:225], v[78:81]
	v_mfma_f32_16x16x32_bf16 v[78:81], v[174:177], v[226:229], v[78:81]
	v_mfma_f32_16x16x32_bf16 v[86:89], v[166:169], v[226:229], v[86:89]
	v_mfma_f32_16x16x32_bf16 v[86:89], v[158:161], v[222:225], v[86:89]
	s_setprio 0
	s_setprio 1
	v_mfma_f32_16x16x32_bf16 v[114:117], v[178:181], v[194:197], v[114:117]
	v_mfma_f32_16x16x32_bf16 v[114:117], v[182:185], v[202:205], v[114:117]
	v_mfma_f32_16x16x32_bf16 v[106:109], v[190:193], v[202:205], v[106:109]
	v_mfma_f32_16x16x32_bf16 v[106:109], v[186:189], v[194:197], v[106:109]
	v_mfma_f32_16x16x32_bf16 v[90:93], v[186:189], v[206:209], v[90:93]
	v_mfma_f32_16x16x32_bf16 v[90:93], v[190:193], v[210:213], v[90:93]
	v_mfma_f32_16x16x32_bf16 v[98:101], v[182:185], v[210:213], v[98:101]
	v_mfma_f32_16x16x32_bf16 v[98:101], v[178:181], v[206:209], v[98:101]
	v_mfma_f32_16x16x32_bf16 v[82:85], v[178:181], v[214:217], v[82:85]
	v_mfma_f32_16x16x32_bf16 v[82:85], v[182:185], v[218:221], v[82:85]
	v_mfma_f32_16x16x32_bf16 v[74:77], v[190:193], v[218:221], v[74:77]
	v_mfma_f32_16x16x32_bf16 v[74:77], v[186:189], v[214:217], v[74:77]
	v_mfma_f32_16x16x32_bf16 v[66:69], v[186:189], v[222:225], v[66:69]
	v_mfma_f32_16x16x32_bf16 v[66:69], v[190:193], v[226:229], v[66:69]
	v_mfma_f32_16x16x32_bf16 v[70:73], v[182:185], v[226:229], v[70:73]
	v_mfma_f32_16x16x32_bf16 v[70:73], v[178:181], v[222:225], v[70:73]
	s_setprio 0
	s_barrier
	s_mov_b32 m0, vcc_lo
	v_lshl_add_u64 v[198:199], s[66:67], 0, v[136:137]
	ds_read_b128 v[194:197], v156 offset:16384
	ds_read_b128 v[202:205], v156 offset:17408
	ds_read_b128 v[206:209], v156 offset:18432
	ds_read_b128 v[210:213], v156 offset:19456
	ds_read_b128 v[214:217], v156 offset:20480
	ds_read_b128 v[218:221], v156 offset:21504
	ds_read_b128 v[222:225], v156 offset:22528
	ds_read_b128 v[226:229], v156 offset:23552
	global_load_lds_dwordx4 v[198:199], off
	v_lshl_add_u64 v[230:231], s[66:67], 0, v[132:133]
	s_mov_b32 m0, s95
	v_lshl_add_u64 v[232:233], s[68:69], 0, v[136:137]
	global_load_lds_dwordx4 v[230:231], off
	s_mov_b32 m0, s97
	v_lshl_add_u64 v[234:235], s[64:65], 0, v[134:135]
	global_load_lds_dwordx4 v[232:233], off
	v_lshl_add_u64 v[232:233], s[68:69], 0, v[132:133]
	s_mov_b32 m0, s96
	s_nop 0
	global_load_lds_dwordx4 v[232:233], off
	v_lshl_add_u64 v[232:233], s[64:65], 0, v[138:139]
	s_mov_b32 m0, s53
	s_nop 0
	global_load_lds_dwordx4 v[232:233], off
	s_mov_b32 m0, s75
	s_nop 0
	global_load_lds_dwordx4 v[234:235], off
	s_waitcnt vmcnt(8)
	s_waitcnt lgkmcnt(0)
	s_barrier
	s_setprio 1
	s_waitcnt lgkmcnt(0)
	v_mfma_f32_16x16x32_bf16 v[62:65], v[158:161], v[194:197], v[62:65]
	v_mfma_f32_16x16x32_bf16 v[62:65], v[166:169], v[202:205], v[62:65]
	v_mfma_f32_16x16x32_bf16 v[58:61], v[174:177], v[202:205], v[58:61]
	v_mfma_f32_16x16x32_bf16 v[58:61], v[170:173], v[194:197], v[58:61]
	v_mfma_f32_16x16x32_bf16 v[46:49], v[170:173], v[206:209], v[46:49]
	v_mfma_f32_16x16x32_bf16 v[46:49], v[174:177], v[210:213], v[46:49]
	v_mfma_f32_16x16x32_bf16 v[54:57], v[166:169], v[210:213], v[54:57]
	v_mfma_f32_16x16x32_bf16 v[54:57], v[158:161], v[206:209], v[54:57]
	v_mfma_f32_16x16x32_bf16 v[38:41], v[158:161], v[214:217], v[38:41]
	v_mfma_f32_16x16x32_bf16 v[38:41], v[166:169], v[218:221], v[38:41]
	v_mfma_f32_16x16x32_bf16 v[30:33], v[174:177], v[218:221], v[30:33]
	v_mfma_f32_16x16x32_bf16 v[30:33], v[170:173], v[214:217], v[30:33]
	v_mfma_f32_16x16x32_bf16 v[14:17], v[170:173], v[222:225], v[14:17]
	v_mfma_f32_16x16x32_bf16 v[14:17], v[174:177], v[226:229], v[14:17]
	v_mfma_f32_16x16x32_bf16 v[22:25], v[166:169], v[226:229], v[22:25]
	v_mfma_f32_16x16x32_bf16 v[22:25], v[158:161], v[222:225], v[22:25]
	s_setprio 0
	s_setprio 1
	v_mfma_f32_16x16x32_bf16 v[50:53], v[178:181], v[194:197], v[50:53]
	v_mfma_f32_16x16x32_bf16 v[50:53], v[182:185], v[202:205], v[50:53]
	v_mfma_f32_16x16x32_bf16 v[42:45], v[190:193], v[202:205], v[42:45]
	v_mfma_f32_16x16x32_bf16 v[42:45], v[186:189], v[194:197], v[42:45]
	v_mfma_f32_16x16x32_bf16 v[26:29], v[186:189], v[206:209], v[26:29]
	v_mfma_f32_16x16x32_bf16 v[26:29], v[190:193], v[210:213], v[26:29]
	v_mfma_f32_16x16x32_bf16 v[34:37], v[182:185], v[210:213], v[34:37]
	v_mfma_f32_16x16x32_bf16 v[34:37], v[178:181], v[206:209], v[34:37]
	v_mfma_f32_16x16x32_bf16 v[18:21], v[178:181], v[214:217], v[18:21]
	v_mfma_f32_16x16x32_bf16 v[18:21], v[182:185], v[218:221], v[18:21]
	v_mfma_f32_16x16x32_bf16 v[10:13], v[190:193], v[218:221], v[10:13]
	v_mfma_f32_16x16x32_bf16 v[10:13], v[186:189], v[214:217], v[10:13]
	v_mfma_f32_16x16x32_bf16 v[2:5], v[186:189], v[222:225], v[2:5]
	v_mfma_f32_16x16x32_bf16 v[2:5], v[190:193], v[226:229], v[2:5]
	v_mfma_f32_16x16x32_bf16 v[6:9], v[182:185], v[226:229], v[6:9]
	v_mfma_f32_16x16x32_bf16 v[6:9], v[178:181], v[222:225], v[6:9]
	s_setprio 0
	s_barrier
	v_add_u32_e32 v157, s94, v145
	ds_read_b128 v[158:161], v157
	ds_read_b128 v[166:169], v157 offset:1024
	ds_read_b128 v[170:173], v157 offset:2048
	ds_read_b128 v[174:177], v157 offset:3072
	v_add_u32_e32 v157, s93, v145
	ds_read_b128 v[178:181], v157
	ds_read_b128 v[182:185], v157 offset:1024
	ds_read_b128 v[186:189], v157 offset:2048
	ds_read_b128 v[190:193], v157 offset:3072
	s_mov_b32 m0, s76
	v_lshl_add_u64 v[236:237], s[62:63], 0, v[138:139]
	ds_read_b128 v[194:197], v156 offset:32768
	ds_read_b128 v[202:205], v156 offset:33792
	ds_read_b128 v[206:209], v156 offset:34816
	ds_read_b128 v[210:213], v156 offset:35840
	ds_read_b128 v[214:217], v156 offset:36864
	ds_read_b128 v[218:221], v156 offset:37888
	ds_read_b128 v[222:225], v156 offset:38912
	ds_read_b128 v[226:229], v156 offset:39936
	global_load_lds_dwordx4 v[236:237], off
	v_lshl_add_u64 v[236:237], s[62:63], 0, v[134:135]
	s_mov_b32 m0, s77
	s_nop 0
	global_load_lds_dwordx4 v[236:237], off
	s_waitcnt vmcnt(8)
	s_waitcnt lgkmcnt(0)
	s_barrier
	s_setprio 1
	s_waitcnt lgkmcnt(0)
	v_mfma_f32_16x16x32_bf16 v[126:129], v[158:161], v[194:197], v[126:129]
	v_mfma_f32_16x16x32_bf16 v[126:129], v[166:169], v[202:205], v[126:129]
	v_mfma_f32_16x16x32_bf16 v[122:125], v[174:177], v[202:205], v[122:125]
	v_mfma_f32_16x16x32_bf16 v[122:125], v[170:173], v[194:197], v[122:125]
	v_mfma_f32_16x16x32_bf16 v[110:113], v[170:173], v[206:209], v[110:113]
	v_mfma_f32_16x16x32_bf16 v[110:113], v[174:177], v[210:213], v[110:113]
	v_mfma_f32_16x16x32_bf16 v[118:121], v[166:169], v[210:213], v[118:121]
	v_mfma_f32_16x16x32_bf16 v[118:121], v[158:161], v[206:209], v[118:121]
	v_mfma_f32_16x16x32_bf16 v[102:105], v[158:161], v[214:217], v[102:105]
	v_mfma_f32_16x16x32_bf16 v[102:105], v[166:169], v[218:221], v[102:105]
	v_mfma_f32_16x16x32_bf16 v[94:97], v[174:177], v[218:221], v[94:97]
	v_mfma_f32_16x16x32_bf16 v[94:97], v[170:173], v[214:217], v[94:97]
	v_mfma_f32_16x16x32_bf16 v[78:81], v[170:173], v[222:225], v[78:81]
	v_mfma_f32_16x16x32_bf16 v[78:81], v[174:177], v[226:229], v[78:81]
	v_mfma_f32_16x16x32_bf16 v[86:89], v[166:169], v[226:229], v[86:89]
	v_mfma_f32_16x16x32_bf16 v[86:89], v[158:161], v[222:225], v[86:89]
	s_setprio 0
	s_setprio 1
	v_mfma_f32_16x16x32_bf16 v[114:117], v[178:181], v[194:197], v[114:117]
	v_mfma_f32_16x16x32_bf16 v[114:117], v[182:185], v[202:205], v[114:117]
	v_mfma_f32_16x16x32_bf16 v[106:109], v[190:193], v[202:205], v[106:109]
	v_mfma_f32_16x16x32_bf16 v[106:109], v[186:189], v[194:197], v[106:109]
	v_mfma_f32_16x16x32_bf16 v[90:93], v[186:189], v[206:209], v[90:93]
	v_mfma_f32_16x16x32_bf16 v[90:93], v[190:193], v[210:213], v[90:93]
	v_mfma_f32_16x16x32_bf16 v[98:101], v[182:185], v[210:213], v[98:101]
	v_mfma_f32_16x16x32_bf16 v[98:101], v[178:181], v[206:209], v[98:101]
	v_mfma_f32_16x16x32_bf16 v[82:85], v[178:181], v[214:217], v[82:85]
	v_mfma_f32_16x16x32_bf16 v[82:85], v[182:185], v[218:221], v[82:85]
	v_mfma_f32_16x16x32_bf16 v[74:77], v[190:193], v[218:221], v[74:77]
	v_mfma_f32_16x16x32_bf16 v[74:77], v[186:189], v[214:217], v[74:77]
	v_mfma_f32_16x16x32_bf16 v[66:69], v[186:189], v[222:225], v[66:69]
	v_mfma_f32_16x16x32_bf16 v[66:69], v[190:193], v[226:229], v[66:69]
	v_mfma_f32_16x16x32_bf16 v[70:73], v[182:185], v[226:229], v[70:73]
	v_mfma_f32_16x16x32_bf16 v[70:73], v[178:181], v[222:225], v[70:73]
	s_setprio 0
	s_barrier
	s_mov_b32 m0, s92
	v_lshl_add_u64 v[198:199], v[198:199], 0, s[14:15]
	ds_read_b128 v[194:197], v156 offset:49152
	ds_read_b128 v[202:205], v156 offset:50176
	ds_read_b128 v[206:209], v156 offset:51200
	ds_read_b128 v[210:213], v156 offset:52224
	ds_read_b128 v[214:217], v156 offset:53248
	ds_read_b128 v[218:221], v156 offset:54272
	ds_read_b128 v[222:225], v156 offset:55296
	ds_read_b128 v[226:229], v156 offset:56320
	global_load_lds_dwordx4 v[198:199], off
	v_lshl_add_u64 v[198:199], v[230:231], 0, s[14:15]
	s_mov_b32 m0, s90
	s_nop 0
	global_load_lds_dwordx4 v[198:199], off
	v_lshl_add_u64 v[198:199], s[60:61], 0, v[136:137]
	s_mov_b32 m0, s91
	s_nop 0
	global_load_lds_dwordx4 v[198:199], off
	v_lshl_add_u64 v[198:199], s[60:61], 0, v[132:133]
	s_mov_b32 m0, s44
	s_nop 0
	global_load_lds_dwordx4 v[198:199], off
	v_lshl_add_u64 v[198:199], v[232:233], 0, s[14:15]
	s_mov_b32 m0, s80
	s_nop 0
	global_load_lds_dwordx4 v[198:199], off
	v_lshl_add_u64 v[198:199], v[234:235], 0, s[14:15]
	s_mov_b32 m0, s81
	s_nop 0
	global_load_lds_dwordx4 v[198:199], off
	s_waitcnt vmcnt(8)
	s_waitcnt lgkmcnt(0)
	s_barrier
	s_setprio 1
	s_waitcnt lgkmcnt(0)
	v_mfma_f32_16x16x32_bf16 v[62:65], v[158:161], v[194:197], v[62:65]
	v_mfma_f32_16x16x32_bf16 v[62:65], v[166:169], v[202:205], v[62:65]
	v_mfma_f32_16x16x32_bf16 v[58:61], v[174:177], v[202:205], v[58:61]
	v_mfma_f32_16x16x32_bf16 v[58:61], v[170:173], v[194:197], v[58:61]
	v_mfma_f32_16x16x32_bf16 v[46:49], v[170:173], v[206:209], v[46:49]
	v_mfma_f32_16x16x32_bf16 v[46:49], v[174:177], v[210:213], v[46:49]
	v_mfma_f32_16x16x32_bf16 v[54:57], v[166:169], v[210:213], v[54:57]
	v_mfma_f32_16x16x32_bf16 v[54:57], v[158:161], v[206:209], v[54:57]
	v_mfma_f32_16x16x32_bf16 v[38:41], v[158:161], v[214:217], v[38:41]
	v_mfma_f32_16x16x32_bf16 v[38:41], v[166:169], v[218:221], v[38:41]
	v_mfma_f32_16x16x32_bf16 v[30:33], v[174:177], v[218:221], v[30:33]
	v_mfma_f32_16x16x32_bf16 v[30:33], v[170:173], v[214:217], v[30:33]
	v_mfma_f32_16x16x32_bf16 v[14:17], v[170:173], v[222:225], v[14:17]
	v_mfma_f32_16x16x32_bf16 v[14:17], v[174:177], v[226:229], v[14:17]
	v_mfma_f32_16x16x32_bf16 v[22:25], v[166:169], v[226:229], v[22:25]
	v_mfma_f32_16x16x32_bf16 v[22:25], v[158:161], v[222:225], v[22:25]
	s_setprio 0
	s_setprio 1
	v_mfma_f32_16x16x32_bf16 v[50:53], v[178:181], v[194:197], v[50:53]
	v_mfma_f32_16x16x32_bf16 v[50:53], v[182:185], v[202:205], v[50:53]
	v_mfma_f32_16x16x32_bf16 v[42:45], v[190:193], v[202:205], v[42:45]
	v_mfma_f32_16x16x32_bf16 v[42:45], v[186:189], v[194:197], v[42:45]
	v_mfma_f32_16x16x32_bf16 v[26:29], v[186:189], v[206:209], v[26:29]
	v_mfma_f32_16x16x32_bf16 v[26:29], v[190:193], v[210:213], v[26:29]
	v_mfma_f32_16x16x32_bf16 v[34:37], v[182:185], v[210:213], v[34:37]
	v_mfma_f32_16x16x32_bf16 v[34:37], v[178:181], v[206:209], v[34:37]
	v_mfma_f32_16x16x32_bf16 v[18:21], v[178:181], v[214:217], v[18:21]
	v_mfma_f32_16x16x32_bf16 v[18:21], v[182:185], v[218:221], v[18:21]
	v_mfma_f32_16x16x32_bf16 v[10:13], v[190:193], v[218:221], v[10:13]
	v_mfma_f32_16x16x32_bf16 v[10:13], v[186:189], v[214:217], v[10:13]
	v_mfma_f32_16x16x32_bf16 v[2:5], v[186:189], v[222:225], v[2:5]
	v_mfma_f32_16x16x32_bf16 v[2:5], v[190:193], v[226:229], v[2:5]
	v_mfma_f32_16x16x32_bf16 v[6:9], v[182:185], v[226:229], v[6:9]
	v_mfma_f32_16x16x32_bf16 v[6:9], v[178:181], v[222:225], v[6:9]
	s_setprio 0
	s_barrier
	s_movk_i32 s44, 0x100
	s_andn2_b64 vcc, exec, s[58:59]
	s_mov_b64 s[60:61], -1
	s_mov_b64 s[58:59], 0
	s_cbranch_vccz .LBB0_1649
	s_and_b64 vcc, exec, s[16:17]
	s_cbranch_vccz .LBB0_1652
	s_barrier

.LBB0_1667:
	s_add_u32 s36, s56, s44
	s_addc_u32 s37, s57, 0
	s_add_u32 s64, s36, 0x100
	s_addc_u32 s65, s37, 0
	s_and_b64 s[62:63], s[60:61], exec
	s_cselect_b32 s65, s21, s65
	s_cselect_b32 s64, s86, s64
	s_add_u32 s44, s54, s44
	s_addc_u32 s62, s55, 0
	s_add_u32 s44, s44, 0x100
	s_addc_u32 s62, s62, 0
	s_and_b64 s[60:61], s[60:61], exec
	s_cselect_b32 s67, s19, s62
	s_cselect_b32 s66, s87, s44
	s_add_u32 s70, s36, 0x10080
	s_addc_u32 s71, s37, 0
	s_add_i32 s97, s82, s38
	ds_read_b128 v[150:153], v146
	ds_read_b128 v[154:157], v146 offset:1024
	ds_read_b128 v[158:161], v146 offset:2048
	ds_read_b128 v[166:169], v146 offset:3072
	ds_read_b128 v[170:173], v147
	ds_read_b128 v[174:177], v147 offset:1024
	ds_read_b128 v[178:181], v147 offset:2048
	ds_read_b128 v[182:185], v147 offset:3072
	s_add_i32 m0, s53, 0xc000
	s_add_i32 vcc_lo, s53, 0xe000
	s_add_i32 s94, s97, 0x2000
	s_add_u32 s68, s66, 0x10000
	s_addc_u32 s69, s67, 0
	s_add_i32 s96, s83, s38
	s_add_i32 s95, s96, 0x2000
	s_add_i32 s93, 0, 0x18000
	s_add_i32 s92, 0, 0x1c000
	s_add_u32 s62, s64, 0x10000
	s_addc_u32 s63, s65, 0
	s_add_i32 s91, s93, s38
	s_add_i32 s89, s91, 0x2000
	s_add_u32 s60, s66, 0x10080
	s_addc_u32 s61, s67, 0
	s_add_i32 s90, s92, s38
	s_add_i32 s44, s90, 0x2000
	v_lshl_add_u64 v[198:199], s[70:71], 0, v[138:139]
	ds_read_b128 v[186:189], v148
	ds_read_b128 v[190:193], v148 offset:1024
	ds_read_b128 v[194:197], v148 offset:2048
	ds_read_b128 v[202:205], v148 offset:3072
	ds_read_b128 v[206:209], v148 offset:4096
	ds_read_b128 v[210:213], v148 offset:5120
	ds_read_b128 v[214:217], v148 offset:6144
	ds_read_b128 v[218:221], v148 offset:7168
	global_load_lds_dwordx4 v[198:199], off
	v_lshl_add_u64 v[198:199], s[70:71], 0, v[134:135]
	s_mov_b32 m0, vcc_lo
	s_nop 0
	global_load_lds_dwordx4 v[198:199], off
	s_nop 0
	s_waitcnt vmcnt(8)
	s_waitcnt lgkmcnt(0)
	s_barrier
	s_setprio 1
	s_waitcnt lgkmcnt(0)
	v_mfma_f32_16x16x32_bf16 v[126:129], v[150:153], v[186:189], v[126:129]
	v_mfma_f32_16x16x32_bf16 v[126:129], v[154:157], v[190:193], v[126:129]
	v_mfma_f32_16x16x32_bf16 v[122:125], v[166:169], v[190:193], v[122:125]
	v_mfma_f32_16x16x32_bf16 v[122:125], v[158:161], v[186:189], v[122:125]
	v_mfma_f32_16x16x32_bf16 v[110:113], v[158:161], v[194:197], v[110:113]
	v_mfma_f32_16x16x32_bf16 v[110:113], v[166:169], v[202:205], v[110:113]
	v_mfma_f32_16x16x32_bf16 v[118:121], v[154:157], v[202:205], v[118:121]
	v_mfma_f32_16x16x32_bf16 v[118:121], v[150:153], v[194:197], v[118:121]
	v_mfma_f32_16x16x32_bf16 v[102:105], v[150:153], v[206:209], v[102:105]
	v_mfma_f32_16x16x32_bf16 v[102:105], v[154:157], v[210:213], v[102:105]
	v_mfma_f32_16x16x32_bf16 v[94:97], v[166:169], v[210:213], v[94:97]
	v_mfma_f32_16x16x32_bf16 v[94:97], v[158:161], v[206:209], v[94:97]
	v_mfma_f32_16x16x32_bf16 v[78:81], v[158:161], v[214:217], v[78:81]
	v_mfma_f32_16x16x32_bf16 v[78:81], v[166:169], v[218:221], v[78:81]
	v_mfma_f32_16x16x32_bf16 v[86:89], v[154:157], v[218:221], v[86:89]
	v_mfma_f32_16x16x32_bf16 v[86:89], v[150:153], v[214:217], v[86:89]
	s_setprio 0
	s_setprio 1
	v_mfma_f32_16x16x32_bf16 v[114:117], v[170:173], v[186:189], v[114:117]
	v_mfma_f32_16x16x32_bf16 v[114:117], v[174:177], v[190:193], v[114:117]
	v_mfma_f32_16x16x32_bf16 v[106:109], v[182:185], v[190:193], v[106:109]
	v_mfma_f32_16x16x32_bf16 v[106:109], v[178:181], v[186:189], v[106:109]
	v_mfma_f32_16x16x32_bf16 v[90:93], v[178:181], v[194:197], v[90:93]
	v_mfma_f32_16x16x32_bf16 v[90:93], v[182:185], v[202:205], v[90:93]
	v_mfma_f32_16x16x32_bf16 v[98:101], v[174:177], v[202:205], v[98:101]
	v_mfma_f32_16x16x32_bf16 v[98:101], v[170:173], v[194:197], v[98:101]
	v_mfma_f32_16x16x32_bf16 v[82:85], v[170:173], v[206:209], v[82:85]
	v_mfma_f32_16x16x32_bf16 v[82:85], v[174:177], v[210:213], v[82:85]
	v_mfma_f32_16x16x32_bf16 v[74:77], v[182:185], v[210:213], v[74:77]
	v_mfma_f32_16x16x32_bf16 v[74:77], v[178:181], v[206:209], v[74:77]
	v_mfma_f32_16x16x32_bf16 v[66:69], v[178:181], v[214:217], v[66:69]
	v_mfma_f32_16x16x32_bf16 v[66:69], v[182:185], v[218:221], v[66:69]
	v_mfma_f32_16x16x32_bf16 v[70:73], v[174:177], v[218:221], v[70:73]
	v_mfma_f32_16x16x32_bf16 v[70:73], v[170:173], v[214:217], v[70:73]
	s_setprio 0
	s_barrier
	s_mov_b32 m0, s97
	v_lshl_add_u64 v[198:199], s[66:67], 0, v[136:137]
	ds_read_b128 v[186:189], v148 offset:16384
	ds_read_b128 v[190:193], v148 offset:17408
	ds_read_b128 v[194:197], v148 offset:18432
	ds_read_b128 v[202:205], v148 offset:19456
	ds_read_b128 v[206:209], v148 offset:20480
	ds_read_b128 v[210:213], v148 offset:21504
	ds_read_b128 v[214:217], v148 offset:22528
	ds_read_b128 v[218:221], v148 offset:23552
	global_load_lds_dwordx4 v[198:199], off
	v_lshl_add_u64 v[222:223], s[66:67], 0, v[132:133]
	s_mov_b32 m0, s94
	v_lshl_add_u64 v[224:225], s[68:69], 0, v[136:137]
	global_load_lds_dwordx4 v[222:223], off
	s_mov_b32 m0, s96
	v_lshl_add_u64 v[226:227], s[64:65], 0, v[134:135]
	global_load_lds_dwordx4 v[224:225], off
	v_lshl_add_u64 v[224:225], s[68:69], 0, v[132:133]
	s_mov_b32 m0, s95
	s_nop 0
	global_load_lds_dwordx4 v[224:225], off
	v_lshl_add_u64 v[224:225], s[64:65], 0, v[138:139]
	s_mov_b32 m0, s53
	s_nop 0
	global_load_lds_dwordx4 v[224:225], off
	s_mov_b32 m0, s75
	s_nop 0
	global_load_lds_dwordx4 v[226:227], off
	s_waitcnt vmcnt(8)
	s_waitcnt lgkmcnt(0)
	s_barrier
	s_setprio 1
	s_waitcnt lgkmcnt(0)
	v_mfma_f32_16x16x32_bf16 v[62:65], v[150:153], v[186:189], v[62:65]
	v_mfma_f32_16x16x32_bf16 v[62:65], v[154:157], v[190:193], v[62:65]
	v_mfma_f32_16x16x32_bf16 v[58:61], v[166:169], v[190:193], v[58:61]
	v_mfma_f32_16x16x32_bf16 v[58:61], v[158:161], v[186:189], v[58:61]
	v_mfma_f32_16x16x32_bf16 v[46:49], v[158:161], v[194:197], v[46:49]
	v_mfma_f32_16x16x32_bf16 v[46:49], v[166:169], v[202:205], v[46:49]
	v_mfma_f32_16x16x32_bf16 v[54:57], v[154:157], v[202:205], v[54:57]
	v_mfma_f32_16x16x32_bf16 v[54:57], v[150:153], v[194:197], v[54:57]
	v_mfma_f32_16x16x32_bf16 v[38:41], v[150:153], v[206:209], v[38:41]
	v_mfma_f32_16x16x32_bf16 v[38:41], v[154:157], v[210:213], v[38:41]
	v_mfma_f32_16x16x32_bf16 v[30:33], v[166:169], v[210:213], v[30:33]
	v_mfma_f32_16x16x32_bf16 v[30:33], v[158:161], v[206:209], v[30:33]
	v_mfma_f32_16x16x32_bf16 v[14:17], v[158:161], v[214:217], v[14:17]
	v_mfma_f32_16x16x32_bf16 v[14:17], v[166:169], v[218:221], v[14:17]
	v_mfma_f32_16x16x32_bf16 v[22:25], v[154:157], v[218:221], v[22:25]
	v_mfma_f32_16x16x32_bf16 v[22:25], v[150:153], v[214:217], v[22:25]
	s_setprio 0
	s_setprio 1
	v_mfma_f32_16x16x32_bf16 v[50:53], v[170:173], v[186:189], v[50:53]
	v_mfma_f32_16x16x32_bf16 v[50:53], v[174:177], v[190:193], v[50:53]
	v_mfma_f32_16x16x32_bf16 v[42:45], v[182:185], v[190:193], v[42:45]
	v_mfma_f32_16x16x32_bf16 v[42:45], v[178:181], v[186:189], v[42:45]
	v_mfma_f32_16x16x32_bf16 v[26:29], v[178:181], v[194:197], v[26:29]
	v_mfma_f32_16x16x32_bf16 v[26:29], v[182:185], v[202:205], v[26:29]
	v_mfma_f32_16x16x32_bf16 v[34:37], v[174:177], v[202:205], v[34:37]
	v_mfma_f32_16x16x32_bf16 v[34:37], v[170:173], v[194:197], v[34:37]
	v_mfma_f32_16x16x32_bf16 v[18:21], v[170:173], v[206:209], v[18:21]
	v_mfma_f32_16x16x32_bf16 v[18:21], v[174:177], v[210:213], v[18:21]
	v_mfma_f32_16x16x32_bf16 v[10:13], v[182:185], v[210:213], v[10:13]
	v_mfma_f32_16x16x32_bf16 v[10:13], v[178:181], v[206:209], v[10:13]
	v_mfma_f32_16x16x32_bf16 v[2:5], v[178:181], v[214:217], v[2:5]
	v_mfma_f32_16x16x32_bf16 v[2:5], v[182:185], v[218:221], v[2:5]
	v_mfma_f32_16x16x32_bf16 v[6:9], v[174:177], v[218:221], v[6:9]
	v_mfma_f32_16x16x32_bf16 v[6:9], v[170:173], v[214:217], v[6:9]
	s_setprio 0
	s_barrier
	v_add_u32_e32 v149, s93, v145
	ds_read_b128 v[150:153], v149
	ds_read_b128 v[154:157], v149 offset:1024
	ds_read_b128 v[158:161], v149 offset:2048
	ds_read_b128 v[166:169], v149 offset:3072
	v_add_u32_e32 v149, s92, v145
	ds_read_b128 v[170:173], v149
	ds_read_b128 v[174:177], v149 offset:1024
	ds_read_b128 v[178:181], v149 offset:2048
	ds_read_b128 v[182:185], v149 offset:3072
	s_mov_b32 m0, s76
	v_lshl_add_u64 v[228:229], s[62:63], 0, v[138:139]
	ds_read_b128 v[186:189], v148 offset:32768
	ds_read_b128 v[190:193], v148 offset:33792
	ds_read_b128 v[194:197], v148 offset:34816
	ds_read_b128 v[202:205], v148 offset:35840
	ds_read_b128 v[206:209], v148 offset:36864
	ds_read_b128 v[210:213], v148 offset:37888
	ds_read_b128 v[214:217], v148 offset:38912
	ds_read_b128 v[218:221], v148 offset:39936
	global_load_lds_dwordx4 v[228:229], off
	v_lshl_add_u64 v[228:229], s[62:63], 0, v[134:135]
	s_mov_b32 m0, s77
	s_nop 0
	global_load_lds_dwordx4 v[228:229], off
	s_waitcnt vmcnt(8)
	s_waitcnt lgkmcnt(0)
	s_barrier
	s_setprio 1
	s_waitcnt lgkmcnt(0)
	v_mfma_f32_16x16x32_bf16 v[126:129], v[150:153], v[186:189], v[126:129]
	v_mfma_f32_16x16x32_bf16 v[126:129], v[154:157], v[190:193], v[126:129]
	v_mfma_f32_16x16x32_bf16 v[122:125], v[166:169], v[190:193], v[122:125]
	v_mfma_f32_16x16x32_bf16 v[122:125], v[158:161], v[186:189], v[122:125]
	v_mfma_f32_16x16x32_bf16 v[110:113], v[158:161], v[194:197], v[110:113]
	v_mfma_f32_16x16x32_bf16 v[110:113], v[166:169], v[202:205], v[110:113]
	v_mfma_f32_16x16x32_bf16 v[118:121], v[154:157], v[202:205], v[118:121]
	v_mfma_f32_16x16x32_bf16 v[118:121], v[150:153], v[194:197], v[118:121]
	v_mfma_f32_16x16x32_bf16 v[102:105], v[150:153], v[206:209], v[102:105]
	v_mfma_f32_16x16x32_bf16 v[102:105], v[154:157], v[210:213], v[102:105]
	v_mfma_f32_16x16x32_bf16 v[94:97], v[166:169], v[210:213], v[94:97]
	v_mfma_f32_16x16x32_bf16 v[94:97], v[158:161], v[206:209], v[94:97]
	v_mfma_f32_16x16x32_bf16 v[78:81], v[158:161], v[214:217], v[78:81]
	v_mfma_f32_16x16x32_bf16 v[78:81], v[166:169], v[218:221], v[78:81]
	v_mfma_f32_16x16x32_bf16 v[86:89], v[154:157], v[218:221], v[86:89]
	v_mfma_f32_16x16x32_bf16 v[86:89], v[150:153], v[214:217], v[86:89]
	s_setprio 0
	s_setprio 1
	v_mfma_f32_16x16x32_bf16 v[114:117], v[170:173], v[186:189], v[114:117]
	v_mfma_f32_16x16x32_bf16 v[114:117], v[174:177], v[190:193], v[114:117]
	v_mfma_f32_16x16x32_bf16 v[106:109], v[182:185], v[190:193], v[106:109]
	v_mfma_f32_16x16x32_bf16 v[106:109], v[178:181], v[186:189], v[106:109]
	v_mfma_f32_16x16x32_bf16 v[90:93], v[178:181], v[194:197], v[90:93]
	v_mfma_f32_16x16x32_bf16 v[90:93], v[182:185], v[202:205], v[90:93]
	v_mfma_f32_16x16x32_bf16 v[98:101], v[174:177], v[202:205], v[98:101]
	v_mfma_f32_16x16x32_bf16 v[98:101], v[170:173], v[194:197], v[98:101]
	v_mfma_f32_16x16x32_bf16 v[82:85], v[170:173], v[206:209], v[82:85]
	v_mfma_f32_16x16x32_bf16 v[82:85], v[174:177], v[210:213], v[82:85]
	v_mfma_f32_16x16x32_bf16 v[74:77], v[182:185], v[210:213], v[74:77]
	v_mfma_f32_16x16x32_bf16 v[74:77], v[178:181], v[206:209], v[74:77]
	v_mfma_f32_16x16x32_bf16 v[66:69], v[178:181], v[214:217], v[66:69]
	v_mfma_f32_16x16x32_bf16 v[66:69], v[182:185], v[218:221], v[66:69]
	v_mfma_f32_16x16x32_bf16 v[70:73], v[174:177], v[218:221], v[70:73]
	v_mfma_f32_16x16x32_bf16 v[70:73], v[170:173], v[214:217], v[70:73]
	s_setprio 0
	s_barrier
	s_mov_b32 m0, s91
	v_lshl_add_u64 v[198:199], v[198:199], 0, s[14:15]
	ds_read_b128 v[186:189], v148 offset:49152
	ds_read_b128 v[190:193], v148 offset:50176
	ds_read_b128 v[194:197], v148 offset:51200
	ds_read_b128 v[202:205], v148 offset:52224
	ds_read_b128 v[206:209], v148 offset:53248
	ds_read_b128 v[210:213], v148 offset:54272
	ds_read_b128 v[214:217], v148 offset:55296
	ds_read_b128 v[218:221], v148 offset:56320
	global_load_lds_dwordx4 v[198:199], off
	v_lshl_add_u64 v[198:199], v[222:223], 0, s[14:15]
	s_mov_b32 m0, s89
	s_nop 0
	global_load_lds_dwordx4 v[198:199], off
	v_lshl_add_u64 v[198:199], s[60:61], 0, v[136:137]
	s_mov_b32 m0, s90
	s_nop 0
	global_load_lds_dwordx4 v[198:199], off
	v_lshl_add_u64 v[198:199], s[60:61], 0, v[132:133]
	s_mov_b32 m0, s44
	s_nop 0
	global_load_lds_dwordx4 v[198:199], off
	v_lshl_add_u64 v[198:199], v[224:225], 0, s[14:15]
	s_mov_b32 m0, s79
	s_nop 0
	global_load_lds_dwordx4 v[198:199], off
	v_lshl_add_u64 v[198:199], v[226:227], 0, s[14:15]
	s_mov_b32 m0, s80
	s_nop 0
	global_load_lds_dwordx4 v[198:199], off
	s_waitcnt vmcnt(8)
	s_waitcnt lgkmcnt(0)
	s_barrier
	s_setprio 1
	s_waitcnt lgkmcnt(0)
	v_mfma_f32_16x16x32_bf16 v[62:65], v[150:153], v[186:189], v[62:65]
	v_mfma_f32_16x16x32_bf16 v[62:65], v[154:157], v[190:193], v[62:65]
	v_mfma_f32_16x16x32_bf16 v[58:61], v[166:169], v[190:193], v[58:61]
	v_mfma_f32_16x16x32_bf16 v[58:61], v[158:161], v[186:189], v[58:61]
	v_mfma_f32_16x16x32_bf16 v[46:49], v[158:161], v[194:197], v[46:49]
	v_mfma_f32_16x16x32_bf16 v[46:49], v[166:169], v[202:205], v[46:49]
	v_mfma_f32_16x16x32_bf16 v[54:57], v[154:157], v[202:205], v[54:57]
	v_mfma_f32_16x16x32_bf16 v[54:57], v[150:153], v[194:197], v[54:57]
	v_mfma_f32_16x16x32_bf16 v[38:41], v[150:153], v[206:209], v[38:41]
	v_mfma_f32_16x16x32_bf16 v[38:41], v[154:157], v[210:213], v[38:41]
	v_mfma_f32_16x16x32_bf16 v[30:33], v[166:169], v[210:213], v[30:33]
	v_mfma_f32_16x16x32_bf16 v[30:33], v[158:161], v[206:209], v[30:33]
	v_mfma_f32_16x16x32_bf16 v[14:17], v[158:161], v[214:217], v[14:17]
	v_mfma_f32_16x16x32_bf16 v[14:17], v[166:169], v[218:221], v[14:17]
	v_mfma_f32_16x16x32_bf16 v[22:25], v[154:157], v[218:221], v[22:25]
	v_mfma_f32_16x16x32_bf16 v[22:25], v[150:153], v[214:217], v[22:25]
	s_setprio 0
	s_setprio 1
	v_mfma_f32_16x16x32_bf16 v[50:53], v[170:173], v[186:189], v[50:53]
	v_mfma_f32_16x16x32_bf16 v[50:53], v[174:177], v[190:193], v[50:53]
	v_mfma_f32_16x16x32_bf16 v[42:45], v[182:185], v[190:193], v[42:45]
	v_mfma_f32_16x16x32_bf16 v[42:45], v[178:181], v[186:189], v[42:45]
	v_mfma_f32_16x16x32_bf16 v[26:29], v[178:181], v[194:197], v[26:29]
	v_mfma_f32_16x16x32_bf16 v[26:29], v[182:185], v[202:205], v[26:29]
	v_mfma_f32_16x16x32_bf16 v[34:37], v[174:177], v[202:205], v[34:37]
	v_mfma_f32_16x16x32_bf16 v[34:37], v[170:173], v[194:197], v[34:37]
	v_mfma_f32_16x16x32_bf16 v[18:21], v[170:173], v[206:209], v[18:21]
	v_mfma_f32_16x16x32_bf16 v[18:21], v[174:177], v[210:213], v[18:21]
	v_mfma_f32_16x16x32_bf16 v[10:13], v[182:185], v[210:213], v[10:13]
	v_mfma_f32_16x16x32_bf16 v[10:13], v[178:181], v[206:209], v[10:13]
	v_mfma_f32_16x16x32_bf16 v[2:5], v[178:181], v[214:217], v[2:5]
	v_mfma_f32_16x16x32_bf16 v[2:5], v[182:185], v[218:221], v[2:5]
	v_mfma_f32_16x16x32_bf16 v[6:9], v[174:177], v[218:221], v[6:9]
	v_mfma_f32_16x16x32_bf16 v[6:9], v[170:173], v[214:217], v[6:9]
	s_setprio 0
	s_barrier
	s_movk_i32 s44, 0x100
	s_andn2_b64 vcc, exec, s[58:59]
	s_mov_b64 s[60:61], -1
	s_mov_b64 s[58:59], 0
	s_cbranch_vccz .LBB0_1667
	s_and_b64 vcc, exec, s[16:17]
	s_cbranch_vccz .LBB0_1670
	s_barrier

.LBB0_1685:
	ds_read_b128 v[156:159], v153
	ds_read_b128 v[166:169], v153 offset:1024
	ds_read_b128 v[170:173], v153 offset:2048
	ds_read_b128 v[174:177], v153 offset:3072
	ds_read_b128 v[178:181], v154
	ds_read_b128 v[182:185], v154 offset:1024
	ds_read_b128 v[186:189], v154 offset:2048
	ds_read_b128 v[190:193], v154 offset:3072
	s_add_u32 s36, s56, 0xfff00080
	s_addc_u32 s37, s57, -1
	s_cmp_eq_u32 s78, 60
	s_cselect_b32 s61, s25, s37
	s_cselect_b32 s60, s74, s36
	s_cselect_b32 s59, s21, s77
	s_cselect_b32 s58, s75, s76
	v_lshl_add_u64 v[160:161], s[56:57], 0, v[140:141]
	s_add_i32 m0, s55, 0xc000
	ds_read_b128 v[194:197], v155
	ds_read_b128 v[202:205], v155 offset:1024
	ds_read_b128 v[206:209], v155 offset:2048
	ds_read_b128 v[210:213], v155 offset:3072
	ds_read_b128 v[214:217], v155 offset:4096
	ds_read_b128 v[218:221], v155 offset:5120
	ds_read_b128 v[222:225], v155 offset:6144
	ds_read_b128 v[226:229], v155 offset:7168
	global_load_lds_dwordx4 v[160:161], off
	v_lshl_add_u64 v[160:161], s[56:57], 0, v[142:143]
	s_add_i32 m0, s55, 0xe000
	s_nop 0
	global_load_lds_dwordx4 v[160:161], off
	s_waitcnt vmcnt(8)
	s_waitcnt lgkmcnt(0)
	s_barrier
	s_setprio 1
	s_waitcnt lgkmcnt(0)
	v_mfma_f32_16x16x32_bf16 v[126:129], v[156:159], v[194:197], v[126:129]
	v_mfma_f32_16x16x32_bf16 v[126:129], v[166:169], v[202:205], v[126:129]
	v_mfma_f32_16x16x32_bf16 v[122:125], v[174:177], v[202:205], v[122:125]
	v_mfma_f32_16x16x32_bf16 v[122:125], v[170:173], v[194:197], v[122:125]
	v_mfma_f32_16x16x32_bf16 v[110:113], v[170:173], v[206:209], v[110:113]
	v_mfma_f32_16x16x32_bf16 v[110:113], v[174:177], v[210:213], v[110:113]
	v_mfma_f32_16x16x32_bf16 v[118:121], v[166:169], v[210:213], v[118:121]
	v_mfma_f32_16x16x32_bf16 v[118:121], v[156:159], v[206:209], v[118:121]
	v_mfma_f32_16x16x32_bf16 v[102:105], v[156:159], v[214:217], v[102:105]
	v_mfma_f32_16x16x32_bf16 v[102:105], v[166:169], v[218:221], v[102:105]
	v_mfma_f32_16x16x32_bf16 v[94:97], v[174:177], v[218:221], v[94:97]
	v_mfma_f32_16x16x32_bf16 v[94:97], v[170:173], v[214:217], v[94:97]
	v_mfma_f32_16x16x32_bf16 v[78:81], v[170:173], v[222:225], v[78:81]
	v_mfma_f32_16x16x32_bf16 v[78:81], v[174:177], v[226:229], v[78:81]
	v_mfma_f32_16x16x32_bf16 v[86:89], v[166:169], v[226:229], v[86:89]
	v_mfma_f32_16x16x32_bf16 v[86:89], v[156:159], v[222:225], v[86:89]
	s_setprio 0
	s_setprio 1
	v_mfma_f32_16x16x32_bf16 v[114:117], v[178:181], v[194:197], v[114:117]
	v_mfma_f32_16x16x32_bf16 v[114:117], v[182:185], v[202:205], v[114:117]
	v_mfma_f32_16x16x32_bf16 v[106:109], v[190:193], v[202:205], v[106:109]
	v_mfma_f32_16x16x32_bf16 v[106:109], v[186:189], v[194:197], v[106:109]
	v_mfma_f32_16x16x32_bf16 v[90:93], v[186:189], v[206:209], v[90:93]
	v_mfma_f32_16x16x32_bf16 v[90:93], v[190:193], v[210:213], v[90:93]
	v_mfma_f32_16x16x32_bf16 v[98:101], v[182:185], v[210:213], v[98:101]
	v_mfma_f32_16x16x32_bf16 v[98:101], v[178:181], v[206:209], v[98:101]
	v_mfma_f32_16x16x32_bf16 v[82:85], v[178:181], v[214:217], v[82:85]
	v_mfma_f32_16x16x32_bf16 v[82:85], v[182:185], v[218:221], v[82:85]
	v_mfma_f32_16x16x32_bf16 v[74:77], v[190:193], v[218:221], v[74:77]
	v_mfma_f32_16x16x32_bf16 v[74:77], v[186:189], v[214:217], v[74:77]
	v_mfma_f32_16x16x32_bf16 v[66:69], v[186:189], v[222:225], v[66:69]
	v_mfma_f32_16x16x32_bf16 v[66:69], v[190:193], v[226:229], v[66:69]
	v_mfma_f32_16x16x32_bf16 v[70:73], v[182:185], v[226:229], v[70:73]
	v_mfma_f32_16x16x32_bf16 v[70:73], v[178:181], v[222:225], v[70:73]
	s_setprio 0
	s_barrier
	s_add_i32 s36, s68, s38
	v_lshl_add_u64 v[160:161], s[58:59], 0, v[136:137]
	s_mov_b32 m0, s36
	ds_read_b128 v[194:197], v155 offset:16384
	ds_read_b128 v[202:205], v155 offset:17408
	ds_read_b128 v[206:209], v155 offset:18432
	ds_read_b128 v[210:213], v155 offset:19456
	ds_read_b128 v[214:217], v155 offset:20480
	ds_read_b128 v[218:221], v155 offset:21504
	ds_read_b128 v[222:225], v155 offset:22528
	ds_read_b128 v[226:229], v155 offset:23552
	global_load_lds_dwordx4 v[160:161], off
	s_add_i32 m0, s36, 0x2000
	s_add_u32 s80, s58, 0x100000
	v_lshl_add_u64 v[198:199], s[58:59], 0, v[132:133]
	s_addc_u32 s81, s59, 0
	s_add_i32 s36, s69, s38
	global_load_lds_dwordx4 v[198:199], off
	v_lshl_add_u64 v[230:231], s[80:81], 0, v[136:137]
	s_mov_b32 m0, s36
	v_lshl_add_u64 v[232:233], s[60:61], 0, v[134:135]
	global_load_lds_dwordx4 v[230:231], off
	v_lshl_add_u64 v[230:231], s[80:81], 0, v[132:133]
	s_add_i32 m0, s36, 0x2000
	s_nop 0
	global_load_lds_dwordx4 v[230:231], off
	v_lshl_add_u64 v[230:231], s[60:61], 0, v[138:139]
	s_mov_b32 m0, s55
	s_nop 0
	global_load_lds_dwordx4 v[230:231], off
	s_mov_b32 m0, s63
	s_nop 0
	global_load_lds_dwordx4 v[232:233], off
	s_nop 0
	s_waitcnt vmcnt(8)
	s_waitcnt lgkmcnt(0)
	s_barrier
	s_setprio 1
	s_waitcnt lgkmcnt(0)
	v_mfma_f32_16x16x32_bf16 v[62:65], v[156:159], v[194:197], v[62:65]
	v_mfma_f32_16x16x32_bf16 v[62:65], v[166:169], v[202:205], v[62:65]
	v_mfma_f32_16x16x32_bf16 v[58:61], v[174:177], v[202:205], v[58:61]
	v_mfma_f32_16x16x32_bf16 v[58:61], v[170:173], v[194:197], v[58:61]
	v_mfma_f32_16x16x32_bf16 v[46:49], v[170:173], v[206:209], v[46:49]
	v_mfma_f32_16x16x32_bf16 v[46:49], v[174:177], v[210:213], v[46:49]
	v_mfma_f32_16x16x32_bf16 v[54:57], v[166:169], v[210:213], v[54:57]
	v_mfma_f32_16x16x32_bf16 v[54:57], v[156:159], v[206:209], v[54:57]
	v_mfma_f32_16x16x32_bf16 v[38:41], v[156:159], v[214:217], v[38:41]
	v_mfma_f32_16x16x32_bf16 v[38:41], v[166:169], v[218:221], v[38:41]
	v_mfma_f32_16x16x32_bf16 v[30:33], v[174:177], v[218:221], v[30:33]
	v_mfma_f32_16x16x32_bf16 v[30:33], v[170:173], v[214:217], v[30:33]
	v_mfma_f32_16x16x32_bf16 v[14:17], v[170:173], v[222:225], v[14:17]
	v_mfma_f32_16x16x32_bf16 v[14:17], v[174:177], v[226:229], v[14:17]
	v_mfma_f32_16x16x32_bf16 v[22:25], v[166:169], v[226:229], v[22:25]
	v_mfma_f32_16x16x32_bf16 v[22:25], v[156:159], v[222:225], v[22:25]
	s_setprio 0
	s_setprio 1
	v_mfma_f32_16x16x32_bf16 v[50:53], v[178:181], v[194:197], v[50:53]
	v_mfma_f32_16x16x32_bf16 v[50:53], v[182:185], v[202:205], v[50:53]
	v_mfma_f32_16x16x32_bf16 v[42:45], v[190:193], v[202:205], v[42:45]
	v_mfma_f32_16x16x32_bf16 v[42:45], v[186:189], v[194:197], v[42:45]
	v_mfma_f32_16x16x32_bf16 v[26:29], v[186:189], v[206:209], v[26:29]
	v_mfma_f32_16x16x32_bf16 v[26:29], v[190:193], v[210:213], v[26:29]
	v_mfma_f32_16x16x32_bf16 v[34:37], v[182:185], v[210:213], v[34:37]
	v_mfma_f32_16x16x32_bf16 v[34:37], v[178:181], v[206:209], v[34:37]
	v_mfma_f32_16x16x32_bf16 v[18:21], v[178:181], v[214:217], v[18:21]
	v_mfma_f32_16x16x32_bf16 v[18:21], v[182:185], v[218:221], v[18:21]
	v_mfma_f32_16x16x32_bf16 v[10:13], v[190:193], v[218:221], v[10:13]
	v_mfma_f32_16x16x32_bf16 v[10:13], v[186:189], v[214:217], v[10:13]
	v_mfma_f32_16x16x32_bf16 v[2:5], v[186:189], v[222:225], v[2:5]
	v_mfma_f32_16x16x32_bf16 v[2:5], v[190:193], v[226:229], v[2:5]
	v_mfma_f32_16x16x32_bf16 v[6:9], v[182:185], v[226:229], v[6:9]
	v_mfma_f32_16x16x32_bf16 v[6:9], v[178:181], v[222:225], v[6:9]
	s_setprio 0
	s_barrier
	s_add_i32 s36, 0, 0x18000
	v_add_u32_e32 v165, s36, v151
	s_add_i32 s37, 0, 0x1c000
	ds_read_b128 v[156:159], v165
	ds_read_b128 v[166:169], v165 offset:1024
	ds_read_b128 v[170:173], v165 offset:2048
	ds_read_b128 v[174:177], v165 offset:3072
	v_add_u32_e32 v165, s37, v151
	ds_read_b128 v[178:181], v165
	ds_read_b128 v[182:185], v165 offset:1024
	ds_read_b128 v[186:189], v165 offset:2048
	ds_read_b128 v[190:193], v165 offset:3072
	s_add_u32 s60, s60, 0x100000
	s_addc_u32 s61, s61, 0
	s_mov_b32 m0, s64
	v_lshl_add_u64 v[234:235], s[60:61], 0, v[138:139]
	ds_read_b128 v[194:197], v155 offset:32768
	ds_read_b128 v[202:205], v155 offset:33792
	ds_read_b128 v[206:209], v155 offset:34816
	ds_read_b128 v[210:213], v155 offset:35840
	ds_read_b128 v[214:217], v155 offset:36864
	ds_read_b128 v[218:221], v155 offset:37888
	ds_read_b128 v[222:225], v155 offset:38912
	ds_read_b128 v[226:229], v155 offset:39936
	global_load_lds_dwordx4 v[234:235], off
	v_lshl_add_u64 v[234:235], s[60:61], 0, v[134:135]
	s_mov_b32 m0, s65
	s_nop 0
	global_load_lds_dwordx4 v[234:235], off
	s_nop 0
	s_waitcnt vmcnt(8)
	s_waitcnt lgkmcnt(0)
	s_barrier
	s_setprio 1
	s_waitcnt lgkmcnt(0)
	v_mfma_f32_16x16x32_bf16 v[126:129], v[156:159], v[194:197], v[126:129]
	v_mfma_f32_16x16x32_bf16 v[126:129], v[166:169], v[202:205], v[126:129]
	v_mfma_f32_16x16x32_bf16 v[122:125], v[174:177], v[202:205], v[122:125]
	v_mfma_f32_16x16x32_bf16 v[122:125], v[170:173], v[194:197], v[122:125]
	v_mfma_f32_16x16x32_bf16 v[110:113], v[170:173], v[206:209], v[110:113]
	v_mfma_f32_16x16x32_bf16 v[110:113], v[174:177], v[210:213], v[110:113]
	v_mfma_f32_16x16x32_bf16 v[118:121], v[166:169], v[210:213], v[118:121]
	v_mfma_f32_16x16x32_bf16 v[118:121], v[156:159], v[206:209], v[118:121]
	v_mfma_f32_16x16x32_bf16 v[102:105], v[156:159], v[214:217], v[102:105]
	v_mfma_f32_16x16x32_bf16 v[102:105], v[166:169], v[218:221], v[102:105]
	v_mfma_f32_16x16x32_bf16 v[94:97], v[174:177], v[218:221], v[94:97]
	v_mfma_f32_16x16x32_bf16 v[94:97], v[170:173], v[214:217], v[94:97]
	v_mfma_f32_16x16x32_bf16 v[78:81], v[170:173], v[222:225], v[78:81]
	v_mfma_f32_16x16x32_bf16 v[78:81], v[174:177], v[226:229], v[78:81]
	v_mfma_f32_16x16x32_bf16 v[86:89], v[166:169], v[226:229], v[86:89]
	v_mfma_f32_16x16x32_bf16 v[86:89], v[156:159], v[222:225], v[86:89]
	s_setprio 0
	s_setprio 1
	v_mfma_f32_16x16x32_bf16 v[114:117], v[178:181], v[194:197], v[114:117]
	v_mfma_f32_16x16x32_bf16 v[114:117], v[182:185], v[202:205], v[114:117]
	v_mfma_f32_16x16x32_bf16 v[106:109], v[190:193], v[202:205], v[106:109]
	v_mfma_f32_16x16x32_bf16 v[106:109], v[186:189], v[194:197], v[106:109]
	v_mfma_f32_16x16x32_bf16 v[90:93], v[186:189], v[206:209], v[90:93]
	v_mfma_f32_16x16x32_bf16 v[90:93], v[190:193], v[210:213], v[90:93]
	v_mfma_f32_16x16x32_bf16 v[98:101], v[182:185], v[210:213], v[98:101]
	v_mfma_f32_16x16x32_bf16 v[98:101], v[178:181], v[206:209], v[98:101]
	v_mfma_f32_16x16x32_bf16 v[82:85], v[178:181], v[214:217], v[82:85]
	v_mfma_f32_16x16x32_bf16 v[82:85], v[182:185], v[218:221], v[82:85]
	v_mfma_f32_16x16x32_bf16 v[74:77], v[190:193], v[218:221], v[74:77]
	v_mfma_f32_16x16x32_bf16 v[74:77], v[186:189], v[214:217], v[74:77]
	v_mfma_f32_16x16x32_bf16 v[66:69], v[186:189], v[222:225], v[66:69]
	v_mfma_f32_16x16x32_bf16 v[66:69], v[190:193], v[226:229], v[66:69]
	v_mfma_f32_16x16x32_bf16 v[70:73], v[182:185], v[226:229], v[70:73]
	v_mfma_f32_16x16x32_bf16 v[70:73], v[178:181], v[222:225], v[70:73]
	s_setprio 0
	s_barrier
	s_add_i32 s36, s36, s38
	v_lshl_add_u64 v[160:161], v[160:161], 0, s[16:17]
	s_mov_b32 m0, s36
	ds_read_b128 v[194:197], v155 offset:49152
	ds_read_b128 v[202:205], v155 offset:50176
	ds_read_b128 v[206:209], v155 offset:51200
	ds_read_b128 v[210:213], v155 offset:52224
	ds_read_b128 v[214:217], v155 offset:53248
	ds_read_b128 v[218:221], v155 offset:54272
	ds_read_b128 v[222:225], v155 offset:55296
	ds_read_b128 v[226:229], v155 offset:56320
	global_load_lds_dwordx4 v[160:161], off
	s_add_i32 m0, s36, 0x2000
	s_add_u32 s58, s58, 0x100080
	v_lshl_add_u64 v[160:161], v[198:199], 0, s[16:17]
	s_addc_u32 s59, s59, 0
	s_add_i32 s36, s37, s38
	global_load_lds_dwordx4 v[160:161], off
	v_lshl_add_u64 v[160:161], s[58:59], 0, v[136:137]
	s_mov_b32 m0, s36
	s_nop 0
	global_load_lds_dwordx4 v[160:161], off
	v_lshl_add_u64 v[160:161], s[58:59], 0, v[132:133]
	s_add_i32 m0, s36, 0x2000
	s_nop 0
	global_load_lds_dwordx4 v[160:161], off
	v_lshl_add_u64 v[160:161], v[230:231], 0, s[16:17]
	s_mov_b32 m0, s66
	s_nop 0
	global_load_lds_dwordx4 v[160:161], off
	v_lshl_add_u64 v[160:161], v[232:233], 0, s[16:17]
	s_mov_b32 m0, s67
	s_nop 0
	global_load_lds_dwordx4 v[160:161], off
	s_waitcnt vmcnt(8)
	s_waitcnt lgkmcnt(0)
	s_barrier
	s_setprio 1
	s_waitcnt lgkmcnt(0)
	v_mfma_f32_16x16x32_bf16 v[62:65], v[156:159], v[194:197], v[62:65]
	v_mfma_f32_16x16x32_bf16 v[62:65], v[166:169], v[202:205], v[62:65]
	v_mfma_f32_16x16x32_bf16 v[58:61], v[174:177], v[202:205], v[58:61]
	v_mfma_f32_16x16x32_bf16 v[58:61], v[170:173], v[194:197], v[58:61]
	v_mfma_f32_16x16x32_bf16 v[46:49], v[170:173], v[206:209], v[46:49]
	v_mfma_f32_16x16x32_bf16 v[46:49], v[174:177], v[210:213], v[46:49]
	v_mfma_f32_16x16x32_bf16 v[54:57], v[166:169], v[210:213], v[54:57]
	v_mfma_f32_16x16x32_bf16 v[54:57], v[156:159], v[206:209], v[54:57]
	v_mfma_f32_16x16x32_bf16 v[38:41], v[156:159], v[214:217], v[38:41]
	v_mfma_f32_16x16x32_bf16 v[38:41], v[166:169], v[218:221], v[38:41]
	v_mfma_f32_16x16x32_bf16 v[30:33], v[174:177], v[218:221], v[30:33]
	v_mfma_f32_16x16x32_bf16 v[30:33], v[170:173], v[214:217], v[30:33]
	v_mfma_f32_16x16x32_bf16 v[14:17], v[170:173], v[222:225], v[14:17]
	v_mfma_f32_16x16x32_bf16 v[14:17], v[174:177], v[226:229], v[14:17]
	v_mfma_f32_16x16x32_bf16 v[22:25], v[166:169], v[226:229], v[22:25]
	v_mfma_f32_16x16x32_bf16 v[22:25], v[156:159], v[222:225], v[22:25]
	s_setprio 0
	s_setprio 1
	v_mfma_f32_16x16x32_bf16 v[50:53], v[178:181], v[194:197], v[50:53]
	v_mfma_f32_16x16x32_bf16 v[50:53], v[182:185], v[202:205], v[50:53]
	v_mfma_f32_16x16x32_bf16 v[42:45], v[190:193], v[202:205], v[42:45]
	v_mfma_f32_16x16x32_bf16 v[42:45], v[186:189], v[194:197], v[42:45]
	v_mfma_f32_16x16x32_bf16 v[26:29], v[186:189], v[206:209], v[26:29]
	v_mfma_f32_16x16x32_bf16 v[26:29], v[190:193], v[210:213], v[26:29]
	v_mfma_f32_16x16x32_bf16 v[34:37], v[182:185], v[210:213], v[34:37]
	v_mfma_f32_16x16x32_bf16 v[34:37], v[178:181], v[206:209], v[34:37]
	v_mfma_f32_16x16x32_bf16 v[18:21], v[178:181], v[214:217], v[18:21]
	v_mfma_f32_16x16x32_bf16 v[18:21], v[182:185], v[218:221], v[18:21]
	v_mfma_f32_16x16x32_bf16 v[10:13], v[190:193], v[218:221], v[10:13]
	v_mfma_f32_16x16x32_bf16 v[10:13], v[186:189], v[214:217], v[10:13]
	v_mfma_f32_16x16x32_bf16 v[2:5], v[186:189], v[222:225], v[2:5]
	v_mfma_f32_16x16x32_bf16 v[2:5], v[190:193], v[226:229], v[2:5]
	v_mfma_f32_16x16x32_bf16 v[6:9], v[182:185], v[226:229], v[6:9]
	v_mfma_f32_16x16x32_bf16 v[6:9], v[178:181], v[222:225], v[6:9]
	s_setprio 0
	s_barrier
	s_add_i32 s78, s78, 2
	s_add_u32 s56, s56, 0x100
	s_addc_u32 s57, s57, 0
	s_add_u32 s76, s76, 0x100
	s_addc_u32 s77, s77, 0
	s_cmp_gt_u32 s78, 61
	s_cbranch_scc0 .LBB0_1685
	s_and_b64 vcc, exec, s[18:19]
	s_cbranch_vccz .LBB0_1688
	s_barrier

.LBB0_1701:
	s_add_u32 s36, s56, s44
	s_addc_u32 s37, s57, 0
	s_add_u32 s64, s36, 0x100
	s_addc_u32 s65, s37, 0
	s_and_b64 s[62:63], s[60:61], exec
	s_cselect_b32 s65, s21, s65
	s_cselect_b32 s64, s86, s64
	s_add_u32 s44, s54, s44
	s_addc_u32 s62, s55, 0
	s_add_u32 s44, s44, 0x100
	s_addc_u32 s62, s62, 0
	s_and_b64 s[60:61], s[60:61], exec
	s_cselect_b32 s67, s25, s62
	s_cselect_b32 s66, s87, s44
	s_add_u32 s70, s36, 0x10080
	s_addc_u32 s71, s37, 0
	s_add_i32 s97, s81, s39
	ds_read_b128 v[152:155], v147
	ds_read_b128 v[156:159], v147 offset:1024
	ds_read_b128 v[166:169], v147 offset:2048
	ds_read_b128 v[170:173], v147 offset:3072
	ds_read_b128 v[174:177], v150
	ds_read_b128 v[178:181], v150 offset:1024
	ds_read_b128 v[182:185], v150 offset:2048
	ds_read_b128 v[186:189], v150 offset:3072
	s_add_i32 m0, s74, 0xc000
	s_add_i32 vcc_lo, s74, 0xe000
	s_add_i32 s94, s97, 0x2000
	s_add_u32 s68, s66, 0x10000
	s_addc_u32 s69, s67, 0
	s_add_i32 s96, s82, s39
	s_add_i32 s95, s96, 0x2000
	s_add_i32 s93, 0, 0x18000
	s_add_i32 s92, 0, 0x1c000
	s_add_u32 s62, s64, 0x10000
	s_addc_u32 s63, s65, 0
	s_add_i32 s91, s93, s39
	s_add_i32 s89, s91, 0x2000
	s_add_u32 s60, s66, 0x10080
	s_addc_u32 s61, s67, 0
	s_add_i32 s90, s92, s39
	s_add_i32 s44, s90, 0x2000
	v_lshl_add_u64 v[160:161], s[70:71], 0, v[138:139]
	ds_read_b128 v[190:193], v151
	ds_read_b128 v[194:197], v151 offset:1024
	ds_read_b128 v[202:205], v151 offset:2048
	ds_read_b128 v[206:209], v151 offset:3072
	ds_read_b128 v[210:213], v151 offset:4096
	ds_read_b128 v[214:217], v151 offset:5120
	ds_read_b128 v[218:221], v151 offset:6144
	ds_read_b128 v[222:225], v151 offset:7168
	global_load_lds_dwordx4 v[160:161], off
	v_lshl_add_u64 v[160:161], s[70:71], 0, v[134:135]
	s_mov_b32 m0, vcc_lo
	s_nop 0
	global_load_lds_dwordx4 v[160:161], off
	s_nop 0
	s_waitcnt vmcnt(8)
	s_waitcnt lgkmcnt(0)
	s_barrier
	s_setprio 1
	s_waitcnt lgkmcnt(0)
	v_mfma_f32_16x16x32_bf16 v[126:129], v[152:155], v[190:193], v[126:129]
	v_mfma_f32_16x16x32_bf16 v[126:129], v[156:159], v[194:197], v[126:129]
	v_mfma_f32_16x16x32_bf16 v[122:125], v[170:173], v[194:197], v[122:125]
	v_mfma_f32_16x16x32_bf16 v[122:125], v[166:169], v[190:193], v[122:125]
	v_mfma_f32_16x16x32_bf16 v[110:113], v[166:169], v[202:205], v[110:113]
	v_mfma_f32_16x16x32_bf16 v[110:113], v[170:173], v[206:209], v[110:113]
	v_mfma_f32_16x16x32_bf16 v[118:121], v[156:159], v[206:209], v[118:121]
	v_mfma_f32_16x16x32_bf16 v[118:121], v[152:155], v[202:205], v[118:121]
	v_mfma_f32_16x16x32_bf16 v[102:105], v[152:155], v[210:213], v[102:105]
	v_mfma_f32_16x16x32_bf16 v[102:105], v[156:159], v[214:217], v[102:105]
	v_mfma_f32_16x16x32_bf16 v[94:97], v[170:173], v[214:217], v[94:97]
	v_mfma_f32_16x16x32_bf16 v[94:97], v[166:169], v[210:213], v[94:97]
	v_mfma_f32_16x16x32_bf16 v[78:81], v[166:169], v[218:221], v[78:81]
	v_mfma_f32_16x16x32_bf16 v[78:81], v[170:173], v[222:225], v[78:81]
	v_mfma_f32_16x16x32_bf16 v[86:89], v[156:159], v[222:225], v[86:89]
	v_mfma_f32_16x16x32_bf16 v[86:89], v[152:155], v[218:221], v[86:89]
	s_setprio 0
	s_setprio 1
	v_mfma_f32_16x16x32_bf16 v[114:117], v[174:177], v[190:193], v[114:117]
	v_mfma_f32_16x16x32_bf16 v[114:117], v[178:181], v[194:197], v[114:117]
	v_mfma_f32_16x16x32_bf16 v[106:109], v[186:189], v[194:197], v[106:109]
	v_mfma_f32_16x16x32_bf16 v[106:109], v[182:185], v[190:193], v[106:109]
	v_mfma_f32_16x16x32_bf16 v[90:93], v[182:185], v[202:205], v[90:93]
	v_mfma_f32_16x16x32_bf16 v[90:93], v[186:189], v[206:209], v[90:93]
	v_mfma_f32_16x16x32_bf16 v[98:101], v[178:181], v[206:209], v[98:101]
	v_mfma_f32_16x16x32_bf16 v[98:101], v[174:177], v[202:205], v[98:101]
	v_mfma_f32_16x16x32_bf16 v[82:85], v[174:177], v[210:213], v[82:85]
	v_mfma_f32_16x16x32_bf16 v[82:85], v[178:181], v[214:217], v[82:85]
	v_mfma_f32_16x16x32_bf16 v[74:77], v[186:189], v[214:217], v[74:77]
	v_mfma_f32_16x16x32_bf16 v[74:77], v[182:185], v[210:213], v[74:77]
	v_mfma_f32_16x16x32_bf16 v[66:69], v[182:185], v[218:221], v[66:69]
	v_mfma_f32_16x16x32_bf16 v[66:69], v[186:189], v[222:225], v[66:69]
	v_mfma_f32_16x16x32_bf16 v[70:73], v[178:181], v[222:225], v[70:73]
	v_mfma_f32_16x16x32_bf16 v[70:73], v[174:177], v[218:221], v[70:73]
	s_setprio 0
	s_barrier
	s_mov_b32 m0, s97
	v_lshl_add_u64 v[160:161], s[66:67], 0, v[136:137]
	ds_read_b128 v[190:193], v151 offset:16384
	ds_read_b128 v[194:197], v151 offset:17408
	ds_read_b128 v[202:205], v151 offset:18432
	ds_read_b128 v[206:209], v151 offset:19456
	ds_read_b128 v[210:213], v151 offset:20480
	ds_read_b128 v[214:217], v151 offset:21504
	ds_read_b128 v[218:221], v151 offset:22528
	ds_read_b128 v[222:225], v151 offset:23552
	global_load_lds_dwordx4 v[160:161], off
	v_lshl_add_u64 v[198:199], s[66:67], 0, v[132:133]
	s_mov_b32 m0, s94
	v_lshl_add_u64 v[226:227], s[68:69], 0, v[136:137]
	global_load_lds_dwordx4 v[198:199], off
	s_mov_b32 m0, s96
	v_lshl_add_u64 v[228:229], s[64:65], 0, v[134:135]
	global_load_lds_dwordx4 v[226:227], off
	v_lshl_add_u64 v[226:227], s[68:69], 0, v[132:133]
	s_mov_b32 m0, s95
	s_nop 0
	global_load_lds_dwordx4 v[226:227], off
	v_lshl_add_u64 v[226:227], s[64:65], 0, v[138:139]
	s_mov_b32 m0, s74
	s_nop 0
	global_load_lds_dwordx4 v[226:227], off
	s_mov_b32 m0, s75
	s_nop 0
	global_load_lds_dwordx4 v[228:229], off
	s_waitcnt vmcnt(8)
	s_waitcnt lgkmcnt(0)
	s_barrier
	s_setprio 1
	s_waitcnt lgkmcnt(0)
	v_mfma_f32_16x16x32_bf16 v[62:65], v[152:155], v[190:193], v[62:65]
	v_mfma_f32_16x16x32_bf16 v[62:65], v[156:159], v[194:197], v[62:65]
	v_mfma_f32_16x16x32_bf16 v[58:61], v[170:173], v[194:197], v[58:61]
	v_mfma_f32_16x16x32_bf16 v[58:61], v[166:169], v[190:193], v[58:61]
	v_mfma_f32_16x16x32_bf16 v[46:49], v[166:169], v[202:205], v[46:49]
	v_mfma_f32_16x16x32_bf16 v[46:49], v[170:173], v[206:209], v[46:49]
	v_mfma_f32_16x16x32_bf16 v[54:57], v[156:159], v[206:209], v[54:57]
	v_mfma_f32_16x16x32_bf16 v[54:57], v[152:155], v[202:205], v[54:57]
	v_mfma_f32_16x16x32_bf16 v[38:41], v[152:155], v[210:213], v[38:41]
	v_mfma_f32_16x16x32_bf16 v[38:41], v[156:159], v[214:217], v[38:41]
	v_mfma_f32_16x16x32_bf16 v[30:33], v[170:173], v[214:217], v[30:33]
	v_mfma_f32_16x16x32_bf16 v[30:33], v[166:169], v[210:213], v[30:33]
	v_mfma_f32_16x16x32_bf16 v[14:17], v[166:169], v[218:221], v[14:17]
	v_mfma_f32_16x16x32_bf16 v[14:17], v[170:173], v[222:225], v[14:17]
	v_mfma_f32_16x16x32_bf16 v[22:25], v[156:159], v[222:225], v[22:25]
	v_mfma_f32_16x16x32_bf16 v[22:25], v[152:155], v[218:221], v[22:25]
	s_setprio 0
	s_setprio 1
	v_mfma_f32_16x16x32_bf16 v[50:53], v[174:177], v[190:193], v[50:53]
	v_mfma_f32_16x16x32_bf16 v[50:53], v[178:181], v[194:197], v[50:53]
	v_mfma_f32_16x16x32_bf16 v[42:45], v[186:189], v[194:197], v[42:45]
	v_mfma_f32_16x16x32_bf16 v[42:45], v[182:185], v[190:193], v[42:45]
	v_mfma_f32_16x16x32_bf16 v[26:29], v[182:185], v[202:205], v[26:29]
	v_mfma_f32_16x16x32_bf16 v[26:29], v[186:189], v[206:209], v[26:29]
	v_mfma_f32_16x16x32_bf16 v[34:37], v[178:181], v[206:209], v[34:37]
	v_mfma_f32_16x16x32_bf16 v[34:37], v[174:177], v[202:205], v[34:37]
	v_mfma_f32_16x16x32_bf16 v[18:21], v[174:177], v[210:213], v[18:21]
	v_mfma_f32_16x16x32_bf16 v[18:21], v[178:181], v[214:217], v[18:21]
	v_mfma_f32_16x16x32_bf16 v[10:13], v[186:189], v[214:217], v[10:13]
	v_mfma_f32_16x16x32_bf16 v[10:13], v[182:185], v[210:213], v[10:13]
	v_mfma_f32_16x16x32_bf16 v[2:5], v[182:185], v[218:221], v[2:5]
	v_mfma_f32_16x16x32_bf16 v[2:5], v[186:189], v[222:225], v[2:5]
	v_mfma_f32_16x16x32_bf16 v[6:9], v[178:181], v[222:225], v[6:9]
	v_mfma_f32_16x16x32_bf16 v[6:9], v[174:177], v[218:221], v[6:9]
	s_setprio 0
	s_barrier
	v_add_u32_e32 v165, s93, v145
	ds_read_b128 v[152:155], v165
	ds_read_b128 v[156:159], v165 offset:1024
	ds_read_b128 v[166:169], v165 offset:2048
	ds_read_b128 v[170:173], v165 offset:3072
	v_add_u32_e32 v165, s92, v145
	ds_read_b128 v[174:177], v165
	ds_read_b128 v[178:181], v165 offset:1024
	ds_read_b128 v[182:185], v165 offset:2048
	ds_read_b128 v[186:189], v165 offset:3072
	s_mov_b32 m0, s76
	v_lshl_add_u64 v[230:231], s[62:63], 0, v[138:139]
	ds_read_b128 v[190:193], v151 offset:32768
	ds_read_b128 v[194:197], v151 offset:33792
	ds_read_b128 v[202:205], v151 offset:34816
	ds_read_b128 v[206:209], v151 offset:35840
	ds_read_b128 v[210:213], v151 offset:36864
	ds_read_b128 v[214:217], v151 offset:37888
	ds_read_b128 v[218:221], v151 offset:38912
	ds_read_b128 v[222:225], v151 offset:39936
	global_load_lds_dwordx4 v[230:231], off
	v_lshl_add_u64 v[230:231], s[62:63], 0, v[134:135]
	s_mov_b32 m0, s77
	s_nop 0
	global_load_lds_dwordx4 v[230:231], off
	s_waitcnt vmcnt(8)
	s_waitcnt lgkmcnt(0)
	s_barrier
	s_setprio 1
	s_waitcnt lgkmcnt(0)
	v_mfma_f32_16x16x32_bf16 v[126:129], v[152:155], v[190:193], v[126:129]
	v_mfma_f32_16x16x32_bf16 v[126:129], v[156:159], v[194:197], v[126:129]
	v_mfma_f32_16x16x32_bf16 v[122:125], v[170:173], v[194:197], v[122:125]
	v_mfma_f32_16x16x32_bf16 v[122:125], v[166:169], v[190:193], v[122:125]
	v_mfma_f32_16x16x32_bf16 v[110:113], v[166:169], v[202:205], v[110:113]
	v_mfma_f32_16x16x32_bf16 v[110:113], v[170:173], v[206:209], v[110:113]
	v_mfma_f32_16x16x32_bf16 v[118:121], v[156:159], v[206:209], v[118:121]
	v_mfma_f32_16x16x32_bf16 v[118:121], v[152:155], v[202:205], v[118:121]
	v_mfma_f32_16x16x32_bf16 v[102:105], v[152:155], v[210:213], v[102:105]
	v_mfma_f32_16x16x32_bf16 v[102:105], v[156:159], v[214:217], v[102:105]
	v_mfma_f32_16x16x32_bf16 v[94:97], v[170:173], v[214:217], v[94:97]
	v_mfma_f32_16x16x32_bf16 v[94:97], v[166:169], v[210:213], v[94:97]
	v_mfma_f32_16x16x32_bf16 v[78:81], v[166:169], v[218:221], v[78:81]
	v_mfma_f32_16x16x32_bf16 v[78:81], v[170:173], v[222:225], v[78:81]
	v_mfma_f32_16x16x32_bf16 v[86:89], v[156:159], v[222:225], v[86:89]
	v_mfma_f32_16x16x32_bf16 v[86:89], v[152:155], v[218:221], v[86:89]
	s_setprio 0
	s_setprio 1
	v_mfma_f32_16x16x32_bf16 v[114:117], v[174:177], v[190:193], v[114:117]
	v_mfma_f32_16x16x32_bf16 v[114:117], v[178:181], v[194:197], v[114:117]
	v_mfma_f32_16x16x32_bf16 v[106:109], v[186:189], v[194:197], v[106:109]
	v_mfma_f32_16x16x32_bf16 v[106:109], v[182:185], v[190:193], v[106:109]
	v_mfma_f32_16x16x32_bf16 v[90:93], v[182:185], v[202:205], v[90:93]
	v_mfma_f32_16x16x32_bf16 v[90:93], v[186:189], v[206:209], v[90:93]
	v_mfma_f32_16x16x32_bf16 v[98:101], v[178:181], v[206:209], v[98:101]
	v_mfma_f32_16x16x32_bf16 v[98:101], v[174:177], v[202:205], v[98:101]
	v_mfma_f32_16x16x32_bf16 v[82:85], v[174:177], v[210:213], v[82:85]
	v_mfma_f32_16x16x32_bf16 v[82:85], v[178:181], v[214:217], v[82:85]
	v_mfma_f32_16x16x32_bf16 v[74:77], v[186:189], v[214:217], v[74:77]
	v_mfma_f32_16x16x32_bf16 v[74:77], v[182:185], v[210:213], v[74:77]
	v_mfma_f32_16x16x32_bf16 v[66:69], v[182:185], v[218:221], v[66:69]
	v_mfma_f32_16x16x32_bf16 v[66:69], v[186:189], v[222:225], v[66:69]
	v_mfma_f32_16x16x32_bf16 v[70:73], v[178:181], v[222:225], v[70:73]
	v_mfma_f32_16x16x32_bf16 v[70:73], v[174:177], v[218:221], v[70:73]
	s_setprio 0
	s_barrier
	s_mov_b32 m0, s91
	v_lshl_add_u64 v[160:161], v[160:161], 0, s[14:15]
	ds_read_b128 v[190:193], v151 offset:49152
	ds_read_b128 v[194:197], v151 offset:50176
	ds_read_b128 v[202:205], v151 offset:51200
	ds_read_b128 v[206:209], v151 offset:52224
	ds_read_b128 v[210:213], v151 offset:53248
	ds_read_b128 v[214:217], v151 offset:54272
	ds_read_b128 v[218:221], v151 offset:55296
	ds_read_b128 v[222:225], v151 offset:56320
	global_load_lds_dwordx4 v[160:161], off
	v_lshl_add_u64 v[160:161], v[198:199], 0, s[14:15]
	s_mov_b32 m0, s89
	s_nop 0
	global_load_lds_dwordx4 v[160:161], off
	v_lshl_add_u64 v[160:161], s[60:61], 0, v[136:137]
	s_mov_b32 m0, s90
	s_nop 0
	global_load_lds_dwordx4 v[160:161], off
	v_lshl_add_u64 v[160:161], s[60:61], 0, v[132:133]
	s_mov_b32 m0, s44
	s_nop 0
	global_load_lds_dwordx4 v[160:161], off
	v_lshl_add_u64 v[160:161], v[226:227], 0, s[14:15]
	s_mov_b32 m0, s79
	s_nop 0
	global_load_lds_dwordx4 v[160:161], off
	v_lshl_add_u64 v[160:161], v[228:229], 0, s[14:15]
	s_mov_b32 m0, s80
	s_nop 0
	global_load_lds_dwordx4 v[160:161], off
	s_waitcnt vmcnt(8)
	s_waitcnt lgkmcnt(0)
	s_barrier
	s_setprio 1
	s_waitcnt lgkmcnt(0)
	v_mfma_f32_16x16x32_bf16 v[62:65], v[152:155], v[190:193], v[62:65]
	v_mfma_f32_16x16x32_bf16 v[62:65], v[156:159], v[194:197], v[62:65]
	v_mfma_f32_16x16x32_bf16 v[58:61], v[170:173], v[194:197], v[58:61]
	v_mfma_f32_16x16x32_bf16 v[58:61], v[166:169], v[190:193], v[58:61]
	v_mfma_f32_16x16x32_bf16 v[46:49], v[166:169], v[202:205], v[46:49]
	v_mfma_f32_16x16x32_bf16 v[46:49], v[170:173], v[206:209], v[46:49]
	v_mfma_f32_16x16x32_bf16 v[54:57], v[156:159], v[206:209], v[54:57]
	v_mfma_f32_16x16x32_bf16 v[54:57], v[152:155], v[202:205], v[54:57]
	v_mfma_f32_16x16x32_bf16 v[38:41], v[152:155], v[210:213], v[38:41]
	v_mfma_f32_16x16x32_bf16 v[38:41], v[156:159], v[214:217], v[38:41]
	v_mfma_f32_16x16x32_bf16 v[30:33], v[170:173], v[214:217], v[30:33]
	v_mfma_f32_16x16x32_bf16 v[30:33], v[166:169], v[210:213], v[30:33]
	v_mfma_f32_16x16x32_bf16 v[14:17], v[166:169], v[218:221], v[14:17]
	v_mfma_f32_16x16x32_bf16 v[14:17], v[170:173], v[222:225], v[14:17]
	v_mfma_f32_16x16x32_bf16 v[22:25], v[156:159], v[222:225], v[22:25]
	v_mfma_f32_16x16x32_bf16 v[22:25], v[152:155], v[218:221], v[22:25]
	s_setprio 0
	s_setprio 1
	v_mfma_f32_16x16x32_bf16 v[50:53], v[174:177], v[190:193], v[50:53]
	v_mfma_f32_16x16x32_bf16 v[50:53], v[178:181], v[194:197], v[50:53]
	v_mfma_f32_16x16x32_bf16 v[42:45], v[186:189], v[194:197], v[42:45]
	v_mfma_f32_16x16x32_bf16 v[42:45], v[182:185], v[190:193], v[42:45]
	v_mfma_f32_16x16x32_bf16 v[26:29], v[182:185], v[202:205], v[26:29]
	v_mfma_f32_16x16x32_bf16 v[26:29], v[186:189], v[206:209], v[26:29]
	v_mfma_f32_16x16x32_bf16 v[34:37], v[178:181], v[206:209], v[34:37]
	v_mfma_f32_16x16x32_bf16 v[34:37], v[174:177], v[202:205], v[34:37]
	v_mfma_f32_16x16x32_bf16 v[18:21], v[174:177], v[210:213], v[18:21]
	v_mfma_f32_16x16x32_bf16 v[18:21], v[178:181], v[214:217], v[18:21]
	v_mfma_f32_16x16x32_bf16 v[10:13], v[186:189], v[214:217], v[10:13]
	v_mfma_f32_16x16x32_bf16 v[10:13], v[182:185], v[210:213], v[10:13]
	v_mfma_f32_16x16x32_bf16 v[2:5], v[182:185], v[218:221], v[2:5]
	v_mfma_f32_16x16x32_bf16 v[2:5], v[186:189], v[222:225], v[2:5]
	v_mfma_f32_16x16x32_bf16 v[6:9], v[178:181], v[222:225], v[6:9]
	v_mfma_f32_16x16x32_bf16 v[6:9], v[174:177], v[218:221], v[6:9]
	s_setprio 0
	s_barrier
	s_movk_i32 s44, 0x100
	s_andn2_b64 vcc, exec, s[58:59]
	s_mov_b64 s[60:61], -1
	s_mov_b64 s[58:59], 0
	s_cbranch_vccz .LBB0_1701
	s_and_b64 vcc, exec, s[16:17]
	s_cbranch_vccz .LBB0_1704
	s_barrier

.LBB0_1902:
	ds_read_b128 v[148:151], v156
	ds_read_b128 v[166:169], v156 offset:1024
	ds_read_b128 v[170:173], v156 offset:2048
	ds_read_b128 v[174:177], v156 offset:3072
	ds_read_b128 v[178:181], v157
	ds_read_b128 v[182:185], v157 offset:1024
	ds_read_b128 v[186:189], v157 offset:2048
	ds_read_b128 v[190:193], v157 offset:3072
	s_add_i32 s92, s58, 2
	s_add_u32 s36, s56, 0xffd50080
	s_addc_u32 s37, s57, -1
	s_cmp_eq_u32 s89, s58
	s_cselect_b32 s58, s54, s90
	s_cselect_b32 s61, s53, s37
	s_cselect_b32 s60, s52, s36
	s_cselect_b32 s59, s55, s91
	v_lshl_add_u64 v[152:153], s[56:57], 0, v[142:143]
	s_add_i32 m0, s67, 0xc000
	ds_read_b128 v[194:197], v158
	ds_read_b128 v[202:205], v158 offset:1024
	ds_read_b128 v[206:209], v158 offset:2048
	ds_read_b128 v[210:213], v158 offset:3072
	ds_read_b128 v[214:217], v158 offset:4096
	ds_read_b128 v[218:221], v158 offset:5120
	ds_read_b128 v[222:225], v158 offset:6144
	ds_read_b128 v[226:229], v158 offset:7168
	global_load_lds_dwordx4 v[152:153], off
	v_lshl_add_u64 v[152:153], s[56:57], 0, v[144:145]
	s_add_i32 m0, s67, 0xe000
	s_nop 0
	global_load_lds_dwordx4 v[152:153], off
	s_nop 0
	s_waitcnt vmcnt(8)
	s_waitcnt lgkmcnt(0)
	s_barrier
	s_setprio 1
	s_waitcnt lgkmcnt(0)
	v_mfma_f32_16x16x32_bf16 v[126:129], v[148:151], v[194:197], v[126:129]
	v_mfma_f32_16x16x32_bf16 v[126:129], v[166:169], v[202:205], v[126:129]
	v_mfma_f32_16x16x32_bf16 v[122:125], v[174:177], v[202:205], v[122:125]
	v_mfma_f32_16x16x32_bf16 v[122:125], v[170:173], v[194:197], v[122:125]
	v_mfma_f32_16x16x32_bf16 v[106:109], v[170:173], v[206:209], v[106:109]
	v_mfma_f32_16x16x32_bf16 v[106:109], v[174:177], v[210:213], v[106:109]
	v_mfma_f32_16x16x32_bf16 v[110:113], v[166:169], v[210:213], v[110:113]
	v_mfma_f32_16x16x32_bf16 v[110:113], v[148:151], v[206:209], v[110:113]
	v_mfma_f32_16x16x32_bf16 v[94:97], v[148:151], v[214:217], v[94:97]
	v_mfma_f32_16x16x32_bf16 v[94:97], v[166:169], v[218:221], v[94:97]
	v_mfma_f32_16x16x32_bf16 v[90:93], v[174:177], v[218:221], v[90:93]
	v_mfma_f32_16x16x32_bf16 v[90:93], v[170:173], v[214:217], v[90:93]
	v_mfma_f32_16x16x32_bf16 v[74:77], v[170:173], v[222:225], v[74:77]
	v_mfma_f32_16x16x32_bf16 v[74:77], v[174:177], v[226:229], v[74:77]
	v_mfma_f32_16x16x32_bf16 v[78:81], v[166:169], v[226:229], v[78:81]
	v_mfma_f32_16x16x32_bf16 v[78:81], v[148:151], v[222:225], v[78:81]
	s_setprio 0
	s_setprio 1
	v_mfma_f32_16x16x32_bf16 v[118:121], v[178:181], v[194:197], v[118:121]
	v_mfma_f32_16x16x32_bf16 v[118:121], v[182:185], v[202:205], v[118:121]
	v_mfma_f32_16x16x32_bf16 v[114:117], v[190:193], v[202:205], v[114:117]
	v_mfma_f32_16x16x32_bf16 v[114:117], v[186:189], v[194:197], v[114:117]
	v_mfma_f32_16x16x32_bf16 v[98:101], v[186:189], v[206:209], v[98:101]
	v_mfma_f32_16x16x32_bf16 v[98:101], v[190:193], v[210:213], v[98:101]
	v_mfma_f32_16x16x32_bf16 v[102:105], v[182:185], v[210:213], v[102:105]
	v_mfma_f32_16x16x32_bf16 v[102:105], v[178:181], v[206:209], v[102:105]
	v_mfma_f32_16x16x32_bf16 v[86:89], v[178:181], v[214:217], v[86:89]
	v_mfma_f32_16x16x32_bf16 v[86:89], v[182:185], v[218:221], v[86:89]
	v_mfma_f32_16x16x32_bf16 v[82:85], v[190:193], v[218:221], v[82:85]
	v_mfma_f32_16x16x32_bf16 v[82:85], v[186:189], v[214:217], v[82:85]
	v_mfma_f32_16x16x32_bf16 v[66:69], v[186:189], v[222:225], v[66:69]
	v_mfma_f32_16x16x32_bf16 v[66:69], v[190:193], v[226:229], v[66:69]
	v_mfma_f32_16x16x32_bf16 v[70:73], v[182:185], v[226:229], v[70:73]
	v_mfma_f32_16x16x32_bf16 v[70:73], v[178:181], v[222:225], v[70:73]
	s_setprio 0
	s_barrier
	s_add_i32 s36, s77, s64
	v_lshl_add_u64 v[152:153], s[58:59], 0, v[134:135]
	s_mov_b32 m0, s36
	ds_read_b128 v[194:197], v158 offset:16384
	ds_read_b128 v[202:205], v158 offset:17408
	ds_read_b128 v[206:209], v158 offset:18432
	ds_read_b128 v[210:213], v158 offset:19456
	ds_read_b128 v[214:217], v158 offset:20480
	ds_read_b128 v[218:221], v158 offset:21504
	ds_read_b128 v[222:225], v158 offset:22528
	ds_read_b128 v[226:229], v158 offset:23552
	global_load_lds_dwordx4 v[152:153], off
	s_add_i32 m0, s36, 0x2000
	s_add_u32 s94, s58, 0x2b0000
	v_lshl_add_u64 v[160:161], s[58:59], 0, v[138:139]
	s_addc_u32 s95, s59, 0
	s_add_i32 s36, s78, s64
	global_load_lds_dwordx4 v[160:161], off
	v_lshl_add_u64 v[198:199], s[94:95], 0, v[134:135]
	s_mov_b32 m0, s36
	v_lshl_add_u64 v[230:231], s[60:61], 0, v[136:137]
	global_load_lds_dwordx4 v[198:199], off
	v_lshl_add_u64 v[198:199], s[94:95], 0, v[138:139]
	s_add_i32 m0, s36, 0x2000
	s_nop 0
	global_load_lds_dwordx4 v[198:199], off
	v_lshl_add_u64 v[198:199], s[60:61], 0, v[132:133]
	s_mov_b32 m0, s67
	s_nop 0
	global_load_lds_dwordx4 v[198:199], off
	s_mov_b32 m0, s68
	s_nop 0
	global_load_lds_dwordx4 v[230:231], off
	s_nop 0
	s_waitcnt vmcnt(8)
	s_waitcnt lgkmcnt(0)
	s_barrier
	s_setprio 1
	s_waitcnt lgkmcnt(0)
	v_mfma_f32_16x16x32_bf16 v[62:65], v[148:151], v[194:197], v[62:65]
	v_mfma_f32_16x16x32_bf16 v[62:65], v[166:169], v[202:205], v[62:65]
	v_mfma_f32_16x16x32_bf16 v[58:61], v[174:177], v[202:205], v[58:61]
	v_mfma_f32_16x16x32_bf16 v[58:61], v[170:173], v[194:197], v[58:61]
	v_mfma_f32_16x16x32_bf16 v[42:45], v[170:173], v[206:209], v[42:45]
	v_mfma_f32_16x16x32_bf16 v[42:45], v[174:177], v[210:213], v[42:45]
	v_mfma_f32_16x16x32_bf16 v[46:49], v[166:169], v[210:213], v[46:49]
	v_mfma_f32_16x16x32_bf16 v[46:49], v[148:151], v[206:209], v[46:49]
	v_mfma_f32_16x16x32_bf16 v[30:33], v[148:151], v[214:217], v[30:33]
	v_mfma_f32_16x16x32_bf16 v[30:33], v[166:169], v[218:221], v[30:33]
	v_mfma_f32_16x16x32_bf16 v[26:29], v[174:177], v[218:221], v[26:29]
	v_mfma_f32_16x16x32_bf16 v[26:29], v[170:173], v[214:217], v[26:29]
	v_mfma_f32_16x16x32_bf16 v[10:13], v[170:173], v[222:225], v[10:13]
	v_mfma_f32_16x16x32_bf16 v[10:13], v[174:177], v[226:229], v[10:13]
	v_mfma_f32_16x16x32_bf16 v[14:17], v[166:169], v[226:229], v[14:17]
	v_mfma_f32_16x16x32_bf16 v[14:17], v[148:151], v[222:225], v[14:17]
	s_setprio 0
	s_setprio 1
	v_mfma_f32_16x16x32_bf16 v[54:57], v[178:181], v[194:197], v[54:57]
	v_mfma_f32_16x16x32_bf16 v[54:57], v[182:185], v[202:205], v[54:57]
	v_mfma_f32_16x16x32_bf16 v[50:53], v[190:193], v[202:205], v[50:53]
	v_mfma_f32_16x16x32_bf16 v[50:53], v[186:189], v[194:197], v[50:53]
	v_mfma_f32_16x16x32_bf16 v[34:37], v[186:189], v[206:209], v[34:37]
	v_mfma_f32_16x16x32_bf16 v[34:37], v[190:193], v[210:213], v[34:37]
	v_mfma_f32_16x16x32_bf16 v[38:41], v[182:185], v[210:213], v[38:41]
	v_mfma_f32_16x16x32_bf16 v[38:41], v[178:181], v[206:209], v[38:41]
	v_mfma_f32_16x16x32_bf16 v[22:25], v[178:181], v[214:217], v[22:25]
	v_mfma_f32_16x16x32_bf16 v[22:25], v[182:185], v[218:221], v[22:25]
	v_mfma_f32_16x16x32_bf16 v[18:21], v[190:193], v[218:221], v[18:21]
	v_mfma_f32_16x16x32_bf16 v[18:21], v[186:189], v[214:217], v[18:21]
	v_mfma_f32_16x16x32_bf16 v[2:5], v[186:189], v[222:225], v[2:5]
	v_mfma_f32_16x16x32_bf16 v[2:5], v[190:193], v[226:229], v[2:5]
	v_mfma_f32_16x16x32_bf16 v[6:9], v[182:185], v[226:229], v[6:9]
	v_mfma_f32_16x16x32_bf16 v[6:9], v[178:181], v[222:225], v[6:9]
	s_setprio 0
	s_barrier
	s_add_i32 s36, 0, 0x18000
	v_add_u32_e32 v140, s36, v154
	s_add_i32 s37, 0, 0x1c000
	ds_read_b128 v[148:151], v140
	ds_read_b128 v[166:169], v140 offset:1024
	ds_read_b128 v[170:173], v140 offset:2048
	ds_read_b128 v[174:177], v140 offset:3072
	v_add_u32_e32 v140, s37, v154
	ds_read_b128 v[178:181], v140
	ds_read_b128 v[182:185], v140 offset:1024
	ds_read_b128 v[186:189], v140 offset:2048
	ds_read_b128 v[190:193], v140 offset:3072
	s_add_u32 s60, s60, 0x2b0000
	s_addc_u32 s61, s61, 0
	s_mov_b32 m0, s69
	v_lshl_add_u64 v[232:233], s[60:61], 0, v[132:133]
	ds_read_b128 v[194:197], v158 offset:32768
	ds_read_b128 v[202:205], v158 offset:33792
	ds_read_b128 v[206:209], v158 offset:34816
	ds_read_b128 v[210:213], v158 offset:35840
	ds_read_b128 v[214:217], v158 offset:36864
	ds_read_b128 v[218:221], v158 offset:37888
	ds_read_b128 v[222:225], v158 offset:38912
	ds_read_b128 v[226:229], v158 offset:39936
	global_load_lds_dwordx4 v[232:233], off
	v_lshl_add_u64 v[232:233], s[60:61], 0, v[136:137]
	s_mov_b32 m0, s70
	s_nop 0
	global_load_lds_dwordx4 v[232:233], off
	s_nop 0
	s_waitcnt vmcnt(8)
	s_waitcnt lgkmcnt(0)
	s_barrier
	s_setprio 1
	s_waitcnt lgkmcnt(0)
	v_mfma_f32_16x16x32_bf16 v[126:129], v[148:151], v[194:197], v[126:129]
	v_mfma_f32_16x16x32_bf16 v[126:129], v[166:169], v[202:205], v[126:129]
	v_mfma_f32_16x16x32_bf16 v[122:125], v[174:177], v[202:205], v[122:125]
	v_mfma_f32_16x16x32_bf16 v[122:125], v[170:173], v[194:197], v[122:125]
	v_mfma_f32_16x16x32_bf16 v[106:109], v[170:173], v[206:209], v[106:109]
	v_mfma_f32_16x16x32_bf16 v[106:109], v[174:177], v[210:213], v[106:109]
	v_mfma_f32_16x16x32_bf16 v[110:113], v[166:169], v[210:213], v[110:113]
	v_mfma_f32_16x16x32_bf16 v[110:113], v[148:151], v[206:209], v[110:113]
	v_mfma_f32_16x16x32_bf16 v[94:97], v[148:151], v[214:217], v[94:97]
	v_mfma_f32_16x16x32_bf16 v[94:97], v[166:169], v[218:221], v[94:97]
	v_mfma_f32_16x16x32_bf16 v[90:93], v[174:177], v[218:221], v[90:93]
	v_mfma_f32_16x16x32_bf16 v[90:93], v[170:173], v[214:217], v[90:93]
	v_mfma_f32_16x16x32_bf16 v[74:77], v[170:173], v[222:225], v[74:77]
	v_mfma_f32_16x16x32_bf16 v[74:77], v[174:177], v[226:229], v[74:77]
	v_mfma_f32_16x16x32_bf16 v[78:81], v[166:169], v[226:229], v[78:81]
	v_mfma_f32_16x16x32_bf16 v[78:81], v[148:151], v[222:225], v[78:81]
	s_setprio 0
	s_setprio 1
	v_mfma_f32_16x16x32_bf16 v[118:121], v[178:181], v[194:197], v[118:121]
	v_mfma_f32_16x16x32_bf16 v[118:121], v[182:185], v[202:205], v[118:121]
	v_mfma_f32_16x16x32_bf16 v[114:117], v[190:193], v[202:205], v[114:117]
	v_mfma_f32_16x16x32_bf16 v[114:117], v[186:189], v[194:197], v[114:117]
	v_mfma_f32_16x16x32_bf16 v[98:101], v[186:189], v[206:209], v[98:101]
	v_mfma_f32_16x16x32_bf16 v[98:101], v[190:193], v[210:213], v[98:101]
	v_mfma_f32_16x16x32_bf16 v[102:105], v[182:185], v[210:213], v[102:105]
	v_mfma_f32_16x16x32_bf16 v[102:105], v[178:181], v[206:209], v[102:105]
	v_mfma_f32_16x16x32_bf16 v[86:89], v[178:181], v[214:217], v[86:89]
	v_mfma_f32_16x16x32_bf16 v[86:89], v[182:185], v[218:221], v[86:89]
	v_mfma_f32_16x16x32_bf16 v[82:85], v[190:193], v[218:221], v[82:85]
	v_mfma_f32_16x16x32_bf16 v[82:85], v[186:189], v[214:217], v[82:85]
	v_mfma_f32_16x16x32_bf16 v[66:69], v[186:189], v[222:225], v[66:69]
	v_mfma_f32_16x16x32_bf16 v[66:69], v[190:193], v[226:229], v[66:69]
	v_mfma_f32_16x16x32_bf16 v[70:73], v[182:185], v[226:229], v[70:73]
	v_mfma_f32_16x16x32_bf16 v[70:73], v[178:181], v[222:225], v[70:73]
	s_setprio 0
	s_barrier
	s_add_i32 s36, s36, s64
	v_lshl_add_u64 v[152:153], v[152:153], 0, s[20:21]
	s_mov_b32 m0, s36
	ds_read_b128 v[194:197], v158 offset:49152
	ds_read_b128 v[202:205], v158 offset:50176
	ds_read_b128 v[206:209], v158 offset:51200
	ds_read_b128 v[210:213], v158 offset:52224
	ds_read_b128 v[214:217], v158 offset:53248
	ds_read_b128 v[218:221], v158 offset:54272
	ds_read_b128 v[222:225], v158 offset:55296
	ds_read_b128 v[226:229], v158 offset:56320
	global_load_lds_dwordx4 v[152:153], off
	s_add_i32 m0, s36, 0x2000
	s_add_u32 s58, s58, 0x2b0080
	v_lshl_add_u64 v[152:153], v[160:161], 0, s[20:21]
	s_addc_u32 s59, s59, 0
	s_add_i32 s36, s37, s64
	global_load_lds_dwordx4 v[152:153], off
	v_lshl_add_u64 v[152:153], s[58:59], 0, v[134:135]
	s_mov_b32 m0, s36
	s_nop 0
	global_load_lds_dwordx4 v[152:153], off
	v_lshl_add_u64 v[152:153], s[58:59], 0, v[138:139]
	s_add_i32 m0, s36, 0x2000
	s_nop 0
	global_load_lds_dwordx4 v[152:153], off
	v_lshl_add_u64 v[152:153], v[198:199], 0, s[20:21]
	s_mov_b32 m0, s73
	s_nop 0
	global_load_lds_dwordx4 v[152:153], off
	v_lshl_add_u64 v[152:153], v[230:231], 0, s[20:21]
	s_mov_b32 m0, s74
	s_nop 0
	global_load_lds_dwordx4 v[152:153], off
	s_waitcnt vmcnt(8)
	s_waitcnt lgkmcnt(0)
	s_barrier
	s_setprio 1
	s_waitcnt lgkmcnt(0)
	v_mfma_f32_16x16x32_bf16 v[62:65], v[148:151], v[194:197], v[62:65]
	v_mfma_f32_16x16x32_bf16 v[62:65], v[166:169], v[202:205], v[62:65]
	v_mfma_f32_16x16x32_bf16 v[58:61], v[174:177], v[202:205], v[58:61]
	v_mfma_f32_16x16x32_bf16 v[58:61], v[170:173], v[194:197], v[58:61]
	v_mfma_f32_16x16x32_bf16 v[42:45], v[170:173], v[206:209], v[42:45]
	v_mfma_f32_16x16x32_bf16 v[42:45], v[174:177], v[210:213], v[42:45]
	v_mfma_f32_16x16x32_bf16 v[46:49], v[166:169], v[210:213], v[46:49]
	v_mfma_f32_16x16x32_bf16 v[46:49], v[148:151], v[206:209], v[46:49]
	v_mfma_f32_16x16x32_bf16 v[30:33], v[148:151], v[214:217], v[30:33]
	v_mfma_f32_16x16x32_bf16 v[30:33], v[166:169], v[218:221], v[30:33]
	v_mfma_f32_16x16x32_bf16 v[26:29], v[174:177], v[218:221], v[26:29]
	v_mfma_f32_16x16x32_bf16 v[26:29], v[170:173], v[214:217], v[26:29]
	v_mfma_f32_16x16x32_bf16 v[10:13], v[170:173], v[222:225], v[10:13]
	v_mfma_f32_16x16x32_bf16 v[10:13], v[174:177], v[226:229], v[10:13]
	v_mfma_f32_16x16x32_bf16 v[14:17], v[166:169], v[226:229], v[14:17]
	v_mfma_f32_16x16x32_bf16 v[14:17], v[148:151], v[222:225], v[14:17]
	s_setprio 0
	s_setprio 1
	v_mfma_f32_16x16x32_bf16 v[54:57], v[178:181], v[194:197], v[54:57]
	v_mfma_f32_16x16x32_bf16 v[54:57], v[182:185], v[202:205], v[54:57]
	v_mfma_f32_16x16x32_bf16 v[50:53], v[190:193], v[202:205], v[50:53]
	v_mfma_f32_16x16x32_bf16 v[50:53], v[186:189], v[194:197], v[50:53]
	v_mfma_f32_16x16x32_bf16 v[34:37], v[186:189], v[206:209], v[34:37]
	v_mfma_f32_16x16x32_bf16 v[34:37], v[190:193], v[210:213], v[34:37]
	v_mfma_f32_16x16x32_bf16 v[38:41], v[182:185], v[210:213], v[38:41]
	v_mfma_f32_16x16x32_bf16 v[38:41], v[178:181], v[206:209], v[38:41]
	v_mfma_f32_16x16x32_bf16 v[22:25], v[178:181], v[214:217], v[22:25]
	v_mfma_f32_16x16x32_bf16 v[22:25], v[182:185], v[218:221], v[22:25]
	v_mfma_f32_16x16x32_bf16 v[18:21], v[190:193], v[218:221], v[18:21]
	v_mfma_f32_16x16x32_bf16 v[18:21], v[186:189], v[214:217], v[18:21]
	v_mfma_f32_16x16x32_bf16 v[2:5], v[186:189], v[222:225], v[2:5]
	v_mfma_f32_16x16x32_bf16 v[2:5], v[190:193], v[226:229], v[2:5]
	v_mfma_f32_16x16x32_bf16 v[6:9], v[182:185], v[226:229], v[6:9]
	v_mfma_f32_16x16x32_bf16 v[6:9], v[178:181], v[222:225], v[6:9]
	s_setprio 0
	s_barrier
	s_add_u32 s56, s56, 0x100
	s_addc_u32 s57, s57, 0
	s_add_u32 s90, s90, 0x100
	s_addc_u32 s91, s91, 0
	s_cmp_ge_i32 s92, s39
	s_mov_b32 s58, s92
	s_cbranch_scc0 .LBB0_1902
	s_and_b64 vcc, exec, s[24:25]
	s_cbranch_vccz .LBB0_1905

.LBB0_2138:
	ds_read_b128 v[146:149], v157
	ds_read_b128 v[164:167], v157 offset:1024
	ds_read_b128 v[168:171], v157 offset:2048
	ds_read_b128 v[172:175], v157 offset:3072
	ds_read_b128 v[176:179], v158
	ds_read_b128 v[180:183], v158 offset:1024
	ds_read_b128 v[184:187], v158 offset:2048
	ds_read_b128 v[188:191], v158 offset:3072
	s_add_u32 s24, s22, 0xfff00080
	s_addc_u32 s25, s23, -1
	s_cmp_eq_u32 s54, 60
	s_cselect_b32 s35, s15, s25
	s_cselect_b32 s34, s50, s24
	s_cselect_b32 s25, s13, s53
	s_cselect_b32 s24, s51, s52
	v_lshl_add_u64 v[150:151], s[22:23], 0, v[138:139]
	s_add_i32 m0, s21, 0xc000
	ds_read_b128 v[192:195], v159
	ds_read_b128 v[196:199], v159 offset:1024
	ds_read_b128 v[200:203], v159 offset:2048
	ds_read_b128 v[204:207], v159 offset:3072
	ds_read_b128 v[208:211], v159 offset:4096
	ds_read_b128 v[212:215], v159 offset:5120
	ds_read_b128 v[216:219], v159 offset:6144
	ds_read_b128 v[220:223], v159 offset:7168
	global_load_lds_dwordx4 v[150:151], off
	v_lshl_add_u64 v[150:151], s[22:23], 0, v[140:141]
	s_add_i32 m0, s21, 0xe000
	s_nop 0
	global_load_lds_dwordx4 v[150:151], off
	s_waitcnt vmcnt(8)
	s_waitcnt lgkmcnt(0)
	s_barrier
	s_setprio 1
	s_waitcnt lgkmcnt(0)
	v_mfma_f32_16x16x32_bf16 v[126:129], v[146:149], v[192:195], v[126:129]
	v_mfma_f32_16x16x32_bf16 v[126:129], v[164:167], v[196:199], v[126:129]
	v_mfma_f32_16x16x32_bf16 v[122:125], v[172:175], v[196:199], v[122:125]
	v_mfma_f32_16x16x32_bf16 v[122:125], v[168:171], v[192:195], v[122:125]
	v_mfma_f32_16x16x32_bf16 v[106:109], v[168:171], v[200:203], v[106:109]
	v_mfma_f32_16x16x32_bf16 v[106:109], v[172:175], v[204:207], v[106:109]
	v_mfma_f32_16x16x32_bf16 v[110:113], v[164:167], v[204:207], v[110:113]
	v_mfma_f32_16x16x32_bf16 v[110:113], v[146:149], v[200:203], v[110:113]
	v_mfma_f32_16x16x32_bf16 v[94:97], v[146:149], v[208:211], v[94:97]
	v_mfma_f32_16x16x32_bf16 v[94:97], v[164:167], v[212:215], v[94:97]
	v_mfma_f32_16x16x32_bf16 v[90:93], v[172:175], v[212:215], v[90:93]
	v_mfma_f32_16x16x32_bf16 v[90:93], v[168:171], v[208:211], v[90:93]
	v_mfma_f32_16x16x32_bf16 v[74:77], v[168:171], v[216:219], v[74:77]
	v_mfma_f32_16x16x32_bf16 v[74:77], v[172:175], v[220:223], v[74:77]
	v_mfma_f32_16x16x32_bf16 v[78:81], v[164:167], v[220:223], v[78:81]
	v_mfma_f32_16x16x32_bf16 v[78:81], v[146:149], v[216:219], v[78:81]
	s_setprio 0
	s_setprio 1
	v_mfma_f32_16x16x32_bf16 v[118:121], v[176:179], v[192:195], v[118:121]
	v_mfma_f32_16x16x32_bf16 v[118:121], v[180:183], v[196:199], v[118:121]
	v_mfma_f32_16x16x32_bf16 v[114:117], v[188:191], v[196:199], v[114:117]
	v_mfma_f32_16x16x32_bf16 v[114:117], v[184:187], v[192:195], v[114:117]
	v_mfma_f32_16x16x32_bf16 v[98:101], v[184:187], v[200:203], v[98:101]
	v_mfma_f32_16x16x32_bf16 v[98:101], v[188:191], v[204:207], v[98:101]
	v_mfma_f32_16x16x32_bf16 v[102:105], v[180:183], v[204:207], v[102:105]
	v_mfma_f32_16x16x32_bf16 v[102:105], v[176:179], v[200:203], v[102:105]
	v_mfma_f32_16x16x32_bf16 v[86:89], v[176:179], v[208:211], v[86:89]
	v_mfma_f32_16x16x32_bf16 v[86:89], v[180:183], v[212:215], v[86:89]
	v_mfma_f32_16x16x32_bf16 v[82:85], v[188:191], v[212:215], v[82:85]
	v_mfma_f32_16x16x32_bf16 v[82:85], v[184:187], v[208:211], v[82:85]
	v_mfma_f32_16x16x32_bf16 v[66:69], v[184:187], v[216:219], v[66:69]
	v_mfma_f32_16x16x32_bf16 v[66:69], v[188:191], v[220:223], v[66:69]
	v_mfma_f32_16x16x32_bf16 v[70:73], v[180:183], v[220:223], v[70:73]
	v_mfma_f32_16x16x32_bf16 v[70:73], v[176:179], v[216:219], v[70:73]
	s_setprio 0
	s_barrier
	s_add_i32 s55, s47, s27
	v_lshl_add_u64 v[150:151], s[24:25], 0, v[134:135]
	s_mov_b32 m0, s55
	ds_read_b128 v[192:195], v159 offset:16384
	ds_read_b128 v[196:199], v159 offset:17408
	ds_read_b128 v[200:203], v159 offset:18432
	ds_read_b128 v[204:207], v159 offset:19456
	ds_read_b128 v[208:211], v159 offset:20480
	ds_read_b128 v[212:215], v159 offset:21504
	ds_read_b128 v[216:219], v159 offset:22528
	ds_read_b128 v[220:223], v159 offset:23552
	global_load_lds_dwordx4 v[150:151], off
	s_add_i32 m0, s55, 0x2000
	s_add_u32 s56, s24, 0x100000
	v_lshl_add_u64 v[160:161], s[24:25], 0, v[130:131]
	s_addc_u32 s57, s25, 0
	s_add_i32 s55, s48, s27
	global_load_lds_dwordx4 v[160:161], off
	v_lshl_add_u64 v[224:225], s[56:57], 0, v[134:135]
	s_mov_b32 m0, s55
	v_lshl_add_u64 v[226:227], s[34:35], 0, v[132:133]
	global_load_lds_dwordx4 v[224:225], off
	v_lshl_add_u64 v[224:225], s[56:57], 0, v[130:131]
	s_add_i32 m0, s55, 0x2000
	s_nop 0
	global_load_lds_dwordx4 v[224:225], off
	v_lshl_add_u64 v[224:225], s[34:35], 0, v[136:137]
	s_mov_b32 m0, s21
	s_nop 0
	global_load_lds_dwordx4 v[224:225], off
	s_mov_b32 m0, s40
	s_nop 0
	global_load_lds_dwordx4 v[226:227], off
	s_nop 0
	s_waitcnt vmcnt(8)
	s_waitcnt lgkmcnt(0)
	s_barrier
	s_setprio 1
	s_waitcnt lgkmcnt(0)
	v_mfma_f32_16x16x32_bf16 v[62:65], v[146:149], v[192:195], v[62:65]
	v_mfma_f32_16x16x32_bf16 v[62:65], v[164:167], v[196:199], v[62:65]
	v_mfma_f32_16x16x32_bf16 v[58:61], v[172:175], v[196:199], v[58:61]
	v_mfma_f32_16x16x32_bf16 v[58:61], v[168:171], v[192:195], v[58:61]
	v_mfma_f32_16x16x32_bf16 v[42:45], v[168:171], v[200:203], v[42:45]
	v_mfma_f32_16x16x32_bf16 v[42:45], v[172:175], v[204:207], v[42:45]
	v_mfma_f32_16x16x32_bf16 v[46:49], v[164:167], v[204:207], v[46:49]
	v_mfma_f32_16x16x32_bf16 v[46:49], v[146:149], v[200:203], v[46:49]
	v_mfma_f32_16x16x32_bf16 v[30:33], v[146:149], v[208:211], v[30:33]
	v_mfma_f32_16x16x32_bf16 v[30:33], v[164:167], v[212:215], v[30:33]
	v_mfma_f32_16x16x32_bf16 v[26:29], v[172:175], v[212:215], v[26:29]
	v_mfma_f32_16x16x32_bf16 v[26:29], v[168:171], v[208:211], v[26:29]
	v_mfma_f32_16x16x32_bf16 v[10:13], v[168:171], v[216:219], v[10:13]
	v_mfma_f32_16x16x32_bf16 v[10:13], v[172:175], v[220:223], v[10:13]
	v_mfma_f32_16x16x32_bf16 v[14:17], v[164:167], v[220:223], v[14:17]
	v_mfma_f32_16x16x32_bf16 v[14:17], v[146:149], v[216:219], v[14:17]
	s_setprio 0
	s_setprio 1
	v_mfma_f32_16x16x32_bf16 v[54:57], v[176:179], v[192:195], v[54:57]
	v_mfma_f32_16x16x32_bf16 v[54:57], v[180:183], v[196:199], v[54:57]
	v_mfma_f32_16x16x32_bf16 v[50:53], v[188:191], v[196:199], v[50:53]
	v_mfma_f32_16x16x32_bf16 v[50:53], v[184:187], v[192:195], v[50:53]
	v_mfma_f32_16x16x32_bf16 v[34:37], v[184:187], v[200:203], v[34:37]
	v_mfma_f32_16x16x32_bf16 v[34:37], v[188:191], v[204:207], v[34:37]
	v_mfma_f32_16x16x32_bf16 v[38:41], v[180:183], v[204:207], v[38:41]
	v_mfma_f32_16x16x32_bf16 v[38:41], v[176:179], v[200:203], v[38:41]
	v_mfma_f32_16x16x32_bf16 v[22:25], v[176:179], v[208:211], v[22:25]
	v_mfma_f32_16x16x32_bf16 v[22:25], v[180:183], v[212:215], v[22:25]
	v_mfma_f32_16x16x32_bf16 v[18:21], v[188:191], v[212:215], v[18:21]
	v_mfma_f32_16x16x32_bf16 v[18:21], v[184:187], v[208:211], v[18:21]
	v_mfma_f32_16x16x32_bf16 v[2:5], v[184:187], v[216:219], v[2:5]
	v_mfma_f32_16x16x32_bf16 v[2:5], v[188:191], v[220:223], v[2:5]
	v_mfma_f32_16x16x32_bf16 v[6:9], v[180:183], v[220:223], v[6:9]
	v_mfma_f32_16x16x32_bf16 v[6:9], v[176:179], v[216:219], v[6:9]
	s_setprio 0
	s_barrier
	s_add_i32 s55, 0, 0x18000
	v_add_u32_e32 v162, s55, v155
	s_add_i32 s56, 0, 0x1c000
	ds_read_b128 v[146:149], v162
	ds_read_b128 v[164:167], v162 offset:1024
	ds_read_b128 v[168:171], v162 offset:2048
	ds_read_b128 v[172:175], v162 offset:3072
	v_add_u32_e32 v162, s56, v155
	ds_read_b128 v[176:179], v162
	ds_read_b128 v[180:183], v162 offset:1024
	ds_read_b128 v[184:187], v162 offset:2048
	ds_read_b128 v[188:191], v162 offset:3072
	s_add_u32 s34, s34, 0x100000
	s_addc_u32 s35, s35, 0
	s_mov_b32 m0, s41
	v_lshl_add_u64 v[228:229], s[34:35], 0, v[136:137]
	ds_read_b128 v[192:195], v159 offset:32768
	ds_read_b128 v[196:199], v159 offset:33792
	ds_read_b128 v[200:203], v159 offset:34816
	ds_read_b128 v[204:207], v159 offset:35840
	ds_read_b128 v[208:211], v159 offset:36864
	ds_read_b128 v[212:215], v159 offset:37888
	ds_read_b128 v[216:219], v159 offset:38912
	ds_read_b128 v[220:223], v159 offset:39936
	global_load_lds_dwordx4 v[228:229], off
	v_lshl_add_u64 v[228:229], s[34:35], 0, v[132:133]
	s_mov_b32 m0, s42
	s_nop 0
	global_load_lds_dwordx4 v[228:229], off
	s_nop 0
	s_waitcnt vmcnt(8)
	s_waitcnt lgkmcnt(0)
	s_barrier
	s_setprio 1
	s_waitcnt lgkmcnt(0)
	v_mfma_f32_16x16x32_bf16 v[126:129], v[146:149], v[192:195], v[126:129]
	v_mfma_f32_16x16x32_bf16 v[126:129], v[164:167], v[196:199], v[126:129]
	v_mfma_f32_16x16x32_bf16 v[122:125], v[172:175], v[196:199], v[122:125]
	v_mfma_f32_16x16x32_bf16 v[122:125], v[168:171], v[192:195], v[122:125]
	v_mfma_f32_16x16x32_bf16 v[106:109], v[168:171], v[200:203], v[106:109]
	v_mfma_f32_16x16x32_bf16 v[106:109], v[172:175], v[204:207], v[106:109]
	v_mfma_f32_16x16x32_bf16 v[110:113], v[164:167], v[204:207], v[110:113]
	v_mfma_f32_16x16x32_bf16 v[110:113], v[146:149], v[200:203], v[110:113]
	v_mfma_f32_16x16x32_bf16 v[94:97], v[146:149], v[208:211], v[94:97]
	v_mfma_f32_16x16x32_bf16 v[94:97], v[164:167], v[212:215], v[94:97]
	v_mfma_f32_16x16x32_bf16 v[90:93], v[172:175], v[212:215], v[90:93]
	v_mfma_f32_16x16x32_bf16 v[90:93], v[168:171], v[208:211], v[90:93]
	v_mfma_f32_16x16x32_bf16 v[74:77], v[168:171], v[216:219], v[74:77]
	v_mfma_f32_16x16x32_bf16 v[74:77], v[172:175], v[220:223], v[74:77]
	v_mfma_f32_16x16x32_bf16 v[78:81], v[164:167], v[220:223], v[78:81]
	v_mfma_f32_16x16x32_bf16 v[78:81], v[146:149], v[216:219], v[78:81]
	s_setprio 0
	s_setprio 1
	v_mfma_f32_16x16x32_bf16 v[118:121], v[176:179], v[192:195], v[118:121]
	v_mfma_f32_16x16x32_bf16 v[118:121], v[180:183], v[196:199], v[118:121]
	v_mfma_f32_16x16x32_bf16 v[114:117], v[188:191], v[196:199], v[114:117]
	v_mfma_f32_16x16x32_bf16 v[114:117], v[184:187], v[192:195], v[114:117]
	v_mfma_f32_16x16x32_bf16 v[98:101], v[184:187], v[200:203], v[98:101]
	v_mfma_f32_16x16x32_bf16 v[98:101], v[188:191], v[204:207], v[98:101]
	v_mfma_f32_16x16x32_bf16 v[102:105], v[180:183], v[204:207], v[102:105]
	v_mfma_f32_16x16x32_bf16 v[102:105], v[176:179], v[200:203], v[102:105]
	v_mfma_f32_16x16x32_bf16 v[86:89], v[176:179], v[208:211], v[86:89]
	v_mfma_f32_16x16x32_bf16 v[86:89], v[180:183], v[212:215], v[86:89]
	v_mfma_f32_16x16x32_bf16 v[82:85], v[188:191], v[212:215], v[82:85]
	v_mfma_f32_16x16x32_bf16 v[82:85], v[184:187], v[208:211], v[82:85]
	v_mfma_f32_16x16x32_bf16 v[66:69], v[184:187], v[216:219], v[66:69]
	v_mfma_f32_16x16x32_bf16 v[66:69], v[188:191], v[220:223], v[66:69]
	v_mfma_f32_16x16x32_bf16 v[70:73], v[180:183], v[220:223], v[70:73]
	v_mfma_f32_16x16x32_bf16 v[70:73], v[176:179], v[216:219], v[70:73]
	s_setprio 0
	s_barrier
	s_add_i32 s34, s55, s27
	v_lshl_add_u64 v[150:151], v[150:151], 0, s[8:9]
	s_mov_b32 m0, s34
	ds_read_b128 v[192:195], v159 offset:49152
	ds_read_b128 v[196:199], v159 offset:50176
	ds_read_b128 v[200:203], v159 offset:51200
	ds_read_b128 v[204:207], v159 offset:52224
	ds_read_b128 v[208:211], v159 offset:53248
	ds_read_b128 v[212:215], v159 offset:54272
	ds_read_b128 v[216:219], v159 offset:55296
	ds_read_b128 v[220:223], v159 offset:56320
	global_load_lds_dwordx4 v[150:151], off
	s_add_i32 m0, s34, 0x2000
	s_add_u32 s24, s24, 0x100080
	v_lshl_add_u64 v[150:151], v[160:161], 0, s[8:9]
	s_addc_u32 s25, s25, 0
	s_add_i32 s34, s56, s27
	global_load_lds_dwordx4 v[150:151], off
	v_lshl_add_u64 v[150:151], s[24:25], 0, v[134:135]
	s_mov_b32 m0, s34
	s_nop 0
	global_load_lds_dwordx4 v[150:151], off
	v_lshl_add_u64 v[150:151], s[24:25], 0, v[130:131]
	s_add_i32 m0, s34, 0x2000
	s_nop 0
	global_load_lds_dwordx4 v[150:151], off
	v_lshl_add_u64 v[150:151], v[224:225], 0, s[8:9]
	s_mov_b32 m0, s44
	s_nop 0
	global_load_lds_dwordx4 v[150:151], off
	v_lshl_add_u64 v[150:151], v[226:227], 0, s[8:9]
	s_mov_b32 m0, s45
	s_nop 0
	global_load_lds_dwordx4 v[150:151], off
	s_waitcnt vmcnt(8)
	s_waitcnt lgkmcnt(0)
	s_barrier
	s_setprio 1
	s_waitcnt lgkmcnt(0)
	v_mfma_f32_16x16x32_bf16 v[62:65], v[146:149], v[192:195], v[62:65]
	v_mfma_f32_16x16x32_bf16 v[62:65], v[164:167], v[196:199], v[62:65]
	v_mfma_f32_16x16x32_bf16 v[58:61], v[172:175], v[196:199], v[58:61]
	v_mfma_f32_16x16x32_bf16 v[58:61], v[168:171], v[192:195], v[58:61]
	v_mfma_f32_16x16x32_bf16 v[42:45], v[168:171], v[200:203], v[42:45]
	v_mfma_f32_16x16x32_bf16 v[42:45], v[172:175], v[204:207], v[42:45]
	v_mfma_f32_16x16x32_bf16 v[46:49], v[164:167], v[204:207], v[46:49]
	v_mfma_f32_16x16x32_bf16 v[46:49], v[146:149], v[200:203], v[46:49]
	v_mfma_f32_16x16x32_bf16 v[30:33], v[146:149], v[208:211], v[30:33]
	v_mfma_f32_16x16x32_bf16 v[30:33], v[164:167], v[212:215], v[30:33]
	v_mfma_f32_16x16x32_bf16 v[26:29], v[172:175], v[212:215], v[26:29]
	v_mfma_f32_16x16x32_bf16 v[26:29], v[168:171], v[208:211], v[26:29]
	v_mfma_f32_16x16x32_bf16 v[10:13], v[168:171], v[216:219], v[10:13]
	v_mfma_f32_16x16x32_bf16 v[10:13], v[172:175], v[220:223], v[10:13]
	v_mfma_f32_16x16x32_bf16 v[14:17], v[164:167], v[220:223], v[14:17]
	v_mfma_f32_16x16x32_bf16 v[14:17], v[146:149], v[216:219], v[14:17]
	s_setprio 0
	s_setprio 1
	v_mfma_f32_16x16x32_bf16 v[54:57], v[176:179], v[192:195], v[54:57]
	v_mfma_f32_16x16x32_bf16 v[54:57], v[180:183], v[196:199], v[54:57]
	v_mfma_f32_16x16x32_bf16 v[50:53], v[188:191], v[196:199], v[50:53]
	v_mfma_f32_16x16x32_bf16 v[50:53], v[184:187], v[192:195], v[50:53]
	v_mfma_f32_16x16x32_bf16 v[34:37], v[184:187], v[200:203], v[34:37]
	v_mfma_f32_16x16x32_bf16 v[34:37], v[188:191], v[204:207], v[34:37]
	v_mfma_f32_16x16x32_bf16 v[38:41], v[180:183], v[204:207], v[38:41]
	v_mfma_f32_16x16x32_bf16 v[38:41], v[176:179], v[200:203], v[38:41]
	v_mfma_f32_16x16x32_bf16 v[22:25], v[176:179], v[208:211], v[22:25]
	v_mfma_f32_16x16x32_bf16 v[22:25], v[180:183], v[212:215], v[22:25]
	v_mfma_f32_16x16x32_bf16 v[18:21], v[188:191], v[212:215], v[18:21]
	v_mfma_f32_16x16x32_bf16 v[18:21], v[184:187], v[208:211], v[18:21]
	v_mfma_f32_16x16x32_bf16 v[2:5], v[184:187], v[216:219], v[2:5]
	v_mfma_f32_16x16x32_bf16 v[2:5], v[188:191], v[220:223], v[2:5]
	v_mfma_f32_16x16x32_bf16 v[6:9], v[180:183], v[220:223], v[6:9]
	v_mfma_f32_16x16x32_bf16 v[6:9], v[176:179], v[216:219], v[6:9]
	s_setprio 0
	s_barrier
	s_add_i32 s54, s54, 2
	s_add_u32 s22, s22, 0x100
	s_addc_u32 s23, s23, 0
	s_add_u32 s52, s52, 0x100
	s_addc_u32 s53, s53, 0
	s_cmp_gt_u32 s54, 61
	s_cbranch_scc0 .LBB0_2138
	s_and_b64 vcc, exec, s[10:11]
	s_cbranch_vccz .LBB0_2141
	s_barrier

.LBB0_2158:
	ds_read_b128 v[146:149], v157
	ds_read_b128 v[164:167], v157 offset:1024
	ds_read_b128 v[168:171], v157 offset:2048
	ds_read_b128 v[172:175], v157 offset:3072
	ds_read_b128 v[176:179], v158
	ds_read_b128 v[180:183], v158 offset:1024
	ds_read_b128 v[184:187], v158 offset:2048
	ds_read_b128 v[188:191], v158 offset:3072
	s_add_u32 s26, s24, 0xfff00080
	s_addc_u32 s27, s25, -1
	s_cmp_eq_u32 s52, 60
	s_cselect_b32 s35, s17, s27
	s_cselect_b32 s34, s48, s26
	s_cselect_b32 s27, s15, s51
	s_cselect_b32 s26, s49, s50
	v_lshl_add_u64 v[150:151], s[24:25], 0, v[138:139]
	s_add_i32 m0, s23, 0xc000
	ds_read_b128 v[192:195], v159
	ds_read_b128 v[196:199], v159 offset:1024
	ds_read_b128 v[200:203], v159 offset:2048
	ds_read_b128 v[204:207], v159 offset:3072
	ds_read_b128 v[208:211], v159 offset:4096
	ds_read_b128 v[212:215], v159 offset:5120
	ds_read_b128 v[216:219], v159 offset:6144
	ds_read_b128 v[220:223], v159 offset:7168
	global_load_lds_dwordx4 v[150:151], off
	v_lshl_add_u64 v[150:151], s[24:25], 0, v[140:141]
	s_add_i32 m0, s23, 0xe000
	s_nop 0
	global_load_lds_dwordx4 v[150:151], off
	s_nop 0
	s_waitcnt vmcnt(8)
	s_waitcnt lgkmcnt(0)
	s_barrier
	s_setprio 1
	s_waitcnt lgkmcnt(0)
	v_mfma_f32_16x16x32_bf16 v[126:129], v[146:149], v[192:195], v[126:129]
	v_mfma_f32_16x16x32_bf16 v[126:129], v[164:167], v[196:199], v[126:129]
	v_mfma_f32_16x16x32_bf16 v[122:125], v[172:175], v[196:199], v[122:125]
	v_mfma_f32_16x16x32_bf16 v[122:125], v[168:171], v[192:195], v[122:125]
	v_mfma_f32_16x16x32_bf16 v[106:109], v[168:171], v[200:203], v[106:109]
	v_mfma_f32_16x16x32_bf16 v[106:109], v[172:175], v[204:207], v[106:109]
	v_mfma_f32_16x16x32_bf16 v[110:113], v[164:167], v[204:207], v[110:113]
	v_mfma_f32_16x16x32_bf16 v[110:113], v[146:149], v[200:203], v[110:113]
	v_mfma_f32_16x16x32_bf16 v[94:97], v[146:149], v[208:211], v[94:97]
	v_mfma_f32_16x16x32_bf16 v[94:97], v[164:167], v[212:215], v[94:97]
	v_mfma_f32_16x16x32_bf16 v[90:93], v[172:175], v[212:215], v[90:93]
	v_mfma_f32_16x16x32_bf16 v[90:93], v[168:171], v[208:211], v[90:93]
	v_mfma_f32_16x16x32_bf16 v[74:77], v[168:171], v[216:219], v[74:77]
	v_mfma_f32_16x16x32_bf16 v[74:77], v[172:175], v[220:223], v[74:77]
	v_mfma_f32_16x16x32_bf16 v[78:81], v[164:167], v[220:223], v[78:81]
	v_mfma_f32_16x16x32_bf16 v[78:81], v[146:149], v[216:219], v[78:81]
	s_setprio 0
	s_setprio 1
	v_mfma_f32_16x16x32_bf16 v[118:121], v[176:179], v[192:195], v[118:121]
	v_mfma_f32_16x16x32_bf16 v[118:121], v[180:183], v[196:199], v[118:121]
	v_mfma_f32_16x16x32_bf16 v[114:117], v[188:191], v[196:199], v[114:117]
	v_mfma_f32_16x16x32_bf16 v[114:117], v[184:187], v[192:195], v[114:117]
	v_mfma_f32_16x16x32_bf16 v[98:101], v[184:187], v[200:203], v[98:101]
	v_mfma_f32_16x16x32_bf16 v[98:101], v[188:191], v[204:207], v[98:101]
	v_mfma_f32_16x16x32_bf16 v[102:105], v[180:183], v[204:207], v[102:105]
	v_mfma_f32_16x16x32_bf16 v[102:105], v[176:179], v[200:203], v[102:105]
	v_mfma_f32_16x16x32_bf16 v[86:89], v[176:179], v[208:211], v[86:89]
	v_mfma_f32_16x16x32_bf16 v[86:89], v[180:183], v[212:215], v[86:89]
	v_mfma_f32_16x16x32_bf16 v[82:85], v[188:191], v[212:215], v[82:85]
	v_mfma_f32_16x16x32_bf16 v[82:85], v[184:187], v[208:211], v[82:85]
	v_mfma_f32_16x16x32_bf16 v[66:69], v[184:187], v[216:219], v[66:69]
	v_mfma_f32_16x16x32_bf16 v[66:69], v[188:191], v[220:223], v[66:69]
	v_mfma_f32_16x16x32_bf16 v[70:73], v[180:183], v[220:223], v[70:73]
	v_mfma_f32_16x16x32_bf16 v[70:73], v[176:179], v[216:219], v[70:73]
	s_setprio 0
	s_barrier
	s_add_i32 s53, s45, s38
	v_lshl_add_u64 v[150:151], s[26:27], 0, v[132:133]
	s_mov_b32 m0, s53
	ds_read_b128 v[192:195], v159 offset:16384
	ds_read_b128 v[196:199], v159 offset:17408
	ds_read_b128 v[200:203], v159 offset:18432
	ds_read_b128 v[204:207], v159 offset:19456
	ds_read_b128 v[208:211], v159 offset:20480
	ds_read_b128 v[212:215], v159 offset:21504
	ds_read_b128 v[216:219], v159 offset:22528
	ds_read_b128 v[220:223], v159 offset:23552
	global_load_lds_dwordx4 v[150:151], off
	s_add_i32 m0, s53, 0x2000
	s_add_u32 s54, s26, 0x100000
	v_lshl_add_u64 v[160:161], s[26:27], 0, v[134:135]
	s_addc_u32 s55, s27, 0
	s_add_i32 s53, s46, s38
	global_load_lds_dwordx4 v[160:161], off
	v_lshl_add_u64 v[224:225], s[54:55], 0, v[132:133]
	s_mov_b32 m0, s53
	v_lshl_add_u64 v[226:227], s[34:35], 0, v[136:137]
	global_load_lds_dwordx4 v[224:225], off
	v_lshl_add_u64 v[224:225], s[54:55], 0, v[134:135]
	s_add_i32 m0, s53, 0x2000
	s_nop 0
	global_load_lds_dwordx4 v[224:225], off
	v_lshl_add_u64 v[224:225], s[34:35], 0, v[130:131]
	s_mov_b32 m0, s23
	s_nop 0
	global_load_lds_dwordx4 v[224:225], off
	s_mov_b32 m0, s40
	s_nop 0
	global_load_lds_dwordx4 v[226:227], off
	s_nop 0
	s_waitcnt vmcnt(8)
	s_waitcnt lgkmcnt(0)
	s_barrier
	s_setprio 1
	s_waitcnt lgkmcnt(0)
	v_mfma_f32_16x16x32_bf16 v[62:65], v[146:149], v[192:195], v[62:65]
	v_mfma_f32_16x16x32_bf16 v[62:65], v[164:167], v[196:199], v[62:65]
	v_mfma_f32_16x16x32_bf16 v[58:61], v[172:175], v[196:199], v[58:61]
	v_mfma_f32_16x16x32_bf16 v[58:61], v[168:171], v[192:195], v[58:61]
	v_mfma_f32_16x16x32_bf16 v[42:45], v[168:171], v[200:203], v[42:45]
	v_mfma_f32_16x16x32_bf16 v[42:45], v[172:175], v[204:207], v[42:45]
	v_mfma_f32_16x16x32_bf16 v[46:49], v[164:167], v[204:207], v[46:49]
	v_mfma_f32_16x16x32_bf16 v[46:49], v[146:149], v[200:203], v[46:49]
	v_mfma_f32_16x16x32_bf16 v[30:33], v[146:149], v[208:211], v[30:33]
	v_mfma_f32_16x16x32_bf16 v[30:33], v[164:167], v[212:215], v[30:33]
	v_mfma_f32_16x16x32_bf16 v[26:29], v[172:175], v[212:215], v[26:29]
	v_mfma_f32_16x16x32_bf16 v[26:29], v[168:171], v[208:211], v[26:29]
	v_mfma_f32_16x16x32_bf16 v[10:13], v[168:171], v[216:219], v[10:13]
	v_mfma_f32_16x16x32_bf16 v[10:13], v[172:175], v[220:223], v[10:13]
	v_mfma_f32_16x16x32_bf16 v[14:17], v[164:167], v[220:223], v[14:17]
	v_mfma_f32_16x16x32_bf16 v[14:17], v[146:149], v[216:219], v[14:17]
	s_setprio 0
	s_setprio 1
	v_mfma_f32_16x16x32_bf16 v[54:57], v[176:179], v[192:195], v[54:57]
	v_mfma_f32_16x16x32_bf16 v[54:57], v[180:183], v[196:199], v[54:57]
	v_mfma_f32_16x16x32_bf16 v[50:53], v[188:191], v[196:199], v[50:53]
	v_mfma_f32_16x16x32_bf16 v[50:53], v[184:187], v[192:195], v[50:53]
	v_mfma_f32_16x16x32_bf16 v[34:37], v[184:187], v[200:203], v[34:37]
	v_mfma_f32_16x16x32_bf16 v[34:37], v[188:191], v[204:207], v[34:37]
	v_mfma_f32_16x16x32_bf16 v[38:41], v[180:183], v[204:207], v[38:41]
	v_mfma_f32_16x16x32_bf16 v[38:41], v[176:179], v[200:203], v[38:41]
	v_mfma_f32_16x16x32_bf16 v[22:25], v[176:179], v[208:211], v[22:25]
	v_mfma_f32_16x16x32_bf16 v[22:25], v[180:183], v[212:215], v[22:25]
	v_mfma_f32_16x16x32_bf16 v[18:21], v[188:191], v[212:215], v[18:21]
	v_mfma_f32_16x16x32_bf16 v[18:21], v[184:187], v[208:211], v[18:21]
	v_mfma_f32_16x16x32_bf16 v[2:5], v[184:187], v[216:219], v[2:5]
	v_mfma_f32_16x16x32_bf16 v[2:5], v[188:191], v[220:223], v[2:5]
	v_mfma_f32_16x16x32_bf16 v[6:9], v[180:183], v[220:223], v[6:9]
	v_mfma_f32_16x16x32_bf16 v[6:9], v[176:179], v[216:219], v[6:9]
	s_setprio 0
	s_barrier
	s_add_i32 s53, 0, 0x18000
	v_add_u32_e32 v162, s53, v155
	s_add_i32 s54, 0, 0x1c000
	ds_read_b128 v[146:149], v162
	ds_read_b128 v[164:167], v162 offset:1024
	ds_read_b128 v[168:171], v162 offset:2048
	ds_read_b128 v[172:175], v162 offset:3072
	v_add_u32_e32 v162, s54, v155
	ds_read_b128 v[176:179], v162
	ds_read_b128 v[180:183], v162 offset:1024
	ds_read_b128 v[184:187], v162 offset:2048
	ds_read_b128 v[188:191], v162 offset:3072
	s_add_u32 s34, s34, 0x100000
	s_addc_u32 s35, s35, 0
	s_mov_b32 m0, s41
	v_lshl_add_u64 v[228:229], s[34:35], 0, v[130:131]
	ds_read_b128 v[192:195], v159 offset:32768
	ds_read_b128 v[196:199], v159 offset:33792
	ds_read_b128 v[200:203], v159 offset:34816
	ds_read_b128 v[204:207], v159 offset:35840
	ds_read_b128 v[208:211], v159 offset:36864
	ds_read_b128 v[212:215], v159 offset:37888
	ds_read_b128 v[216:219], v159 offset:38912
	ds_read_b128 v[220:223], v159 offset:39936
	global_load_lds_dwordx4 v[228:229], off
	v_lshl_add_u64 v[228:229], s[34:35], 0, v[136:137]
	s_mov_b32 m0, s42
	s_nop 0
	global_load_lds_dwordx4 v[228:229], off
	s_nop 0
	s_waitcnt vmcnt(8)
	s_waitcnt lgkmcnt(0)
	s_barrier
	s_setprio 1
	s_waitcnt lgkmcnt(0)
	v_mfma_f32_16x16x32_bf16 v[126:129], v[146:149], v[192:195], v[126:129]
	v_mfma_f32_16x16x32_bf16 v[126:129], v[164:167], v[196:199], v[126:129]
	v_mfma_f32_16x16x32_bf16 v[122:125], v[172:175], v[196:199], v[122:125]
	v_mfma_f32_16x16x32_bf16 v[122:125], v[168:171], v[192:195], v[122:125]
	v_mfma_f32_16x16x32_bf16 v[106:109], v[168:171], v[200:203], v[106:109]
	v_mfma_f32_16x16x32_bf16 v[106:109], v[172:175], v[204:207], v[106:109]
	v_mfma_f32_16x16x32_bf16 v[110:113], v[164:167], v[204:207], v[110:113]
	v_mfma_f32_16x16x32_bf16 v[110:113], v[146:149], v[200:203], v[110:113]
	v_mfma_f32_16x16x32_bf16 v[94:97], v[146:149], v[208:211], v[94:97]
	v_mfma_f32_16x16x32_bf16 v[94:97], v[164:167], v[212:215], v[94:97]
	v_mfma_f32_16x16x32_bf16 v[90:93], v[172:175], v[212:215], v[90:93]
	v_mfma_f32_16x16x32_bf16 v[90:93], v[168:171], v[208:211], v[90:93]
	v_mfma_f32_16x16x32_bf16 v[74:77], v[168:171], v[216:219], v[74:77]
	v_mfma_f32_16x16x32_bf16 v[74:77], v[172:175], v[220:223], v[74:77]
	v_mfma_f32_16x16x32_bf16 v[78:81], v[164:167], v[220:223], v[78:81]
	v_mfma_f32_16x16x32_bf16 v[78:81], v[146:149], v[216:219], v[78:81]
	s_setprio 0
	s_setprio 1
	v_mfma_f32_16x16x32_bf16 v[118:121], v[176:179], v[192:195], v[118:121]
	v_mfma_f32_16x16x32_bf16 v[118:121], v[180:183], v[196:199], v[118:121]
	v_mfma_f32_16x16x32_bf16 v[114:117], v[188:191], v[196:199], v[114:117]
	v_mfma_f32_16x16x32_bf16 v[114:117], v[184:187], v[192:195], v[114:117]
	v_mfma_f32_16x16x32_bf16 v[98:101], v[184:187], v[200:203], v[98:101]
	v_mfma_f32_16x16x32_bf16 v[98:101], v[188:191], v[204:207], v[98:101]
	v_mfma_f32_16x16x32_bf16 v[102:105], v[180:183], v[204:207], v[102:105]
	v_mfma_f32_16x16x32_bf16 v[102:105], v[176:179], v[200:203], v[102:105]
	v_mfma_f32_16x16x32_bf16 v[86:89], v[176:179], v[208:211], v[86:89]
	v_mfma_f32_16x16x32_bf16 v[86:89], v[180:183], v[212:215], v[86:89]
	v_mfma_f32_16x16x32_bf16 v[82:85], v[188:191], v[212:215], v[82:85]
	v_mfma_f32_16x16x32_bf16 v[82:85], v[184:187], v[208:211], v[82:85]
	v_mfma_f32_16x16x32_bf16 v[66:69], v[184:187], v[216:219], v[66:69]
	v_mfma_f32_16x16x32_bf16 v[66:69], v[188:191], v[220:223], v[66:69]
	v_mfma_f32_16x16x32_bf16 v[70:73], v[180:183], v[220:223], v[70:73]
	v_mfma_f32_16x16x32_bf16 v[70:73], v[176:179], v[216:219], v[70:73]
	s_setprio 0
	s_barrier
	s_add_i32 s34, s53, s38
	v_lshl_add_u64 v[150:151], v[150:151], 0, s[10:11]
	s_mov_b32 m0, s34
	ds_read_b128 v[192:195], v159 offset:49152
	ds_read_b128 v[196:199], v159 offset:50176
	ds_read_b128 v[200:203], v159 offset:51200
	ds_read_b128 v[204:207], v159 offset:52224
	ds_read_b128 v[208:211], v159 offset:53248
	ds_read_b128 v[212:215], v159 offset:54272
	ds_read_b128 v[216:219], v159 offset:55296
	ds_read_b128 v[220:223], v159 offset:56320
	global_load_lds_dwordx4 v[150:151], off
	s_add_i32 m0, s34, 0x2000
	s_add_u32 s26, s26, 0x100080
	v_lshl_add_u64 v[150:151], v[160:161], 0, s[10:11]
	s_addc_u32 s27, s27, 0
	s_add_i32 s34, s54, s38
	global_load_lds_dwordx4 v[150:151], off
	v_lshl_add_u64 v[150:151], s[26:27], 0, v[132:133]
	s_mov_b32 m0, s34
	s_nop 0
	global_load_lds_dwordx4 v[150:151], off
	v_lshl_add_u64 v[150:151], s[26:27], 0, v[134:135]
	s_add_i32 m0, s34, 0x2000
	s_nop 0
	global_load_lds_dwordx4 v[150:151], off
	v_lshl_add_u64 v[150:151], v[224:225], 0, s[10:11]
	s_mov_b32 m0, s43
	s_nop 0
	global_load_lds_dwordx4 v[150:151], off
	v_lshl_add_u64 v[150:151], v[226:227], 0, s[10:11]
	s_mov_b32 m0, s44
	s_nop 0
	global_load_lds_dwordx4 v[150:151], off
	s_waitcnt vmcnt(8)
	s_waitcnt lgkmcnt(0)
	s_barrier
	s_setprio 1
	s_waitcnt lgkmcnt(0)
	v_mfma_f32_16x16x32_bf16 v[62:65], v[146:149], v[192:195], v[62:65]
	v_mfma_f32_16x16x32_bf16 v[62:65], v[164:167], v[196:199], v[62:65]
	v_mfma_f32_16x16x32_bf16 v[58:61], v[172:175], v[196:199], v[58:61]
	v_mfma_f32_16x16x32_bf16 v[58:61], v[168:171], v[192:195], v[58:61]
	v_mfma_f32_16x16x32_bf16 v[42:45], v[168:171], v[200:203], v[42:45]
	v_mfma_f32_16x16x32_bf16 v[42:45], v[172:175], v[204:207], v[42:45]
	v_mfma_f32_16x16x32_bf16 v[46:49], v[164:167], v[204:207], v[46:49]
	v_mfma_f32_16x16x32_bf16 v[46:49], v[146:149], v[200:203], v[46:49]
	v_mfma_f32_16x16x32_bf16 v[30:33], v[146:149], v[208:211], v[30:33]
	v_mfma_f32_16x16x32_bf16 v[30:33], v[164:167], v[212:215], v[30:33]
	v_mfma_f32_16x16x32_bf16 v[26:29], v[172:175], v[212:215], v[26:29]
	v_mfma_f32_16x16x32_bf16 v[26:29], v[168:171], v[208:211], v[26:29]
	v_mfma_f32_16x16x32_bf16 v[10:13], v[168:171], v[216:219], v[10:13]
	v_mfma_f32_16x16x32_bf16 v[10:13], v[172:175], v[220:223], v[10:13]
	v_mfma_f32_16x16x32_bf16 v[14:17], v[164:167], v[220:223], v[14:17]
	v_mfma_f32_16x16x32_bf16 v[14:17], v[146:149], v[216:219], v[14:17]
	s_setprio 0
	s_setprio 1
	v_mfma_f32_16x16x32_bf16 v[54:57], v[176:179], v[192:195], v[54:57]
	v_mfma_f32_16x16x32_bf16 v[54:57], v[180:183], v[196:199], v[54:57]
	v_mfma_f32_16x16x32_bf16 v[50:53], v[188:191], v[196:199], v[50:53]
	v_mfma_f32_16x16x32_bf16 v[50:53], v[184:187], v[192:195], v[50:53]
	v_mfma_f32_16x16x32_bf16 v[34:37], v[184:187], v[200:203], v[34:37]
	v_mfma_f32_16x16x32_bf16 v[34:37], v[188:191], v[204:207], v[34:37]
	v_mfma_f32_16x16x32_bf16 v[38:41], v[180:183], v[204:207], v[38:41]
	v_mfma_f32_16x16x32_bf16 v[38:41], v[176:179], v[200:203], v[38:41]
	v_mfma_f32_16x16x32_bf16 v[22:25], v[176:179], v[208:211], v[22:25]
	v_mfma_f32_16x16x32_bf16 v[22:25], v[180:183], v[212:215], v[22:25]
	v_mfma_f32_16x16x32_bf16 v[18:21], v[188:191], v[212:215], v[18:21]
	v_mfma_f32_16x16x32_bf16 v[18:21], v[184:187], v[208:211], v[18:21]
	v_mfma_f32_16x16x32_bf16 v[2:5], v[184:187], v[216:219], v[2:5]
	v_mfma_f32_16x16x32_bf16 v[2:5], v[188:191], v[220:223], v[2:5]
	v_mfma_f32_16x16x32_bf16 v[6:9], v[180:183], v[220:223], v[6:9]
	v_mfma_f32_16x16x32_bf16 v[6:9], v[176:179], v[216:219], v[6:9]
	s_setprio 0
	s_barrier
	s_add_i32 s52, s52, 2
	s_add_u32 s24, s24, 0x100
	s_addc_u32 s25, s25, 0
	s_add_u32 s50, s50, 0x100
	s_addc_u32 s51, s51, 0
	s_cmp_gt_u32 s52, 61
	s_cbranch_scc0 .LBB0_2158
	s_and_b64 vcc, exec, s[12:13]
	s_cbranch_vccz .LBB0_2161
	s_barrier
